# v11 + hyena FFT radix-16 pair passes (12 loops) rewritten by hand: 112 packed f32 ops per 16-point group, no register shuffles
# speedup vs baseline: 1.0245x; 1.0089x over previous
; DI float2 twid(float r) { return float2{__builtin_amdgcn_cosf(r), -__builtin_amdgcn_sinf(r)}; }
; DI void bfly_fwd(float2 a0, float2 a1, float2 a2, float2 a3, float r, float2& o0, float2& o1, float2& o2, float2& o3) {
;   float2 t0 = {a0.x + a2.x, a0.y + a2.y}, t1 = {a0.x - a2.x, a0.y - a2.y}, t2 = {a1.x + a3.x, a1.y + a3.y}, t3 = {a1.x - a3.x, a1.y - a3.y};
;   float2 b0 = {t0.x + t2.x, t0.y + t2.y}, b2 = {t0.x - t2.x, t0.y - t2.y}, b1 = {t1.x + t3.y, t1.y - t3.x}, b3 = {t1.x - t3.y, t1.y + t3.x};
;   float2 w1 = twid(r), w2 = cmul(w1, w1), w3 = cmul(w2, w1);
;   o0 = b0; o1 = cmul(b1, w1); o2 = cmul(b2, w2); o3 = cmul(b3, w3);
;   const int lq2 = lq1 - 2, Q1 = 1 << lq1, Q2 = 1 << lq2; const float invM1 = 1.f / (float)(4 << lq1), invM2 = 1.f / (float)(4 << lq2);
;   for (int gg = tid; gg < NBT * (N / 16); gg += NTHR) { const int g = gg & (N / 16 - 1); float2* z = z0 + (gg / (N / 16)) * N; const int jp = g & (Q2 - 1), base = ((g >> lq2) << (lq2 + 4)) + jp; float2 x[4][4];
; #pragma unroll
;     for (int q1 = 0; q1 < 4; ++q1)
; #pragma unroll
;       for (int q2 = 0; q2 < 4; ++q2) x[q1][q2] = z[base + q1 * Q1 + q2 * Q2];
; #pragma unroll
;     for (int q2 = 0; q2 < 4; ++q2) bfly_fwd(x[0][q2], x[1][q2], x[2][q2], x[3][q2], (float)(jp + q2 * Q2) * invM1, x[0][q2], x[1][q2], x[2][q2], x[3][q2]);
; #pragma unroll
;     for (int q1 = 0; q1 < 4; ++q1) bfly_fwd(x[q1][0], x[q1][1], x[q1][2], x[q1][3], (float)jp * invM2, x[q1][0], x[q1][1], x[q1][2], x[q1][3]);
.LBB0_1488:
	s_or_b64 exec, exec, s[0:1]
	s_add_i32 s0, 16, 0x20000
	v_mov_b32_e32 v0, s0
	v_readlane_b32 s0, v240, 48
	s_or_b32 s96, s21, s75
	s_waitcnt lgkmcnt(0)
	s_barrier
	ds_read_b128 v[6:9], v0
	v_mov_b32_e32 v0, s0
	s_lshl_b64 s[0:1], s[96:97], 2
	s_add_u32 s0, s18, s0
	s_addc_u32 s1, s19, s1
	ds_read_b128 v[2:5], v0
	global_load_dword v0, v1, s[0:1]
	s_movk_i32 s0, 0x200
	v_cmp_gt_i32_e32 vcc, s0, v10
	v_lshlrev_b32_e32 v11, 7, v10
	s_and_saveexec_b64 s[0:1], vcc
	s_cbranch_execz .LBB0_1491
	v_cvt_f32_ubyte0_e32 v15, v10
	v_mul_f32_e32 v14, 0x39800000, v15
	v_sin_f32_e32 v12, v14
	s_movk_i32 s8, 0x100
	v_cos_f32_e32 v14, v14
	v_or_b32_sdwa v17, v10, s8 dst_sel:DWORD dst_unused:UNUSED_PAD src0_sel:BYTE_0 src1_sel:DWORD
	v_cvt_f32_u32_e32 v17, v17
	v_and_b32_e32 v13, 0x8000, v11
	v_lshlrev_b32_sdwa v16, v151, v10 dst_sel:DWORD dst_unused:UNUSED_PAD src0_sel:DWORD src1_sel:BYTE_0
	v_add3_u32 v72, 16, v13, v16
	v_mul_f32_e32 v13, v12, v12
	v_fma_f32 v16, v14, v14, -v13
	v_mul_f32_e64 v13, v14, -v12
	v_add_f32_e32 v18, v13, v13
	v_mul_f32_e32 v13, 0x39800000, v17
	v_sin_f32_e32 v22, v13
	s_movk_i32 s8, 0x200
	v_cos_f32_e32 v24, v13
	v_or_b32_sdwa v17, v10, s8 dst_sel:DWORD dst_unused:UNUSED_PAD src0_sel:BYTE_0 src1_sel:DWORD
	v_cvt_f32_u32_e32 v17, v17
	v_mul_f32_e32 v13, v12, v16
	v_fma_f32 v26, v14, v18, -v13
	v_mul_f32_e32 v13, v22, v22
	v_fma_f32 v28, v24, v24, -v13
	v_mul_f32_e64 v13, v24, -v22
	v_add_f32_e32 v30, v13, v13
	v_mul_f32_e32 v13, 0x39800000, v17
	v_sin_f32_e32 v34, v13
	s_movk_i32 s8, 0x300
	v_cos_f32_e32 v36, v13
	v_or_b32_sdwa v17, v10, s8 dst_sel:DWORD dst_unused:UNUSED_PAD src0_sel:BYTE_0 src1_sel:DWORD
	v_cvt_f32_u32_e32 v17, v17
	v_mul_f32_e32 v13, v22, v28
	v_fma_f32 v38, v24, v30, -v13
	v_mul_f32_e32 v13, v34, v34
	v_fma_f32 v40, v36, v36, -v13
	v_mul_f32_e64 v13, v36, -v34
	v_add_f32_e32 v42, v13, v13
	v_mul_f32_e32 v13, 0x39800000, v17
	v_sin_f32_e32 v46, v13
	v_cos_f32_e32 v48, v13
	v_mul_f32_e32 v13, v34, v40
	v_fma_f32 v50, v36, v42, -v13
	v_mul_f32_e32 v13, v46, v46
	v_fma_f32 v52, v48, v48, -v13
	v_mul_f32_e64 v13, v48, -v46
	v_add_f32_e32 v54, v13, v13
	v_mul_f32_e32 v13, 0x3a800000, v15
	v_sin_f32_e32 v58, v13
	v_cos_f32_e32 v60, v13
	v_mul_f32_e32 v13, v46, v52
	v_fma_f32 v62, v48, v54, -v13
	v_mul_f32_e32 v13, v58, v58
	v_fma_f32 v64, v60, v60, -v13
	v_mul_f32_e64 v13, v60, -v58
	v_add_f32_e32 v66, v13, v13
	v_mul_f32_e32 v20, v12, v18
	v_mul_f32_e32 v32, v22, v30
	v_mul_f32_e32 v44, v34, v42
	v_mul_f32_e32 v56, v46, v54
	v_mul_f32_e32 v68, v58, v66
	v_mul_f32_e32 v13, v58, v64
	v_fmac_f32_e32 v20, v14, v16
	v_fmac_f32_e32 v32, v24, v28
	v_fmac_f32_e32 v44, v36, v40
	v_fmac_f32_e32 v56, v48, v52
	v_fmac_f32_e32 v68, v60, v64
	v_fma_f32 v70, v60, v66, -v13
	v_mov_b32_e32 v61, v60
	v_mov_b32_e32 v59, v58
	v_mov_b32_e32 v65, v64
	v_mov_b32_e32 v67, v66
	v_mov_b32_e32 v69, v68
	v_mov_b32_e32 v71, v70
	v_mov_b32_e32 v15, v14
	v_mov_b32_e32 v13, v12
	v_mov_b32_e32 v37, v36
	v_mov_b32_e32 v35, v34
	v_mov_b32_e32 v25, v24
	v_mov_b32_e32 v23, v22
	v_mov_b32_e32 v49, v48
	v_mov_b32_e32 v47, v46
	v_mov_b32_e32 v17, v16
	v_mov_b32_e32 v41, v40
	v_mov_b32_e32 v29, v28
	v_mov_b32_e32 v53, v52
	v_mov_b32_e32 v21, v20
	v_mov_b32_e32 v27, v26
	v_mov_b32_e32 v45, v44
	v_mov_b32_e32 v51, v50
	v_mov_b32_e32 v33, v32
	v_mov_b32_e32 v39, v38
	v_mov_b32_e32 v57, v56
	v_mov_b32_e32 v63, v62
	v_mov_b32_e32 v19, v18
	v_mov_b32_e32 v31, v30
	v_mov_b32_e32 v43, v42
	v_mov_b32_e32 v55, v54
	s_mov_b64 s[10:11], 0
	v_mov_b32_e32 v73, v10
	v_and_b32_e32 v241, 0xff, v73
	v_add_u32_e32 v250, 0x0, v241
	v_cvt_f32_u32_e32 v250, v250
	v_mul_f32_e32 v250, 0x39800000, v250
	v_cos_f32_e32 v218, v250
	v_sin_f32_e32 v219, v250
	s_nop 1
	v_xor_b32_e32 v219, 0x80000000, v219
	s_nop 0
	v_pk_mul_f32 v[126:127], v[218:219], v[218:219] op_sel:[1,1] op_sel_hi:[1,0]
	s_nop 0
	v_pk_fma_f32 v[220:221], v[218:219], v[218:219], v[126:127] op_sel_hi:[0,1,1] neg_lo:[0,0,1]
	s_nop 0
	v_pk_mul_f32 v[126:127], v[220:221], v[218:219] op_sel:[1,1] op_sel_hi:[1,0]
	s_nop 0
	v_pk_fma_f32 v[222:223], v[220:221], v[218:219], v[126:127] op_sel_hi:[0,1,1] neg_lo:[0,0,1]
	s_nop 0
	v_add_u32_e32 v250, 0x100, v241
	v_cvt_f32_u32_e32 v250, v250
	v_mul_f32_e32 v250, 0x39800000, v250
	v_cos_f32_e32 v224, v250
	v_sin_f32_e32 v225, v250
	s_nop 1
	v_xor_b32_e32 v225, 0x80000000, v225
	s_nop 0
	v_pk_mul_f32 v[126:127], v[224:225], v[224:225] op_sel:[1,1] op_sel_hi:[1,0]
	s_nop 0
	v_pk_fma_f32 v[226:227], v[224:225], v[224:225], v[126:127] op_sel_hi:[0,1,1] neg_lo:[0,0,1]
	s_nop 0
	v_pk_mul_f32 v[126:127], v[226:227], v[224:225] op_sel:[1,1] op_sel_hi:[1,0]
	s_nop 0
	v_pk_fma_f32 v[228:229], v[226:227], v[224:225], v[126:127] op_sel_hi:[0,1,1] neg_lo:[0,0,1]
	s_nop 0
	v_add_u32_e32 v250, 0x200, v241
	v_cvt_f32_u32_e32 v250, v250
	v_mul_f32_e32 v250, 0x39800000, v250
	v_cos_f32_e32 v230, v250
	v_sin_f32_e32 v231, v250
	s_nop 1
	v_xor_b32_e32 v231, 0x80000000, v231
	s_nop 0
	v_pk_mul_f32 v[126:127], v[230:231], v[230:231] op_sel:[1,1] op_sel_hi:[1,0]
	s_nop 0
	v_pk_fma_f32 v[232:233], v[230:231], v[230:231], v[126:127] op_sel_hi:[0,1,1] neg_lo:[0,0,1]
	s_nop 0
	v_pk_mul_f32 v[126:127], v[232:233], v[230:231] op_sel:[1,1] op_sel_hi:[1,0]
	s_nop 0
	v_pk_fma_f32 v[234:235], v[232:233], v[230:231], v[126:127] op_sel_hi:[0,1,1] neg_lo:[0,0,1]
	s_nop 0
	v_add_u32_e32 v250, 0x300, v241
	v_cvt_f32_u32_e32 v250, v250
	v_mul_f32_e32 v250, 0x39800000, v250
	v_cos_f32_e32 v236, v250
	v_sin_f32_e32 v237, v250
	s_nop 1
	v_xor_b32_e32 v237, 0x80000000, v237
	s_nop 0
	v_pk_mul_f32 v[126:127], v[236:237], v[236:237] op_sel:[1,1] op_sel_hi:[1,0]
	s_nop 0
	v_pk_fma_f32 v[238:239], v[236:237], v[236:237], v[126:127] op_sel_hi:[0,1,1] neg_lo:[0,0,1]
	s_nop 0
	v_pk_mul_f32 v[126:127], v[238:239], v[236:237] op_sel:[1,1] op_sel_hi:[1,0]
	s_nop 0
	v_pk_fma_f32 v[242:243], v[238:239], v[236:237], v[126:127] op_sel_hi:[0,1,1] neg_lo:[0,0,1]
	s_nop 0
	v_cvt_f32_u32_e32 v250, v241
	v_mul_f32_e32 v250, 0x3a800000, v250
	v_cos_f32_e32 v244, v250
	v_sin_f32_e32 v245, v250
	s_nop 1
	v_xor_b32_e32 v245, 0x80000000, v245
	s_nop 0
	v_pk_mul_f32 v[126:127], v[244:245], v[244:245] op_sel:[1,1] op_sel_hi:[1,0]
	s_nop 0
	v_pk_fma_f32 v[246:247], v[244:245], v[244:245], v[126:127] op_sel_hi:[0,1,1] neg_lo:[0,0,1]
	s_nop 0
	v_pk_mul_f32 v[126:127], v[246:247], v[244:245] op_sel:[1,1] op_sel_hi:[1,0]
	s_nop 0
	v_pk_fma_f32 v[248:249], v[246:247], v[244:245], v[126:127] op_sel_hi:[0,1,1] neg_lo:[0,0,1]
	s_nop 0
; DI float2 twid(float r) { return float2{__builtin_amdgcn_cosf(r), -__builtin_amdgcn_sinf(r)}; }
; DI void bfly_fwd(float2 a0, float2 a1, float2 a2, float2 a3, float r, float2& o0, float2& o1, float2& o2, float2& o3) {
;   float2 t0 = {a0.x + a2.x, a0.y + a2.y}, t1 = {a0.x - a2.x, a0.y - a2.y}, t2 = {a1.x + a3.x, a1.y + a3.y}, t3 = {a1.x - a3.x, a1.y - a3.y};
;   float2 b0 = {t0.x + t2.x, t0.y + t2.y}, b2 = {t0.x - t2.x, t0.y - t2.y}, b1 = {t1.x + t3.y, t1.y - t3.x}, b3 = {t1.x - t3.y, t1.y + t3.x};
;   float2 w1 = twid(r), w2 = cmul(w1, w1), w3 = cmul(w2, w1);
;   o0 = b0; o1 = cmul(b1, w1); o2 = cmul(b2, w2); o3 = cmul(b3, w3);
; }
;     ...
;   for (int gg = tid; gg < NBT * (N / 16); gg += NTHR) { const int g = gg & (N / 16 - 1); float2* z = z0 + (gg / (N / 16)) * N; const int jp = g & (Q2 - 1), base = ((g >> lq2) << (lq2 + 4)) + jp; float2 x[4][4];
; #pragma unroll
;     for (int q1 = 0; q1 < 4; ++q1)
; #pragma unroll
;       for (int q2 = 0; q2 < 4; ++q2) x[q1][q2] = z[base + q1 * Q1 + q2 * Q2];
; #pragma unroll
;     for (int q2 = 0; q2 < 4; ++q2) bfly_fwd(x[0][q2], x[1][q2], x[2][q2], x[3][q2], (float)(jp + q2 * Q2) * invM1, x[0][q2], x[1][q2], x[2][q2], x[3][q2]);
; #pragma unroll
;     for (int q1 = 0; q1 < 4; ++q1) bfly_fwd(x[q1][0], x[q1][1], x[q1][2], x[q1][3], (float)jp * invM2, x[q1][0], x[q1][1], x[q1][2], x[q1][3]);
.LBB0_1490:
	v_ashrrev_i32_e32 v74, 31, v73
	v_lshrrev_b32_e32 v74, 23, v74
	v_add_lshl_u32 v74, v73, v74, 7
	v_and_b32_e32 v74, 0xffff0000, v74
	v_add_u32_e32 v90, v72, v74
	ds_read2st64_b64 v[76:79], v90 offset1:4
	ds_read2st64_b64 v[80:83], v90 offset0:8 offset1:12
	ds_read2st64_b64 v[84:87], v90 offset0:16 offset1:20
	ds_read2st64_b64 v[92:95], v90 offset0:24 offset1:28
	ds_read2st64_b64 v[96:99], v90 offset0:32 offset1:36
	ds_read2st64_b64 v[100:103], v90 offset0:40 offset1:44
	ds_read2st64_b64 v[104:107], v90 offset0:48 offset1:52
	ds_read2st64_b64 v[108:111], v90 offset0:56 offset1:60
	v_cmp_lt_i32_e64 s[8:9], -1, v73
	s_or_b64 s[10:11], s[8:9], s[10:11]
	s_waitcnt lgkmcnt(0)
	v_pk_add_f32 v[88:89], v[76:77], v[96:97]
	v_pk_add_f32 v[118:119], v[78:79], v[98:99]
	v_pk_add_f32 v[114:115], v[84:85], v[104:105]
	v_pk_add_f32 v[122:123], v[86:87], v[106:107]
	v_pk_add_f32 v[112:113], v[76:77], v[96:97] neg_lo:[0,1] neg_hi:[0,1]
	v_pk_add_f32 v[120:121], v[78:79], v[98:99] neg_lo:[0,1] neg_hi:[0,1]
	v_pk_add_f32 v[116:117], v[84:85], v[104:105] neg_lo:[0,1] neg_hi:[0,1]
	v_pk_add_f32 v[124:125], v[86:87], v[106:107] neg_lo:[0,1] neg_hi:[0,1]
	v_pk_add_f32 v[76:77], v[88:89], v[114:115]
	v_pk_add_f32 v[78:79], v[118:119], v[122:123]
	v_pk_add_f32 v[88:89], v[88:89], v[114:115] neg_lo:[0,1] neg_hi:[0,1]
	v_pk_add_f32 v[118:119], v[118:119], v[122:123] neg_lo:[0,1] neg_hi:[0,1]
	v_pk_add_f32 v[114:115], v[112:113], v[116:117] op_sel:[0,1] op_sel_hi:[1,0] neg_hi:[0,1]
	v_pk_add_f32 v[122:123], v[120:121], v[124:125] op_sel:[0,1] op_sel_hi:[1,0] neg_hi:[0,1]
	v_pk_add_f32 v[112:113], v[112:113], v[116:117] op_sel:[0,1] op_sel_hi:[1,0] neg_lo:[0,1]
	v_pk_add_f32 v[120:121], v[120:121], v[124:125] op_sel:[0,1] op_sel_hi:[1,0] neg_lo:[0,1]
	v_pk_mul_f32 v[126:127], v[88:89], v[220:221] op_sel:[1,1] op_sel_hi:[1,0]
	v_pk_mul_f32 v[130:131], v[118:119], v[226:227] op_sel:[1,1] op_sel_hi:[1,0]
	v_pk_mul_f32 v[128:129], v[114:115], v[218:219] op_sel:[1,1] op_sel_hi:[1,0]
	v_pk_mul_f32 v[132:133], v[122:123], v[224:225] op_sel:[1,1] op_sel_hi:[1,0]
	v_pk_fma_f32 v[96:97], v[88:89], v[220:221], v[126:127] op_sel_hi:[0,1,1] neg_lo:[0,0,1]
	v_pk_fma_f32 v[98:99], v[118:119], v[226:227], v[130:131] op_sel_hi:[0,1,1] neg_lo:[0,0,1]
	v_pk_mul_f32 v[126:127], v[112:113], v[222:223] op_sel:[1,1] op_sel_hi:[1,0]
	v_pk_mul_f32 v[130:131], v[120:121], v[228:229] op_sel:[1,1] op_sel_hi:[1,0]
	v_pk_fma_f32 v[84:85], v[114:115], v[218:219], v[128:129] op_sel_hi:[0,1,1] neg_lo:[0,0,1]
	v_pk_fma_f32 v[86:87], v[122:123], v[224:225], v[132:133] op_sel_hi:[0,1,1] neg_lo:[0,0,1]
	v_pk_fma_f32 v[104:105], v[112:113], v[222:223], v[126:127] op_sel_hi:[0,1,1] neg_lo:[0,0,1]
	v_pk_fma_f32 v[106:107], v[120:121], v[228:229], v[130:131] op_sel_hi:[0,1,1] neg_lo:[0,0,1]
	v_pk_add_f32 v[88:89], v[80:81], v[100:101]
	v_pk_add_f32 v[118:119], v[82:83], v[102:103]
	v_pk_add_f32 v[114:115], v[92:93], v[108:109]
	v_pk_add_f32 v[122:123], v[94:95], v[110:111]
	v_pk_add_f32 v[112:113], v[80:81], v[100:101] neg_lo:[0,1] neg_hi:[0,1]
	v_pk_add_f32 v[120:121], v[82:83], v[102:103] neg_lo:[0,1] neg_hi:[0,1]
	v_pk_add_f32 v[116:117], v[92:93], v[108:109] neg_lo:[0,1] neg_hi:[0,1]
	v_pk_add_f32 v[124:125], v[94:95], v[110:111] neg_lo:[0,1] neg_hi:[0,1]
	v_pk_add_f32 v[80:81], v[88:89], v[114:115]
	v_pk_add_f32 v[82:83], v[118:119], v[122:123]
	v_pk_add_f32 v[88:89], v[88:89], v[114:115] neg_lo:[0,1] neg_hi:[0,1]
	v_pk_add_f32 v[118:119], v[118:119], v[122:123] neg_lo:[0,1] neg_hi:[0,1]
	v_pk_add_f32 v[114:115], v[112:113], v[116:117] op_sel:[0,1] op_sel_hi:[1,0] neg_hi:[0,1]
	v_pk_add_f32 v[122:123], v[120:121], v[124:125] op_sel:[0,1] op_sel_hi:[1,0] neg_hi:[0,1]
	v_pk_add_f32 v[112:113], v[112:113], v[116:117] op_sel:[0,1] op_sel_hi:[1,0] neg_lo:[0,1]
	v_pk_add_f32 v[120:121], v[120:121], v[124:125] op_sel:[0,1] op_sel_hi:[1,0] neg_lo:[0,1]
	v_pk_mul_f32 v[126:127], v[88:89], v[232:233] op_sel:[1,1] op_sel_hi:[1,0]
	v_pk_mul_f32 v[130:131], v[118:119], v[238:239] op_sel:[1,1] op_sel_hi:[1,0]
	v_pk_mul_f32 v[128:129], v[114:115], v[230:231] op_sel:[1,1] op_sel_hi:[1,0]
	v_pk_mul_f32 v[132:133], v[122:123], v[236:237] op_sel:[1,1] op_sel_hi:[1,0]
	v_pk_fma_f32 v[100:101], v[88:89], v[232:233], v[126:127] op_sel_hi:[0,1,1] neg_lo:[0,0,1]
	v_pk_fma_f32 v[102:103], v[118:119], v[238:239], v[130:131] op_sel_hi:[0,1,1] neg_lo:[0,0,1]
	v_pk_mul_f32 v[126:127], v[112:113], v[234:235] op_sel:[1,1] op_sel_hi:[1,0]
	v_pk_mul_f32 v[130:131], v[120:121], v[242:243] op_sel:[1,1] op_sel_hi:[1,0]
	v_pk_fma_f32 v[92:93], v[114:115], v[230:231], v[128:129] op_sel_hi:[0,1,1] neg_lo:[0,0,1]
	v_pk_fma_f32 v[94:95], v[122:123], v[236:237], v[132:133] op_sel_hi:[0,1,1] neg_lo:[0,0,1]
	v_pk_fma_f32 v[108:109], v[112:113], v[234:235], v[126:127] op_sel_hi:[0,1,1] neg_lo:[0,0,1]
	v_pk_fma_f32 v[110:111], v[120:121], v[242:243], v[130:131] op_sel_hi:[0,1,1] neg_lo:[0,0,1]
	v_pk_add_f32 v[88:89], v[76:77], v[80:81]
	v_pk_add_f32 v[118:119], v[84:85], v[92:93]
	v_pk_add_f32 v[114:115], v[78:79], v[82:83]
	v_pk_add_f32 v[122:123], v[86:87], v[94:95]
	v_pk_add_f32 v[112:113], v[76:77], v[80:81] neg_lo:[0,1] neg_hi:[0,1]
	v_pk_add_f32 v[120:121], v[84:85], v[92:93] neg_lo:[0,1] neg_hi:[0,1]
	v_pk_add_f32 v[116:117], v[78:79], v[82:83] neg_lo:[0,1] neg_hi:[0,1]
	v_pk_add_f32 v[124:125], v[86:87], v[94:95] neg_lo:[0,1] neg_hi:[0,1]
	v_pk_add_f32 v[76:77], v[88:89], v[114:115]
	v_pk_add_f32 v[84:85], v[118:119], v[122:123]
	v_pk_add_f32 v[88:89], v[88:89], v[114:115] neg_lo:[0,1] neg_hi:[0,1]
	v_pk_add_f32 v[118:119], v[118:119], v[122:123] neg_lo:[0,1] neg_hi:[0,1]
	v_pk_add_f32 v[114:115], v[112:113], v[116:117] op_sel:[0,1] op_sel_hi:[1,0] neg_hi:[0,1]
;   const int lq2 = lq1 - 2, Q1 = 1 << lq1, Q2 = 1 << lq2; const float invM1 = 1.f / (float)(4 << lq1), invM2 = 1.f / (float)(4 << lq2);
;   for (int gg = tid; gg < NBT * (N / 16); gg += NTHR) { const int g = gg & (N / 16 - 1); float2* z = z0 + (gg / (N / 16)) * N; const int jp = g & (Q2 - 1), base = ((g >> lq2) << (lq2 + 4)) + jp; float2 x[4][4];
;     ...
;     for (int q1 = 0; q1 < 4; ++q1) bfly_fwd(x[q1][0], x[q1][1], x[q1][2], x[q1][3], (float)jp * invM2, x[q1][0], x[q1][1], x[q1][2], x[q1][3]);
; #pragma unroll
;     for (int q1 = 0; q1 < 4; ++q1)
; #pragma unroll
;       for (int q2 = 0; q2 < 4; ++q2) z[base + q1 * Q1 + q2 * Q2] = x[q1][q2]; }
;   __syncthreads();
; }
	v_pk_add_f32 v[122:123], v[120:121], v[124:125] op_sel:[0,1] op_sel_hi:[1,0] neg_hi:[0,1]
	v_pk_add_f32 v[112:113], v[112:113], v[116:117] op_sel:[0,1] op_sel_hi:[1,0] neg_lo:[0,1]
	v_pk_add_f32 v[120:121], v[120:121], v[124:125] op_sel:[0,1] op_sel_hi:[1,0] neg_lo:[0,1]
	v_pk_mul_f32 v[126:127], v[88:89], v[246:247] op_sel:[1,1] op_sel_hi:[1,0]
	v_pk_mul_f32 v[130:131], v[118:119], v[246:247] op_sel:[1,1] op_sel_hi:[1,0]
	v_pk_mul_f32 v[128:129], v[114:115], v[244:245] op_sel:[1,1] op_sel_hi:[1,0]
	v_pk_mul_f32 v[132:133], v[122:123], v[244:245] op_sel:[1,1] op_sel_hi:[1,0]
	v_pk_fma_f32 v[80:81], v[88:89], v[246:247], v[126:127] op_sel_hi:[0,1,1] neg_lo:[0,0,1]
	v_pk_fma_f32 v[92:93], v[118:119], v[246:247], v[130:131] op_sel_hi:[0,1,1] neg_lo:[0,0,1]
	v_pk_mul_f32 v[126:127], v[112:113], v[248:249] op_sel:[1,1] op_sel_hi:[1,0]
	v_pk_mul_f32 v[130:131], v[120:121], v[248:249] op_sel:[1,1] op_sel_hi:[1,0]
	v_pk_fma_f32 v[78:79], v[114:115], v[244:245], v[128:129] op_sel_hi:[0,1,1] neg_lo:[0,0,1]
	v_pk_fma_f32 v[86:87], v[122:123], v[244:245], v[132:133] op_sel_hi:[0,1,1] neg_lo:[0,0,1]
	v_pk_fma_f32 v[82:83], v[112:113], v[248:249], v[126:127] op_sel_hi:[0,1,1] neg_lo:[0,0,1]
	v_pk_fma_f32 v[94:95], v[120:121], v[248:249], v[130:131] op_sel_hi:[0,1,1] neg_lo:[0,0,1]
	v_pk_add_f32 v[88:89], v[96:97], v[100:101]
	v_pk_add_f32 v[118:119], v[104:105], v[108:109]
	v_pk_add_f32 v[114:115], v[98:99], v[102:103]
	v_pk_add_f32 v[122:123], v[106:107], v[110:111]
	v_pk_add_f32 v[112:113], v[96:97], v[100:101] neg_lo:[0,1] neg_hi:[0,1]
	v_pk_add_f32 v[120:121], v[104:105], v[108:109] neg_lo:[0,1] neg_hi:[0,1]
	v_pk_add_f32 v[116:117], v[98:99], v[102:103] neg_lo:[0,1] neg_hi:[0,1]
	v_pk_add_f32 v[124:125], v[106:107], v[110:111] neg_lo:[0,1] neg_hi:[0,1]
	v_pk_add_f32 v[96:97], v[88:89], v[114:115]
	v_pk_add_f32 v[104:105], v[118:119], v[122:123]
	v_pk_add_f32 v[88:89], v[88:89], v[114:115] neg_lo:[0,1] neg_hi:[0,1]
	v_pk_add_f32 v[118:119], v[118:119], v[122:123] neg_lo:[0,1] neg_hi:[0,1]
	v_pk_add_f32 v[114:115], v[112:113], v[116:117] op_sel:[0,1] op_sel_hi:[1,0] neg_hi:[0,1]
	v_pk_add_f32 v[122:123], v[120:121], v[124:125] op_sel:[0,1] op_sel_hi:[1,0] neg_hi:[0,1]
	v_pk_add_f32 v[112:113], v[112:113], v[116:117] op_sel:[0,1] op_sel_hi:[1,0] neg_lo:[0,1]
	v_pk_add_f32 v[120:121], v[120:121], v[124:125] op_sel:[0,1] op_sel_hi:[1,0] neg_lo:[0,1]
	v_pk_mul_f32 v[126:127], v[88:89], v[246:247] op_sel:[1,1] op_sel_hi:[1,0]
	v_pk_mul_f32 v[130:131], v[118:119], v[246:247] op_sel:[1,1] op_sel_hi:[1,0]
	v_pk_mul_f32 v[128:129], v[114:115], v[244:245] op_sel:[1,1] op_sel_hi:[1,0]
	v_pk_mul_f32 v[132:133], v[122:123], v[244:245] op_sel:[1,1] op_sel_hi:[1,0]
	v_pk_fma_f32 v[100:101], v[88:89], v[246:247], v[126:127] op_sel_hi:[0,1,1] neg_lo:[0,0,1]
	v_pk_fma_f32 v[108:109], v[118:119], v[246:247], v[130:131] op_sel_hi:[0,1,1] neg_lo:[0,0,1]
	v_pk_mul_f32 v[126:127], v[112:113], v[248:249] op_sel:[1,1] op_sel_hi:[1,0]
	v_pk_mul_f32 v[130:131], v[120:121], v[248:249] op_sel:[1,1] op_sel_hi:[1,0]
	v_pk_fma_f32 v[98:99], v[114:115], v[244:245], v[128:129] op_sel_hi:[0,1,1] neg_lo:[0,0,1]
	v_pk_fma_f32 v[106:107], v[122:123], v[244:245], v[132:133] op_sel_hi:[0,1,1] neg_lo:[0,0,1]
	v_pk_fma_f32 v[102:103], v[112:113], v[248:249], v[126:127] op_sel_hi:[0,1,1] neg_lo:[0,0,1]
	v_pk_fma_f32 v[110:111], v[120:121], v[248:249], v[130:131] op_sel_hi:[0,1,1] neg_lo:[0,0,1]
	s_nop 0
	ds_write2st64_b64 v90, v[76:77], v[78:79] offset1:4
	ds_write2st64_b64 v90, v[80:81], v[82:83] offset0:8 offset1:12
	ds_write2st64_b64 v90, v[84:85], v[86:87] offset0:16 offset1:20
	ds_write2st64_b64 v90, v[92:93], v[94:95] offset0:24 offset1:28
	ds_write2st64_b64 v90, v[96:97], v[98:99] offset0:32 offset1:36
	ds_write2st64_b64 v90, v[100:101], v[102:103] offset0:40 offset1:44
	ds_write2st64_b64 v90, v[104:105], v[106:107] offset0:48 offset1:52
	ds_write2st64_b64 v90, v[108:109], v[110:111] offset0:56 offset1:60
	v_add_u32_e32 v74, 0x200, v73
	v_mov_b32_e32 v73, v74
	s_andn2_b64 exec, exec, s[10:11]
	s_cbranch_execnz .LBB0_1490
.LBB0_1491:
	s_or_b64 exec, exec, s[0:1]
	s_waitcnt lgkmcnt(0)
	s_barrier
	s_and_saveexec_b64 s[0:1], vcc
	s_cbranch_execz .LBB0_1494
	v_and_b32_e32 v13, 15, v10
	v_cvt_f32_ubyte0_e32 v15, v13
	v_mul_f32_e32 v14, 0x3b800000, v15
	v_sin_f32_e32 v12, v14
	v_cos_f32_e32 v14, v14
	v_and_b32_e32 v11, 0xf800, v11
	v_lshlrev_b32_e32 v16, 3, v13
	v_add3_u32 v11, 16, v11, v16
	v_mul_f32_e64 v17, v14, -v12
	v_add_f32_e32 v18, v17, v17
	v_or_b32_e32 v17, 16, v13
	v_cvt_f32_ubyte0_e32 v17, v17
	v_mul_f32_e32 v17, 0x3b800000, v17
	v_sin_f32_e32 v22, v17
	v_mul_f32_e32 v16, v12, v12
	v_cos_f32_e32 v24, v17
	v_fma_f32 v16, v14, v14, -v16
	v_mul_f32_e32 v17, v12, v16
	v_fma_f32 v26, v14, v18, -v17
	v_mul_f32_e32 v17, v22, v22
	v_fma_f32 v28, v24, v24, -v17
	v_mul_f32_e64 v17, v24, -v22
	v_add_f32_e32 v30, v17, v17
	v_or_b32_e32 v17, 32, v13
	v_cvt_f32_ubyte0_e32 v17, v17
	v_mul_f32_e32 v17, 0x3b800000, v17
	v_sin_f32_e32 v34, v17
	v_or_b32_e32 v13, 48, v13
	v_cos_f32_e32 v36, v17
	v_cvt_f32_ubyte0_e32 v13, v13
	v_mul_f32_e32 v13, 0x3b800000, v13
	v_mul_f32_e32 v17, v22, v28
	v_sin_f32_e32 v46, v13
	v_fma_f32 v38, v24, v30, -v17
	v_mul_f32_e32 v17, v34, v34
	v_cos_f32_e32 v48, v13
	v_fma_f32 v40, v36, v36, -v17
	v_mul_f32_e64 v17, v36, -v34
	v_add_f32_e32 v42, v17, v17
	v_mul_f32_e32 v13, v34, v40
	v_fma_f32 v50, v36, v42, -v13
	v_mul_f32_e32 v13, v46, v46
	v_fma_f32 v52, v48, v48, -v13
	v_mul_f32_e64 v13, v48, -v46
	v_add_f32_e32 v54, v13, v13
	v_mul_f32_e32 v13, 0x3c800000, v15
	v_sin_f32_e32 v58, v13
	v_cos_f32_e32 v60, v13
	v_mul_f32_e32 v13, v46, v52
	v_fma_f32 v62, v48, v54, -v13
; DI float2 twid(float r) { return float2{__builtin_amdgcn_cosf(r), -__builtin_amdgcn_sinf(r)}; }
; DI void bfly_fwd(float2 a0, float2 a1, float2 a2, float2 a3, float r, float2& o0, float2& o1, float2& o2, float2& o3) {
;   float2 t0 = {a0.x + a2.x, a0.y + a2.y}, t1 = {a0.x - a2.x, a0.y - a2.y}, t2 = {a1.x + a3.x, a1.y + a3.y}, t3 = {a1.x - a3.x, a1.y - a3.y};
;   float2 b0 = {t0.x + t2.x, t0.y + t2.y}, b2 = {t0.x - t2.x, t0.y - t2.y}, b1 = {t1.x + t3.y, t1.y - t3.x}, b3 = {t1.x - t3.y, t1.y + t3.x};
;   float2 w1 = twid(r), w2 = cmul(w1, w1), w3 = cmul(w2, w1);
;   o0 = b0; o1 = cmul(b1, w1); o2 = cmul(b2, w2); o3 = cmul(b3, w3);
;   const int lq2 = lq1 - 2, Q1 = 1 << lq1, Q2 = 1 << lq2; const float invM1 = 1.f / (float)(4 << lq1), invM2 = 1.f / (float)(4 << lq2);
;   for (int gg = tid; gg < NBT * (N / 16); gg += NTHR) { const int g = gg & (N / 16 - 1); float2* z = z0 + (gg / (N / 16)) * N; const int jp = g & (Q2 - 1), base = ((g >> lq2) << (lq2 + 4)) + jp; float2 x[4][4];
; #pragma unroll
;     for (int q1 = 0; q1 < 4; ++q1)
; #pragma unroll
;       for (int q2 = 0; q2 < 4; ++q2) x[q1][q2] = z[base + q1 * Q1 + q2 * Q2];
	v_mul_f32_e32 v13, v58, v58
	v_fma_f32 v64, v60, v60, -v13
	v_mul_f32_e64 v13, v60, -v58
	v_add_f32_e32 v66, v13, v13
	v_mul_f32_e32 v20, v12, v18
	v_mul_f32_e32 v32, v22, v30
	v_mul_f32_e32 v44, v34, v42
	v_mul_f32_e32 v56, v46, v54
	v_mul_f32_e32 v68, v58, v66
	v_mul_f32_e32 v13, v58, v64
	v_fmac_f32_e32 v20, v14, v16
	v_fmac_f32_e32 v32, v24, v28
	v_fmac_f32_e32 v44, v36, v40
	v_fmac_f32_e32 v56, v48, v52
	v_fmac_f32_e32 v68, v60, v64
	v_fma_f32 v70, v60, v66, -v13
	v_mov_b32_e32 v61, v60
	v_mov_b32_e32 v59, v58
	v_mov_b32_e32 v65, v64
	v_mov_b32_e32 v67, v66
	v_mov_b32_e32 v69, v68
	v_mov_b32_e32 v71, v70
	v_mov_b32_e32 v15, v14
	v_mov_b32_e32 v13, v12
	v_mov_b32_e32 v37, v36
	v_mov_b32_e32 v35, v34
	v_mov_b32_e32 v25, v24
	v_mov_b32_e32 v23, v22
	v_mov_b32_e32 v49, v48
	v_mov_b32_e32 v47, v46
	v_mov_b32_e32 v17, v16
	v_mov_b32_e32 v41, v40
	v_mov_b32_e32 v29, v28
	v_mov_b32_e32 v53, v52
	v_mov_b32_e32 v21, v20
	v_mov_b32_e32 v27, v26
	v_mov_b32_e32 v45, v44
	v_mov_b32_e32 v51, v50
	v_mov_b32_e32 v33, v32
	v_mov_b32_e32 v39, v38
	v_mov_b32_e32 v57, v56
	v_mov_b32_e32 v63, v62
	v_mov_b32_e32 v19, v18
	v_mov_b32_e32 v31, v30
	v_mov_b32_e32 v43, v42
	v_mov_b32_e32 v55, v54
	s_mov_b64 s[8:9], 0
	v_mov_b32_e32 v72, v10
	v_and_b32_e32 v241, 0xf, v72
	v_add_u32_e32 v250, 0x0, v241
	v_cvt_f32_u32_e32 v250, v250
	v_mul_f32_e32 v250, 0x3b800000, v250
	v_cos_f32_e32 v218, v250
	v_sin_f32_e32 v219, v250
	s_nop 1
	v_xor_b32_e32 v219, 0x80000000, v219
	s_nop 0
	v_pk_mul_f32 v[124:125], v[218:219], v[218:219] op_sel:[1,1] op_sel_hi:[1,0]
	s_nop 0
	v_pk_fma_f32 v[220:221], v[218:219], v[218:219], v[124:125] op_sel_hi:[0,1,1] neg_lo:[0,0,1]
	s_nop 0
	v_pk_mul_f32 v[124:125], v[220:221], v[218:219] op_sel:[1,1] op_sel_hi:[1,0]
	s_nop 0
	v_pk_fma_f32 v[222:223], v[220:221], v[218:219], v[124:125] op_sel_hi:[0,1,1] neg_lo:[0,0,1]
	s_nop 0
	v_add_u32_e32 v250, 0x10, v241
	v_cvt_f32_u32_e32 v250, v250
	v_mul_f32_e32 v250, 0x3b800000, v250
	v_cos_f32_e32 v224, v250
	v_sin_f32_e32 v225, v250
	s_nop 1
	v_xor_b32_e32 v225, 0x80000000, v225
	s_nop 0
	v_pk_mul_f32 v[124:125], v[224:225], v[224:225] op_sel:[1,1] op_sel_hi:[1,0]
	s_nop 0
	v_pk_fma_f32 v[226:227], v[224:225], v[224:225], v[124:125] op_sel_hi:[0,1,1] neg_lo:[0,0,1]
	s_nop 0
	v_pk_mul_f32 v[124:125], v[226:227], v[224:225] op_sel:[1,1] op_sel_hi:[1,0]
	s_nop 0
	v_pk_fma_f32 v[228:229], v[226:227], v[224:225], v[124:125] op_sel_hi:[0,1,1] neg_lo:[0,0,1]
	s_nop 0
	v_add_u32_e32 v250, 0x20, v241
	v_cvt_f32_u32_e32 v250, v250
	v_mul_f32_e32 v250, 0x3b800000, v250
	v_cos_f32_e32 v230, v250
	v_sin_f32_e32 v231, v250
	s_nop 1
	v_xor_b32_e32 v231, 0x80000000, v231
	s_nop 0
	v_pk_mul_f32 v[124:125], v[230:231], v[230:231] op_sel:[1,1] op_sel_hi:[1,0]
	s_nop 0
	v_pk_fma_f32 v[232:233], v[230:231], v[230:231], v[124:125] op_sel_hi:[0,1,1] neg_lo:[0,0,1]
	s_nop 0
	v_pk_mul_f32 v[124:125], v[232:233], v[230:231] op_sel:[1,1] op_sel_hi:[1,0]
	s_nop 0
	v_pk_fma_f32 v[234:235], v[232:233], v[230:231], v[124:125] op_sel_hi:[0,1,1] neg_lo:[0,0,1]
	s_nop 0
	v_add_u32_e32 v250, 0x30, v241
	v_cvt_f32_u32_e32 v250, v250
	v_mul_f32_e32 v250, 0x3b800000, v250
	v_cos_f32_e32 v236, v250
	v_sin_f32_e32 v237, v250
	s_nop 1
	v_xor_b32_e32 v237, 0x80000000, v237
	s_nop 0
	v_pk_mul_f32 v[124:125], v[236:237], v[236:237] op_sel:[1,1] op_sel_hi:[1,0]
	s_nop 0
	v_pk_fma_f32 v[238:239], v[236:237], v[236:237], v[124:125] op_sel_hi:[0,1,1] neg_lo:[0,0,1]
	s_nop 0
	v_pk_mul_f32 v[124:125], v[238:239], v[236:237] op_sel:[1,1] op_sel_hi:[1,0]
	s_nop 0
	v_pk_fma_f32 v[242:243], v[238:239], v[236:237], v[124:125] op_sel_hi:[0,1,1] neg_lo:[0,0,1]
	s_nop 0
	v_cvt_f32_u32_e32 v250, v241
	v_mul_f32_e32 v250, 0x3c800000, v250
	v_cos_f32_e32 v244, v250
	v_sin_f32_e32 v245, v250
	s_nop 1
	v_xor_b32_e32 v245, 0x80000000, v245
	s_nop 0
	v_pk_mul_f32 v[124:125], v[244:245], v[244:245] op_sel:[1,1] op_sel_hi:[1,0]
	s_nop 0
	v_pk_fma_f32 v[246:247], v[244:245], v[244:245], v[124:125] op_sel_hi:[0,1,1] neg_lo:[0,0,1]
	s_nop 0
	v_pk_mul_f32 v[124:125], v[246:247], v[244:245] op_sel:[1,1] op_sel_hi:[1,0]
	s_nop 0
	v_pk_fma_f32 v[248:249], v[246:247], v[244:245], v[124:125] op_sel_hi:[0,1,1] neg_lo:[0,0,1]
	s_nop 0
.LBB0_1493:
	v_ashrrev_i32_e32 v73, 31, v72
	v_lshrrev_b32_e32 v73, 23, v73
	v_add_lshl_u32 v73, v72, v73, 7
	v_and_b32_e32 v73, 0xffff0000, v73
	v_add_u32_e32 v73, v11, v73
	ds_read2_b64 v[74:77], v73 offset1:16
	ds_read2_b64 v[78:81], v73 offset0:32 offset1:48
	ds_read2_b64 v[82:85], v73 offset0:64 offset1:80
	ds_read2_b64 v[86:89], v73 offset0:96 offset1:112
	ds_read2_b64 v[92:95], v73 offset0:128 offset1:144
	ds_read2_b64 v[96:99], v73 offset0:160 offset1:176
	ds_read2_b64 v[100:103], v73 offset0:192 offset1:208
	ds_read2_b64 v[104:107], v73 offset0:224 offset1:240
	v_cmp_lt_i32_e32 vcc, -1, v72
	s_or_b64 s[8:9], vcc, s[8:9]
	s_waitcnt lgkmcnt(0)
; DI float2 twid(float r) { return float2{__builtin_amdgcn_cosf(r), -__builtin_amdgcn_sinf(r)}; }
; DI void bfly_fwd(float2 a0, float2 a1, float2 a2, float2 a3, float r, float2& o0, float2& o1, float2& o2, float2& o3) {
;   float2 t0 = {a0.x + a2.x, a0.y + a2.y}, t1 = {a0.x - a2.x, a0.y - a2.y}, t2 = {a1.x + a3.x, a1.y + a3.y}, t3 = {a1.x - a3.x, a1.y - a3.y};
;   float2 b0 = {t0.x + t2.x, t0.y + t2.y}, b2 = {t0.x - t2.x, t0.y - t2.y}, b1 = {t1.x + t3.y, t1.y - t3.x}, b3 = {t1.x - t3.y, t1.y + t3.x};
;   float2 w1 = twid(r), w2 = cmul(w1, w1), w3 = cmul(w2, w1);
;   o0 = b0; o1 = cmul(b1, w1); o2 = cmul(b2, w2); o3 = cmul(b3, w3);
; }
;     ...
;       for (int q2 = 0; q2 < 4; ++q2) x[q1][q2] = z[base + q1 * Q1 + q2 * Q2];
; #pragma unroll
;     for (int q2 = 0; q2 < 4; ++q2) bfly_fwd(x[0][q2], x[1][q2], x[2][q2], x[3][q2], (float)(jp + q2 * Q2) * invM1, x[0][q2], x[1][q2], x[2][q2], x[3][q2]);
	v_pk_add_f32 v[108:109], v[74:75], v[92:93]
	v_pk_add_f32 v[116:117], v[76:77], v[94:95]
	v_pk_add_f32 v[112:113], v[82:83], v[100:101]
	v_pk_add_f32 v[120:121], v[84:85], v[102:103]
	v_pk_add_f32 v[110:111], v[74:75], v[92:93] neg_lo:[0,1] neg_hi:[0,1]
	v_pk_add_f32 v[118:119], v[76:77], v[94:95] neg_lo:[0,1] neg_hi:[0,1]
	v_pk_add_f32 v[114:115], v[82:83], v[100:101] neg_lo:[0,1] neg_hi:[0,1]
	v_pk_add_f32 v[122:123], v[84:85], v[102:103] neg_lo:[0,1] neg_hi:[0,1]
	v_pk_add_f32 v[74:75], v[108:109], v[112:113]
	v_pk_add_f32 v[76:77], v[116:117], v[120:121]
	v_pk_add_f32 v[108:109], v[108:109], v[112:113] neg_lo:[0,1] neg_hi:[0,1]
	v_pk_add_f32 v[116:117], v[116:117], v[120:121] neg_lo:[0,1] neg_hi:[0,1]
	v_pk_add_f32 v[112:113], v[110:111], v[114:115] op_sel:[0,1] op_sel_hi:[1,0] neg_hi:[0,1]
	v_pk_add_f32 v[120:121], v[118:119], v[122:123] op_sel:[0,1] op_sel_hi:[1,0] neg_hi:[0,1]
	v_pk_add_f32 v[110:111], v[110:111], v[114:115] op_sel:[0,1] op_sel_hi:[1,0] neg_lo:[0,1]
	v_pk_add_f32 v[118:119], v[118:119], v[122:123] op_sel:[0,1] op_sel_hi:[1,0] neg_lo:[0,1]
	v_pk_mul_f32 v[124:125], v[108:109], v[220:221] op_sel:[1,1] op_sel_hi:[1,0]
	v_pk_mul_f32 v[128:129], v[116:117], v[226:227] op_sel:[1,1] op_sel_hi:[1,0]
	v_pk_mul_f32 v[126:127], v[112:113], v[218:219] op_sel:[1,1] op_sel_hi:[1,0]
	v_pk_mul_f32 v[130:131], v[120:121], v[224:225] op_sel:[1,1] op_sel_hi:[1,0]
	v_pk_fma_f32 v[92:93], v[108:109], v[220:221], v[124:125] op_sel_hi:[0,1,1] neg_lo:[0,0,1]
	v_pk_fma_f32 v[94:95], v[116:117], v[226:227], v[128:129] op_sel_hi:[0,1,1] neg_lo:[0,0,1]
	v_pk_mul_f32 v[124:125], v[110:111], v[222:223] op_sel:[1,1] op_sel_hi:[1,0]
	v_pk_mul_f32 v[128:129], v[118:119], v[228:229] op_sel:[1,1] op_sel_hi:[1,0]
	v_pk_fma_f32 v[82:83], v[112:113], v[218:219], v[126:127] op_sel_hi:[0,1,1] neg_lo:[0,0,1]
	v_pk_fma_f32 v[84:85], v[120:121], v[224:225], v[130:131] op_sel_hi:[0,1,1] neg_lo:[0,0,1]
	v_pk_fma_f32 v[100:101], v[110:111], v[222:223], v[124:125] op_sel_hi:[0,1,1] neg_lo:[0,0,1]
	v_pk_fma_f32 v[102:103], v[118:119], v[228:229], v[128:129] op_sel_hi:[0,1,1] neg_lo:[0,0,1]
	v_pk_add_f32 v[108:109], v[78:79], v[96:97]
	v_pk_add_f32 v[116:117], v[80:81], v[98:99]
	v_pk_add_f32 v[112:113], v[86:87], v[104:105]
	v_pk_add_f32 v[120:121], v[88:89], v[106:107]
	v_pk_add_f32 v[110:111], v[78:79], v[96:97] neg_lo:[0,1] neg_hi:[0,1]
	v_pk_add_f32 v[118:119], v[80:81], v[98:99] neg_lo:[0,1] neg_hi:[0,1]
	v_pk_add_f32 v[114:115], v[86:87], v[104:105] neg_lo:[0,1] neg_hi:[0,1]
	v_pk_add_f32 v[122:123], v[88:89], v[106:107] neg_lo:[0,1] neg_hi:[0,1]
	v_pk_add_f32 v[78:79], v[108:109], v[112:113]
	v_pk_add_f32 v[80:81], v[116:117], v[120:121]
	v_pk_add_f32 v[108:109], v[108:109], v[112:113] neg_lo:[0,1] neg_hi:[0,1]
	v_pk_add_f32 v[116:117], v[116:117], v[120:121] neg_lo:[0,1] neg_hi:[0,1]
	v_pk_add_f32 v[112:113], v[110:111], v[114:115] op_sel:[0,1] op_sel_hi:[1,0] neg_hi:[0,1]
	v_pk_add_f32 v[120:121], v[118:119], v[122:123] op_sel:[0,1] op_sel_hi:[1,0] neg_hi:[0,1]
	v_pk_add_f32 v[110:111], v[110:111], v[114:115] op_sel:[0,1] op_sel_hi:[1,0] neg_lo:[0,1]
	v_pk_add_f32 v[118:119], v[118:119], v[122:123] op_sel:[0,1] op_sel_hi:[1,0] neg_lo:[0,1]
	v_pk_mul_f32 v[124:125], v[108:109], v[232:233] op_sel:[1,1] op_sel_hi:[1,0]
	v_pk_mul_f32 v[128:129], v[116:117], v[238:239] op_sel:[1,1] op_sel_hi:[1,0]
	v_pk_mul_f32 v[126:127], v[112:113], v[230:231] op_sel:[1,1] op_sel_hi:[1,0]
	v_pk_mul_f32 v[130:131], v[120:121], v[236:237] op_sel:[1,1] op_sel_hi:[1,0]
	v_pk_fma_f32 v[96:97], v[108:109], v[232:233], v[124:125] op_sel_hi:[0,1,1] neg_lo:[0,0,1]
	v_pk_fma_f32 v[98:99], v[116:117], v[238:239], v[128:129] op_sel_hi:[0,1,1] neg_lo:[0,0,1]
	v_pk_mul_f32 v[124:125], v[110:111], v[234:235] op_sel:[1,1] op_sel_hi:[1,0]
	v_pk_mul_f32 v[128:129], v[118:119], v[242:243] op_sel:[1,1] op_sel_hi:[1,0]
	v_pk_fma_f32 v[86:87], v[112:113], v[230:231], v[126:127] op_sel_hi:[0,1,1] neg_lo:[0,0,1]
	v_pk_fma_f32 v[88:89], v[120:121], v[236:237], v[130:131] op_sel_hi:[0,1,1] neg_lo:[0,0,1]
	v_pk_fma_f32 v[104:105], v[110:111], v[234:235], v[124:125] op_sel_hi:[0,1,1] neg_lo:[0,0,1]
	v_pk_fma_f32 v[106:107], v[118:119], v[242:243], v[128:129] op_sel_hi:[0,1,1] neg_lo:[0,0,1]
	v_pk_add_f32 v[108:109], v[74:75], v[78:79]
	v_pk_add_f32 v[116:117], v[82:83], v[86:87]
	v_pk_add_f32 v[112:113], v[76:77], v[80:81]
	v_pk_add_f32 v[120:121], v[84:85], v[88:89]
	v_pk_add_f32 v[110:111], v[74:75], v[78:79] neg_lo:[0,1] neg_hi:[0,1]
	v_pk_add_f32 v[118:119], v[82:83], v[86:87] neg_lo:[0,1] neg_hi:[0,1]
; DI float2 twid(float r) { return float2{__builtin_amdgcn_cosf(r), -__builtin_amdgcn_sinf(r)}; }
; DI void bfly_fwd(float2 a0, float2 a1, float2 a2, float2 a3, float r, float2& o0, float2& o1, float2& o2, float2& o3) {
;   float2 t0 = {a0.x + a2.x, a0.y + a2.y}, t1 = {a0.x - a2.x, a0.y - a2.y}, t2 = {a1.x + a3.x, a1.y + a3.y}, t3 = {a1.x - a3.x, a1.y - a3.y};
;   float2 b0 = {t0.x + t2.x, t0.y + t2.y}, b2 = {t0.x - t2.x, t0.y - t2.y}, b1 = {t1.x + t3.y, t1.y - t3.x}, b3 = {t1.x - t3.y, t1.y + t3.x};
;   float2 w1 = twid(r), w2 = cmul(w1, w1), w3 = cmul(w2, w1);
;   o0 = b0; o1 = cmul(b1, w1); o2 = cmul(b2, w2); o3 = cmul(b3, w3);
; }
;     ...
;     for (int q1 = 0; q1 < 4; ++q1) bfly_fwd(x[q1][0], x[q1][1], x[q1][2], x[q1][3], (float)jp * invM2, x[q1][0], x[q1][1], x[q1][2], x[q1][3]);
; #pragma unroll
;     for (int q1 = 0; q1 < 4; ++q1)
; #pragma unroll
;       for (int q2 = 0; q2 < 4; ++q2) z[base + q1 * Q1 + q2 * Q2] = x[q1][q2]; }
;   __syncthreads();
; }
	v_pk_add_f32 v[114:115], v[76:77], v[80:81] neg_lo:[0,1] neg_hi:[0,1]
	v_pk_add_f32 v[122:123], v[84:85], v[88:89] neg_lo:[0,1] neg_hi:[0,1]
	v_pk_add_f32 v[74:75], v[108:109], v[112:113]
	v_pk_add_f32 v[82:83], v[116:117], v[120:121]
	v_pk_add_f32 v[108:109], v[108:109], v[112:113] neg_lo:[0,1] neg_hi:[0,1]
	v_pk_add_f32 v[116:117], v[116:117], v[120:121] neg_lo:[0,1] neg_hi:[0,1]
	v_pk_add_f32 v[112:113], v[110:111], v[114:115] op_sel:[0,1] op_sel_hi:[1,0] neg_hi:[0,1]
	v_pk_add_f32 v[120:121], v[118:119], v[122:123] op_sel:[0,1] op_sel_hi:[1,0] neg_hi:[0,1]
	v_pk_add_f32 v[110:111], v[110:111], v[114:115] op_sel:[0,1] op_sel_hi:[1,0] neg_lo:[0,1]
	v_pk_add_f32 v[118:119], v[118:119], v[122:123] op_sel:[0,1] op_sel_hi:[1,0] neg_lo:[0,1]
	v_pk_mul_f32 v[124:125], v[108:109], v[246:247] op_sel:[1,1] op_sel_hi:[1,0]
	v_pk_mul_f32 v[128:129], v[116:117], v[246:247] op_sel:[1,1] op_sel_hi:[1,0]
	v_pk_mul_f32 v[126:127], v[112:113], v[244:245] op_sel:[1,1] op_sel_hi:[1,0]
	v_pk_mul_f32 v[130:131], v[120:121], v[244:245] op_sel:[1,1] op_sel_hi:[1,0]
	v_pk_fma_f32 v[78:79], v[108:109], v[246:247], v[124:125] op_sel_hi:[0,1,1] neg_lo:[0,0,1]
	v_pk_fma_f32 v[86:87], v[116:117], v[246:247], v[128:129] op_sel_hi:[0,1,1] neg_lo:[0,0,1]
	v_pk_mul_f32 v[124:125], v[110:111], v[248:249] op_sel:[1,1] op_sel_hi:[1,0]
	v_pk_mul_f32 v[128:129], v[118:119], v[248:249] op_sel:[1,1] op_sel_hi:[1,0]
	v_pk_fma_f32 v[76:77], v[112:113], v[244:245], v[126:127] op_sel_hi:[0,1,1] neg_lo:[0,0,1]
	v_pk_fma_f32 v[84:85], v[120:121], v[244:245], v[130:131] op_sel_hi:[0,1,1] neg_lo:[0,0,1]
	v_pk_fma_f32 v[80:81], v[110:111], v[248:249], v[124:125] op_sel_hi:[0,1,1] neg_lo:[0,0,1]
	v_pk_fma_f32 v[88:89], v[118:119], v[248:249], v[128:129] op_sel_hi:[0,1,1] neg_lo:[0,0,1]
	v_pk_add_f32 v[108:109], v[92:93], v[96:97]
	v_pk_add_f32 v[116:117], v[100:101], v[104:105]
	v_pk_add_f32 v[112:113], v[94:95], v[98:99]
	v_pk_add_f32 v[120:121], v[102:103], v[106:107]
	v_pk_add_f32 v[110:111], v[92:93], v[96:97] neg_lo:[0,1] neg_hi:[0,1]
	v_pk_add_f32 v[118:119], v[100:101], v[104:105] neg_lo:[0,1] neg_hi:[0,1]
	v_pk_add_f32 v[114:115], v[94:95], v[98:99] neg_lo:[0,1] neg_hi:[0,1]
	v_pk_add_f32 v[122:123], v[102:103], v[106:107] neg_lo:[0,1] neg_hi:[0,1]
	v_pk_add_f32 v[92:93], v[108:109], v[112:113]
	v_pk_add_f32 v[100:101], v[116:117], v[120:121]
	v_pk_add_f32 v[108:109], v[108:109], v[112:113] neg_lo:[0,1] neg_hi:[0,1]
	v_pk_add_f32 v[116:117], v[116:117], v[120:121] neg_lo:[0,1] neg_hi:[0,1]
	v_pk_add_f32 v[112:113], v[110:111], v[114:115] op_sel:[0,1] op_sel_hi:[1,0] neg_hi:[0,1]
	v_pk_add_f32 v[120:121], v[118:119], v[122:123] op_sel:[0,1] op_sel_hi:[1,0] neg_hi:[0,1]
	v_pk_add_f32 v[110:111], v[110:111], v[114:115] op_sel:[0,1] op_sel_hi:[1,0] neg_lo:[0,1]
	v_pk_add_f32 v[118:119], v[118:119], v[122:123] op_sel:[0,1] op_sel_hi:[1,0] neg_lo:[0,1]
	v_pk_mul_f32 v[124:125], v[108:109], v[246:247] op_sel:[1,1] op_sel_hi:[1,0]
	v_pk_mul_f32 v[128:129], v[116:117], v[246:247] op_sel:[1,1] op_sel_hi:[1,0]
	v_pk_mul_f32 v[126:127], v[112:113], v[244:245] op_sel:[1,1] op_sel_hi:[1,0]
	v_pk_mul_f32 v[130:131], v[120:121], v[244:245] op_sel:[1,1] op_sel_hi:[1,0]
	v_pk_fma_f32 v[96:97], v[108:109], v[246:247], v[124:125] op_sel_hi:[0,1,1] neg_lo:[0,0,1]
	v_pk_fma_f32 v[104:105], v[116:117], v[246:247], v[128:129] op_sel_hi:[0,1,1] neg_lo:[0,0,1]
	v_pk_mul_f32 v[124:125], v[110:111], v[248:249] op_sel:[1,1] op_sel_hi:[1,0]
	v_pk_mul_f32 v[128:129], v[118:119], v[248:249] op_sel:[1,1] op_sel_hi:[1,0]
	v_pk_fma_f32 v[94:95], v[112:113], v[244:245], v[126:127] op_sel_hi:[0,1,1] neg_lo:[0,0,1]
	v_pk_fma_f32 v[102:103], v[120:121], v[244:245], v[130:131] op_sel_hi:[0,1,1] neg_lo:[0,0,1]
	v_pk_fma_f32 v[98:99], v[110:111], v[248:249], v[124:125] op_sel_hi:[0,1,1] neg_lo:[0,0,1]
	v_pk_fma_f32 v[106:107], v[118:119], v[248:249], v[128:129] op_sel_hi:[0,1,1] neg_lo:[0,0,1]
	s_nop 0
	ds_write2_b64 v73, v[74:75], v[76:77] offset1:16
	ds_write2_b64 v73, v[78:79], v[80:81] offset0:32 offset1:48
	ds_write2_b64 v73, v[82:83], v[84:85] offset0:64 offset1:80
	ds_write2_b64 v73, v[86:87], v[88:89] offset0:96 offset1:112
	ds_write2_b64 v73, v[92:93], v[94:95] offset0:128 offset1:144
	ds_write2_b64 v73, v[96:97], v[98:99] offset0:160 offset1:176
	ds_write2_b64 v73, v[100:101], v[102:103] offset0:192 offset1:208
	ds_write2_b64 v73, v[104:105], v[106:107] offset0:224 offset1:240
	v_add_u32_e32 v73, 0x200, v72
	v_mov_b32_e32 v72, v73
	s_andn2_b64 exec, exec, s[8:9]
	s_cbranch_execnz .LBB0_1493

; DI float2 twid(float r) { return float2{__builtin_amdgcn_cosf(r), -__builtin_amdgcn_sinf(r)}; }
; DI void bfly_fwd(float2 a0, float2 a1, float2 a2, float2 a3, float r, float2& o0, float2& o1, float2& o2, float2& o3) {
;   float2 t0 = {a0.x + a2.x, a0.y + a2.y}, t1 = {a0.x - a2.x, a0.y - a2.y}, t2 = {a1.x + a3.x, a1.y + a3.y}, t3 = {a1.x - a3.x, a1.y - a3.y};
;   float2 b0 = {t0.x + t2.x, t0.y + t2.y}, b2 = {t0.x - t2.x, t0.y - t2.y}, b1 = {t1.x + t3.y, t1.y - t3.x}, b3 = {t1.x - t3.y, t1.y + t3.x};
;   float2 w1 = twid(r), w2 = cmul(w1, w1), w3 = cmul(w2, w1);
;   o0 = b0; o1 = cmul(b1, w1); o2 = cmul(b2, w2); o3 = cmul(b3, w3);
;   const int lq2 = lq1 - 2, Q1 = 1 << lq1, Q2 = 1 << lq2; const float invM1 = 1.f / (float)(4 << lq1), invM2 = 1.f / (float)(4 << lq2);
;   for (int gg = tid; gg < NBT * (N / 16); gg += NTHR) { const int g = gg & (N / 16 - 1); float2* z = z0 + (gg / (N / 16)) * N; const int jp = g & (Q2 - 1), base = ((g >> lq2) << (lq2 + 4)) + jp; float2 x[4][4];
; #pragma unroll
;     for (int q1 = 0; q1 < 4; ++q1)
; #pragma unroll
;       for (int q2 = 0; q2 < 4; ++q2) x[q1][q2] = z[base + q1 * Q1 + q2 * Q2];
; #pragma unroll
;     for (int q2 = 0; q2 < 4; ++q2) bfly_fwd(x[0][q2], x[1][q2], x[2][q2], x[3][q2], (float)(jp + q2 * Q2) * invM1, x[0][q2], x[1][q2], x[2][q2], x[3][q2]);
; #pragma unroll
;     for (int q1 = 0; q1 < 4; ++q1) bfly_fwd(x[q1][0], x[q1][1], x[q1][2], x[q1][3], (float)jp * invM2, x[q1][0], x[q1][1], x[q1][2], x[q1][3]);
.LBB0_1516:
	s_or_b64 exec, exec, s[0:1]
	s_add_i32 s0, 16, 0x20000
	v_mov_b32_e32 v0, s0
	v_readlane_b32 s0, v240, 48
	s_or_b32 s96, s21, s75
	s_waitcnt lgkmcnt(0)
	s_barrier
	ds_read_b128 v[6:9], v0
	v_mov_b32_e32 v0, s0
	s_lshl_b64 s[0:1], s[96:97], 2
	s_add_u32 s0, s18, s0
	s_addc_u32 s1, s19, s1
	ds_read_b128 v[2:5], v0
	global_load_dword v0, v1, s[0:1]
	s_movk_i32 s0, 0x400
	v_cmp_gt_i32_e32 vcc, s0, v10
	v_lshlrev_b32_e32 v11, 4, v10
	s_and_saveexec_b64 s[0:1], vcc
	s_cbranch_execz .LBB0_1519
	s_movk_i32 s10, 0x100
	v_cvt_f32_ubyte0_e32 v13, v10
	v_or_b32_sdwa v15, v10, s10 dst_sel:DWORD dst_unused:UNUSED_PAD src0_sel:BYTE_0 src1_sel:DWORD
	v_mul_f32_e32 v14, 0x39800000, v13
	v_cvt_f32_u32_e32 v15, v15
	v_sin_f32_e32 v12, v14
	v_cos_f32_e32 v14, v14
	s_movk_i32 s10, 0x200
	v_mul_f32_e32 v15, 0x39800000, v15
	v_sin_f32_e32 v22, v15
	v_mul_f32_e64 v17, v14, -v12
	v_mul_f32_e32 v16, v12, v12
	v_add_f32_e32 v18, v17, v17
	v_cos_f32_e32 v24, v15
	v_or_b32_sdwa v17, v10, s10 dst_sel:DWORD dst_unused:UNUSED_PAD src0_sel:BYTE_0 src1_sel:DWORD
	v_fma_f32 v16, v14, v14, -v16
	v_cvt_f32_u32_e32 v17, v17
	v_mul_f32_e32 v15, v12, v16
	v_fma_f32 v26, v14, v18, -v15
	v_mul_f32_e32 v15, v22, v22
	v_fma_f32 v28, v24, v24, -v15
	v_mul_f32_e64 v15, v24, -v22
	v_add_f32_e32 v30, v15, v15
	v_mul_f32_e32 v15, 0x39800000, v17
	v_sin_f32_e32 v34, v15
	s_movk_i32 s10, 0x300
	v_cos_f32_e32 v36, v15
	v_or_b32_sdwa v17, v10, s10 dst_sel:DWORD dst_unused:UNUSED_PAD src0_sel:BYTE_0 src1_sel:DWORD
	v_cvt_f32_u32_e32 v17, v17
	v_mul_f32_e32 v15, v22, v28
	v_fma_f32 v38, v24, v30, -v15
	v_mul_f32_e32 v15, v34, v34
	v_fma_f32 v40, v36, v36, -v15
	v_mul_f32_e64 v15, v36, -v34
	v_add_f32_e32 v42, v15, v15
	v_mul_f32_e32 v15, 0x39800000, v17
	v_sin_f32_e32 v46, v15
	v_cos_f32_e32 v48, v15
	v_mul_f32_e32 v13, 0x3a800000, v13
	v_mul_f32_e32 v15, v34, v40
	v_sin_f32_e32 v58, v13
	v_fma_f32 v50, v36, v42, -v15
	v_mul_f32_e32 v15, v46, v46
	v_cos_f32_e32 v60, v13
	v_fma_f32 v52, v48, v48, -v15
	v_mul_f32_e64 v15, v48, -v46
	v_add_f32_e32 v54, v15, v15
	v_mul_f32_e32 v13, v46, v52
	v_fma_f32 v62, v48, v54, -v13
	v_mul_f32_e32 v13, v58, v58
	v_fma_f32 v64, v60, v60, -v13
	v_mul_f32_e64 v13, v60, -v58
	v_add_f32_e32 v66, v13, v13
	v_mul_f32_e32 v20, v12, v18
	v_mul_f32_e32 v32, v22, v30
	v_mul_f32_e32 v44, v34, v42
	v_mul_f32_e32 v56, v46, v54
	v_mul_f32_e32 v68, v58, v66
	v_mul_f32_e32 v13, v58, v64
	v_fmac_f32_e32 v20, v14, v16
	v_fmac_f32_e32 v32, v24, v28
	v_fmac_f32_e32 v44, v36, v40
	v_fmac_f32_e32 v56, v48, v52
	v_fmac_f32_e32 v68, v60, v64
	v_fma_f32 v70, v60, v66, -v13
	v_mov_b32_e32 v61, v60
	v_mov_b32_e32 v59, v58
	v_mov_b32_e32 v65, v64
	v_mov_b32_e32 v67, v66
	v_mov_b32_e32 v69, v68
	v_mov_b32_e32 v71, v70
	v_mov_b32_e32 v15, v14
	v_mov_b32_e32 v13, v12
	v_mov_b32_e32 v37, v36
	v_mov_b32_e32 v35, v34
	v_mov_b32_e32 v25, v24
	v_mov_b32_e32 v23, v22
	v_mov_b32_e32 v49, v48
	v_mov_b32_e32 v47, v46
	v_mov_b32_e32 v17, v16
	v_mov_b32_e32 v41, v40
	v_mov_b32_e32 v29, v28
	v_mov_b32_e32 v53, v52
	v_mov_b32_e32 v21, v20
	v_mov_b32_e32 v27, v26
	v_mov_b32_e32 v45, v44
	v_mov_b32_e32 v51, v50
	v_mov_b32_e32 v33, v32
	v_mov_b32_e32 v39, v38
	v_mov_b32_e32 v57, v56
	v_mov_b32_e32 v63, v62
	v_mov_b32_e32 v19, v18
	v_mov_b32_e32 v31, v30
	v_mov_b32_e32 v43, v42
	v_mov_b32_e32 v55, v54
	v_lshlrev_b32_e32 v72, 4, v10
	s_mov_b64 s[12:13], 0
	v_mov_b32_e32 v73, v10
	v_and_b32_e32 v241, 0xff, v73
	v_add_u32_e32 v250, 0x0, v241
	v_cvt_f32_u32_e32 v250, v250
	v_mul_f32_e32 v250, 0x39800000, v250
	v_cos_f32_e32 v218, v250
	v_sin_f32_e32 v219, v250
	s_nop 1
	v_xor_b32_e32 v219, 0x80000000, v219
	s_nop 0
	v_pk_mul_f32 v[128:129], v[218:219], v[218:219] op_sel:[1,1] op_sel_hi:[1,0]
	s_nop 0
	v_pk_fma_f32 v[220:221], v[218:219], v[218:219], v[128:129] op_sel_hi:[0,1,1] neg_lo:[0,0,1]
	s_nop 0
	v_pk_mul_f32 v[128:129], v[220:221], v[218:219] op_sel:[1,1] op_sel_hi:[1,0]
	s_nop 0
	v_pk_fma_f32 v[222:223], v[220:221], v[218:219], v[128:129] op_sel_hi:[0,1,1] neg_lo:[0,0,1]
	s_nop 0
	v_add_u32_e32 v250, 0x100, v241
	v_cvt_f32_u32_e32 v250, v250
	v_mul_f32_e32 v250, 0x39800000, v250
	v_cos_f32_e32 v224, v250
	v_sin_f32_e32 v225, v250
	s_nop 1
	v_xor_b32_e32 v225, 0x80000000, v225
	s_nop 0
	v_pk_mul_f32 v[128:129], v[224:225], v[224:225] op_sel:[1,1] op_sel_hi:[1,0]
	s_nop 0
	v_pk_fma_f32 v[226:227], v[224:225], v[224:225], v[128:129] op_sel_hi:[0,1,1] neg_lo:[0,0,1]
	s_nop 0
	v_pk_mul_f32 v[128:129], v[226:227], v[224:225] op_sel:[1,1] op_sel_hi:[1,0]
	s_nop 0
	v_pk_fma_f32 v[228:229], v[226:227], v[224:225], v[128:129] op_sel_hi:[0,1,1] neg_lo:[0,0,1]
	s_nop 0
	v_add_u32_e32 v250, 0x200, v241
	v_cvt_f32_u32_e32 v250, v250
	v_mul_f32_e32 v250, 0x39800000, v250
	v_cos_f32_e32 v230, v250
	v_sin_f32_e32 v231, v250
	s_nop 1
	v_xor_b32_e32 v231, 0x80000000, v231
	s_nop 0
	v_pk_mul_f32 v[128:129], v[230:231], v[230:231] op_sel:[1,1] op_sel_hi:[1,0]
	s_nop 0
	v_pk_fma_f32 v[232:233], v[230:231], v[230:231], v[128:129] op_sel_hi:[0,1,1] neg_lo:[0,0,1]
	s_nop 0
	v_pk_mul_f32 v[128:129], v[232:233], v[230:231] op_sel:[1,1] op_sel_hi:[1,0]
	s_nop 0
	v_pk_fma_f32 v[234:235], v[232:233], v[230:231], v[128:129] op_sel_hi:[0,1,1] neg_lo:[0,0,1]
	s_nop 0
	v_add_u32_e32 v250, 0x300, v241
	v_cvt_f32_u32_e32 v250, v250
	v_mul_f32_e32 v250, 0x39800000, v250
	v_cos_f32_e32 v236, v250
	v_sin_f32_e32 v237, v250
	s_nop 1
	v_xor_b32_e32 v237, 0x80000000, v237
	s_nop 0
	v_pk_mul_f32 v[128:129], v[236:237], v[236:237] op_sel:[1,1] op_sel_hi:[1,0]
	s_nop 0
	v_pk_fma_f32 v[238:239], v[236:237], v[236:237], v[128:129] op_sel_hi:[0,1,1] neg_lo:[0,0,1]
	s_nop 0
	v_pk_mul_f32 v[128:129], v[238:239], v[236:237] op_sel:[1,1] op_sel_hi:[1,0]
	s_nop 0
	v_pk_fma_f32 v[242:243], v[238:239], v[236:237], v[128:129] op_sel_hi:[0,1,1] neg_lo:[0,0,1]
	s_nop 0
	v_cvt_f32_u32_e32 v250, v241
	v_mul_f32_e32 v250, 0x3a800000, v250
	v_cos_f32_e32 v244, v250
	v_sin_f32_e32 v245, v250
	s_nop 1
	v_xor_b32_e32 v245, 0x80000000, v245
	s_nop 0
	v_pk_mul_f32 v[128:129], v[244:245], v[244:245] op_sel:[1,1] op_sel_hi:[1,0]
	s_nop 0
	v_pk_fma_f32 v[246:247], v[244:245], v[244:245], v[128:129] op_sel_hi:[0,1,1] neg_lo:[0,0,1]
	s_nop 0
	v_pk_mul_f32 v[128:129], v[246:247], v[244:245] op_sel:[1,1] op_sel_hi:[1,0]
	s_nop 0
	v_pk_fma_f32 v[248:249], v[246:247], v[244:245], v[128:129] op_sel_hi:[0,1,1] neg_lo:[0,0,1]
	s_nop 0
; DI float2 twid(float r) { return float2{__builtin_amdgcn_cosf(r), -__builtin_amdgcn_sinf(r)}; }
; DI void bfly_fwd(float2 a0, float2 a1, float2 a2, float2 a3, float r, float2& o0, float2& o1, float2& o2, float2& o3) {
;   float2 t0 = {a0.x + a2.x, a0.y + a2.y}, t1 = {a0.x - a2.x, a0.y - a2.y}, t2 = {a1.x + a3.x, a1.y + a3.y}, t3 = {a1.x - a3.x, a1.y - a3.y};
;   float2 b0 = {t0.x + t2.x, t0.y + t2.y}, b2 = {t0.x - t2.x, t0.y - t2.y}, b1 = {t1.x + t3.y, t1.y - t3.x}, b3 = {t1.x - t3.y, t1.y + t3.x};
;   float2 w1 = twid(r), w2 = cmul(w1, w1), w3 = cmul(w2, w1);
;   o0 = b0; o1 = cmul(b1, w1); o2 = cmul(b2, w2); o3 = cmul(b3, w3);
; }
;     ...
;   for (int gg = tid; gg < NBT * (N / 16); gg += NTHR) { const int g = gg & (N / 16 - 1); float2* z = z0 + (gg / (N / 16)) * N; const int jp = g & (Q2 - 1), base = ((g >> lq2) << (lq2 + 4)) + jp; float2 x[4][4];
; #pragma unroll
;     for (int q1 = 0; q1 < 4; ++q1)
; #pragma unroll
;       for (int q2 = 0; q2 < 4; ++q2) x[q1][q2] = z[base + q1 * Q1 + q2 * Q2];
; #pragma unroll
;     for (int q2 = 0; q2 < 4; ++q2) bfly_fwd(x[0][q2], x[1][q2], x[2][q2], x[3][q2], (float)(jp + q2 * Q2) * invM1, x[0][q2], x[1][q2], x[2][q2], x[3][q2]);
; #pragma unroll
;     for (int q1 = 0; q1 < 4; ++q1) bfly_fwd(x[q1][0], x[q1][1], x[q1][2], x[q1][3], (float)jp * invM2, x[q1][0], x[q1][1], x[q1][2], x[q1][3]);
.LBB0_1518:
	v_ashrrev_i32_e32 v74, 31, v73
	v_lshrrev_b32_e32 v74, 22, v74
	v_add_lshl_u32 v74, v73, v74, 7
	v_and_b32_e32 v74, 0xfffe0000, v74
	v_and_b32_e32 v75, 0x3000, v72
	v_add_u32_e32 v74, 16, v74
	v_lshlrev_b32_e32 v75, 3, v75
	v_lshlrev_b32_sdwa v76, v151, v10 dst_sel:DWORD dst_unused:UNUSED_PAD src0_sel:DWORD src1_sel:BYTE_0
	v_add3_u32 v90, v74, v75, v76
	ds_read2st64_b64 v[78:81], v90 offset1:4
	ds_read2st64_b64 v[82:85], v90 offset0:8 offset1:12
	ds_read2st64_b64 v[86:89], v90 offset0:16 offset1:20
	ds_read2st64_b64 v[92:95], v90 offset0:24 offset1:28
	ds_read2st64_b64 v[96:99], v90 offset0:32 offset1:36
	ds_read2st64_b64 v[100:103], v90 offset0:40 offset1:44
	ds_read2st64_b64 v[104:107], v90 offset0:48 offset1:52
	ds_read2st64_b64 v[108:111], v90 offset0:56 offset1:60
	v_cmp_lt_i32_e64 s[10:11], s5, v73
	s_or_b64 s[12:13], s[10:11], s[12:13]
	s_waitcnt lgkmcnt(0)
	v_pk_add_f32 v[112:113], v[78:79], v[96:97]
	v_pk_add_f32 v[120:121], v[80:81], v[98:99]
	v_pk_add_f32 v[116:117], v[86:87], v[104:105]
	v_pk_add_f32 v[124:125], v[88:89], v[106:107]
	v_pk_add_f32 v[114:115], v[78:79], v[96:97] neg_lo:[0,1] neg_hi:[0,1]
	v_pk_add_f32 v[122:123], v[80:81], v[98:99] neg_lo:[0,1] neg_hi:[0,1]
	v_pk_add_f32 v[118:119], v[86:87], v[104:105] neg_lo:[0,1] neg_hi:[0,1]
	v_pk_add_f32 v[126:127], v[88:89], v[106:107] neg_lo:[0,1] neg_hi:[0,1]
	v_pk_add_f32 v[78:79], v[112:113], v[116:117]
	v_pk_add_f32 v[80:81], v[120:121], v[124:125]
	v_pk_add_f32 v[112:113], v[112:113], v[116:117] neg_lo:[0,1] neg_hi:[0,1]
	v_pk_add_f32 v[120:121], v[120:121], v[124:125] neg_lo:[0,1] neg_hi:[0,1]
	v_pk_add_f32 v[116:117], v[114:115], v[118:119] op_sel:[0,1] op_sel_hi:[1,0] neg_hi:[0,1]
	v_pk_add_f32 v[124:125], v[122:123], v[126:127] op_sel:[0,1] op_sel_hi:[1,0] neg_hi:[0,1]
	v_pk_add_f32 v[114:115], v[114:115], v[118:119] op_sel:[0,1] op_sel_hi:[1,0] neg_lo:[0,1]
	v_pk_add_f32 v[122:123], v[122:123], v[126:127] op_sel:[0,1] op_sel_hi:[1,0] neg_lo:[0,1]
	v_pk_mul_f32 v[128:129], v[112:113], v[220:221] op_sel:[1,1] op_sel_hi:[1,0]
	v_pk_mul_f32 v[132:133], v[120:121], v[226:227] op_sel:[1,1] op_sel_hi:[1,0]
	v_pk_mul_f32 v[130:131], v[116:117], v[218:219] op_sel:[1,1] op_sel_hi:[1,0]
	v_pk_mul_f32 v[134:135], v[124:125], v[224:225] op_sel:[1,1] op_sel_hi:[1,0]
	v_pk_fma_f32 v[96:97], v[112:113], v[220:221], v[128:129] op_sel_hi:[0,1,1] neg_lo:[0,0,1]
	v_pk_fma_f32 v[98:99], v[120:121], v[226:227], v[132:133] op_sel_hi:[0,1,1] neg_lo:[0,0,1]
	v_pk_mul_f32 v[128:129], v[114:115], v[222:223] op_sel:[1,1] op_sel_hi:[1,0]
	v_pk_mul_f32 v[132:133], v[122:123], v[228:229] op_sel:[1,1] op_sel_hi:[1,0]
	v_pk_fma_f32 v[86:87], v[116:117], v[218:219], v[130:131] op_sel_hi:[0,1,1] neg_lo:[0,0,1]
	v_pk_fma_f32 v[88:89], v[124:125], v[224:225], v[134:135] op_sel_hi:[0,1,1] neg_lo:[0,0,1]
	v_pk_fma_f32 v[104:105], v[114:115], v[222:223], v[128:129] op_sel_hi:[0,1,1] neg_lo:[0,0,1]
	v_pk_fma_f32 v[106:107], v[122:123], v[228:229], v[132:133] op_sel_hi:[0,1,1] neg_lo:[0,0,1]
	v_pk_add_f32 v[112:113], v[82:83], v[100:101]
	v_pk_add_f32 v[120:121], v[84:85], v[102:103]
	v_pk_add_f32 v[116:117], v[92:93], v[108:109]
	v_pk_add_f32 v[124:125], v[94:95], v[110:111]
	v_pk_add_f32 v[114:115], v[82:83], v[100:101] neg_lo:[0,1] neg_hi:[0,1]
	v_pk_add_f32 v[122:123], v[84:85], v[102:103] neg_lo:[0,1] neg_hi:[0,1]
	v_pk_add_f32 v[118:119], v[92:93], v[108:109] neg_lo:[0,1] neg_hi:[0,1]
	v_pk_add_f32 v[126:127], v[94:95], v[110:111] neg_lo:[0,1] neg_hi:[0,1]
	v_pk_add_f32 v[82:83], v[112:113], v[116:117]
	v_pk_add_f32 v[84:85], v[120:121], v[124:125]
	v_pk_add_f32 v[112:113], v[112:113], v[116:117] neg_lo:[0,1] neg_hi:[0,1]
	v_pk_add_f32 v[120:121], v[120:121], v[124:125] neg_lo:[0,1] neg_hi:[0,1]
	v_pk_add_f32 v[116:117], v[114:115], v[118:119] op_sel:[0,1] op_sel_hi:[1,0] neg_hi:[0,1]
	v_pk_add_f32 v[124:125], v[122:123], v[126:127] op_sel:[0,1] op_sel_hi:[1,0] neg_hi:[0,1]
	v_pk_add_f32 v[114:115], v[114:115], v[118:119] op_sel:[0,1] op_sel_hi:[1,0] neg_lo:[0,1]
	v_pk_add_f32 v[122:123], v[122:123], v[126:127] op_sel:[0,1] op_sel_hi:[1,0] neg_lo:[0,1]
	v_pk_mul_f32 v[128:129], v[112:113], v[232:233] op_sel:[1,1] op_sel_hi:[1,0]
	v_pk_mul_f32 v[132:133], v[120:121], v[238:239] op_sel:[1,1] op_sel_hi:[1,0]
	v_pk_mul_f32 v[130:131], v[116:117], v[230:231] op_sel:[1,1] op_sel_hi:[1,0]
	v_pk_mul_f32 v[134:135], v[124:125], v[236:237] op_sel:[1,1] op_sel_hi:[1,0]
	v_pk_fma_f32 v[100:101], v[112:113], v[232:233], v[128:129] op_sel_hi:[0,1,1] neg_lo:[0,0,1]
	v_pk_fma_f32 v[102:103], v[120:121], v[238:239], v[132:133] op_sel_hi:[0,1,1] neg_lo:[0,0,1]
	v_pk_mul_f32 v[128:129], v[114:115], v[234:235] op_sel:[1,1] op_sel_hi:[1,0]
	v_pk_mul_f32 v[132:133], v[122:123], v[242:243] op_sel:[1,1] op_sel_hi:[1,0]
	v_pk_fma_f32 v[92:93], v[116:117], v[230:231], v[130:131] op_sel_hi:[0,1,1] neg_lo:[0,0,1]
	v_pk_fma_f32 v[94:95], v[124:125], v[236:237], v[134:135] op_sel_hi:[0,1,1] neg_lo:[0,0,1]
	v_pk_fma_f32 v[108:109], v[114:115], v[234:235], v[128:129] op_sel_hi:[0,1,1] neg_lo:[0,0,1]
	v_pk_fma_f32 v[110:111], v[122:123], v[242:243], v[132:133] op_sel_hi:[0,1,1] neg_lo:[0,0,1]
	v_pk_add_f32 v[112:113], v[78:79], v[82:83]
	v_pk_add_f32 v[120:121], v[86:87], v[92:93]
	v_pk_add_f32 v[116:117], v[80:81], v[84:85]
	v_pk_add_f32 v[124:125], v[88:89], v[94:95]
	v_pk_add_f32 v[114:115], v[78:79], v[82:83] neg_lo:[0,1] neg_hi:[0,1]
	v_pk_add_f32 v[122:123], v[86:87], v[92:93] neg_lo:[0,1] neg_hi:[0,1]
	v_pk_add_f32 v[118:119], v[80:81], v[84:85] neg_lo:[0,1] neg_hi:[0,1]
	v_pk_add_f32 v[126:127], v[88:89], v[94:95] neg_lo:[0,1] neg_hi:[0,1]
	v_pk_add_f32 v[78:79], v[112:113], v[116:117]
; DI float2 twid(float r) { return float2{__builtin_amdgcn_cosf(r), -__builtin_amdgcn_sinf(r)}; }
; DI void bfly_fwd(float2 a0, float2 a1, float2 a2, float2 a3, float r, float2& o0, float2& o1, float2& o2, float2& o3) {
;   float2 t0 = {a0.x + a2.x, a0.y + a2.y}, t1 = {a0.x - a2.x, a0.y - a2.y}, t2 = {a1.x + a3.x, a1.y + a3.y}, t3 = {a1.x - a3.x, a1.y - a3.y};
;   float2 b0 = {t0.x + t2.x, t0.y + t2.y}, b2 = {t0.x - t2.x, t0.y - t2.y}, b1 = {t1.x + t3.y, t1.y - t3.x}, b3 = {t1.x - t3.y, t1.y + t3.x};
;   float2 w1 = twid(r), w2 = cmul(w1, w1), w3 = cmul(w2, w1);
;   o0 = b0; o1 = cmul(b1, w1); o2 = cmul(b2, w2); o3 = cmul(b3, w3);
;     ...
;     for (int q1 = 0; q1 < 4; ++q1) bfly_fwd(x[q1][0], x[q1][1], x[q1][2], x[q1][3], (float)jp * invM2, x[q1][0], x[q1][1], x[q1][2], x[q1][3]);
; #pragma unroll
;     for (int q1 = 0; q1 < 4; ++q1)
; #pragma unroll
;       for (int q2 = 0; q2 < 4; ++q2) z[base + q1 * Q1 + q2 * Q2] = x[q1][q2]; }
	v_pk_add_f32 v[86:87], v[120:121], v[124:125]
	v_pk_add_f32 v[112:113], v[112:113], v[116:117] neg_lo:[0,1] neg_hi:[0,1]
	v_pk_add_f32 v[120:121], v[120:121], v[124:125] neg_lo:[0,1] neg_hi:[0,1]
	v_pk_add_f32 v[116:117], v[114:115], v[118:119] op_sel:[0,1] op_sel_hi:[1,0] neg_hi:[0,1]
	v_pk_add_f32 v[124:125], v[122:123], v[126:127] op_sel:[0,1] op_sel_hi:[1,0] neg_hi:[0,1]
	v_pk_add_f32 v[114:115], v[114:115], v[118:119] op_sel:[0,1] op_sel_hi:[1,0] neg_lo:[0,1]
	v_pk_add_f32 v[122:123], v[122:123], v[126:127] op_sel:[0,1] op_sel_hi:[1,0] neg_lo:[0,1]
	v_pk_mul_f32 v[128:129], v[112:113], v[246:247] op_sel:[1,1] op_sel_hi:[1,0]
	v_pk_mul_f32 v[132:133], v[120:121], v[246:247] op_sel:[1,1] op_sel_hi:[1,0]
	v_pk_mul_f32 v[130:131], v[116:117], v[244:245] op_sel:[1,1] op_sel_hi:[1,0]
	v_pk_mul_f32 v[134:135], v[124:125], v[244:245] op_sel:[1,1] op_sel_hi:[1,0]
	v_pk_fma_f32 v[82:83], v[112:113], v[246:247], v[128:129] op_sel_hi:[0,1,1] neg_lo:[0,0,1]
	v_pk_fma_f32 v[92:93], v[120:121], v[246:247], v[132:133] op_sel_hi:[0,1,1] neg_lo:[0,0,1]
	v_pk_mul_f32 v[128:129], v[114:115], v[248:249] op_sel:[1,1] op_sel_hi:[1,0]
	v_pk_mul_f32 v[132:133], v[122:123], v[248:249] op_sel:[1,1] op_sel_hi:[1,0]
	v_pk_fma_f32 v[80:81], v[116:117], v[244:245], v[130:131] op_sel_hi:[0,1,1] neg_lo:[0,0,1]
	v_pk_fma_f32 v[88:89], v[124:125], v[244:245], v[134:135] op_sel_hi:[0,1,1] neg_lo:[0,0,1]
	v_pk_fma_f32 v[84:85], v[114:115], v[248:249], v[128:129] op_sel_hi:[0,1,1] neg_lo:[0,0,1]
	v_pk_fma_f32 v[94:95], v[122:123], v[248:249], v[132:133] op_sel_hi:[0,1,1] neg_lo:[0,0,1]
	v_pk_add_f32 v[112:113], v[96:97], v[100:101]
	v_pk_add_f32 v[120:121], v[104:105], v[108:109]
	v_pk_add_f32 v[116:117], v[98:99], v[102:103]
	v_pk_add_f32 v[124:125], v[106:107], v[110:111]
	v_pk_add_f32 v[114:115], v[96:97], v[100:101] neg_lo:[0,1] neg_hi:[0,1]
	v_pk_add_f32 v[122:123], v[104:105], v[108:109] neg_lo:[0,1] neg_hi:[0,1]
	v_pk_add_f32 v[118:119], v[98:99], v[102:103] neg_lo:[0,1] neg_hi:[0,1]
	v_pk_add_f32 v[126:127], v[106:107], v[110:111] neg_lo:[0,1] neg_hi:[0,1]
	v_pk_add_f32 v[96:97], v[112:113], v[116:117]
	v_pk_add_f32 v[104:105], v[120:121], v[124:125]
	v_pk_add_f32 v[112:113], v[112:113], v[116:117] neg_lo:[0,1] neg_hi:[0,1]
	v_pk_add_f32 v[120:121], v[120:121], v[124:125] neg_lo:[0,1] neg_hi:[0,1]
	v_pk_add_f32 v[116:117], v[114:115], v[118:119] op_sel:[0,1] op_sel_hi:[1,0] neg_hi:[0,1]
	v_pk_add_f32 v[124:125], v[122:123], v[126:127] op_sel:[0,1] op_sel_hi:[1,0] neg_hi:[0,1]
	v_pk_add_f32 v[114:115], v[114:115], v[118:119] op_sel:[0,1] op_sel_hi:[1,0] neg_lo:[0,1]
	v_pk_add_f32 v[122:123], v[122:123], v[126:127] op_sel:[0,1] op_sel_hi:[1,0] neg_lo:[0,1]
	v_pk_mul_f32 v[128:129], v[112:113], v[246:247] op_sel:[1,1] op_sel_hi:[1,0]
	v_pk_mul_f32 v[132:133], v[120:121], v[246:247] op_sel:[1,1] op_sel_hi:[1,0]
	v_pk_mul_f32 v[130:131], v[116:117], v[244:245] op_sel:[1,1] op_sel_hi:[1,0]
	v_pk_mul_f32 v[134:135], v[124:125], v[244:245] op_sel:[1,1] op_sel_hi:[1,0]
	v_pk_fma_f32 v[100:101], v[112:113], v[246:247], v[128:129] op_sel_hi:[0,1,1] neg_lo:[0,0,1]
	v_pk_fma_f32 v[108:109], v[120:121], v[246:247], v[132:133] op_sel_hi:[0,1,1] neg_lo:[0,0,1]
	v_pk_mul_f32 v[128:129], v[114:115], v[248:249] op_sel:[1,1] op_sel_hi:[1,0]
	v_pk_mul_f32 v[132:133], v[122:123], v[248:249] op_sel:[1,1] op_sel_hi:[1,0]
	v_pk_fma_f32 v[98:99], v[116:117], v[244:245], v[130:131] op_sel_hi:[0,1,1] neg_lo:[0,0,1]
	v_pk_fma_f32 v[106:107], v[124:125], v[244:245], v[134:135] op_sel_hi:[0,1,1] neg_lo:[0,0,1]
	v_pk_fma_f32 v[102:103], v[114:115], v[248:249], v[128:129] op_sel_hi:[0,1,1] neg_lo:[0,0,1]
	v_pk_fma_f32 v[110:111], v[122:123], v[248:249], v[132:133] op_sel_hi:[0,1,1] neg_lo:[0,0,1]
	s_nop 0
	ds_write2st64_b64 v90, v[78:79], v[80:81] offset1:4
	ds_write2st64_b64 v90, v[82:83], v[84:85] offset0:8 offset1:12
	ds_write2st64_b64 v90, v[86:87], v[88:89] offset0:16 offset1:20
	ds_write2st64_b64 v90, v[92:93], v[94:95] offset0:24 offset1:28
	ds_write2st64_b64 v90, v[96:97], v[98:99] offset0:32 offset1:36
	ds_write2st64_b64 v90, v[100:101], v[102:103] offset0:40 offset1:44
	ds_write2st64_b64 v90, v[104:105], v[106:107] offset0:48 offset1:52
	ds_write2st64_b64 v90, v[108:109], v[110:111] offset0:56 offset1:60
	v_add_u32_e32 v72, 0x2000, v72
	v_add_u32_e32 v74, 0x200, v73
	v_mov_b32_e32 v73, v74
	s_andn2_b64 exec, exec, s[12:13]
	s_cbranch_execnz .LBB0_1518
; DI float2 twid(float r) { return float2{__builtin_amdgcn_cosf(r), -__builtin_amdgcn_sinf(r)}; }
; DI void bfly_fwd(float2 a0, float2 a1, float2 a2, float2 a3, float r, float2& o0, float2& o1, float2& o2, float2& o3) {
;   float2 t0 = {a0.x + a2.x, a0.y + a2.y}, t1 = {a0.x - a2.x, a0.y - a2.y}, t2 = {a1.x + a3.x, a1.y + a3.y}, t3 = {a1.x - a3.x, a1.y - a3.y};
;   float2 b0 = {t0.x + t2.x, t0.y + t2.y}, b2 = {t0.x - t2.x, t0.y - t2.y}, b1 = {t1.x + t3.y, t1.y - t3.x}, b3 = {t1.x - t3.y, t1.y + t3.x};
;   float2 w1 = twid(r), w2 = cmul(w1, w1), w3 = cmul(w2, w1);
;   o0 = b0; o1 = cmul(b1, w1); o2 = cmul(b2, w2); o3 = cmul(b3, w3);
;   const int lq2 = lq1 - 2, Q1 = 1 << lq1, Q2 = 1 << lq2; const float invM1 = 1.f / (float)(4 << lq1), invM2 = 1.f / (float)(4 << lq2);
;   for (int gg = tid; gg < NBT * (N / 16); gg += NTHR) { const int g = gg & (N / 16 - 1); float2* z = z0 + (gg / (N / 16)) * N; const int jp = g & (Q2 - 1), base = ((g >> lq2) << (lq2 + 4)) + jp; float2 x[4][4];
; #pragma unroll
;     for (int q1 = 0; q1 < 4; ++q1)
; #pragma unroll
;       for (int q2 = 0; q2 < 4; ++q2) x[q1][q2] = z[base + q1 * Q1 + q2 * Q2];
; #pragma unroll
;     for (int q2 = 0; q2 < 4; ++q2) bfly_fwd(x[0][q2], x[1][q2], x[2][q2], x[3][q2], (float)(jp + q2 * Q2) * invM1, x[0][q2], x[1][q2], x[2][q2], x[3][q2]);
; #pragma unroll
;     for (int q1 = 0; q1 < 4; ++q1) bfly_fwd(x[q1][0], x[q1][1], x[q1][2], x[q1][3], (float)jp * invM2, x[q1][0], x[q1][1], x[q1][2], x[q1][3]);
.LBB0_1519:
	s_or_b64 exec, exec, s[0:1]
	s_waitcnt lgkmcnt(0)
	s_barrier
	s_and_saveexec_b64 s[0:1], vcc
	s_cbranch_execz .LBB0_1522
	v_and_b32_e32 v72, 15, v10
	v_cvt_f32_ubyte0_e32 v13, v72
	v_mul_f32_e32 v14, 0x3b800000, v13
	v_sin_f32_e32 v12, v14
	v_cos_f32_e32 v14, v14
	v_mul_f32_e32 v13, 0x3c800000, v13
	v_sin_f32_e32 v58, v13
	v_mul_f32_e32 v15, v12, v12
	v_fma_f32 v16, v14, v14, -v15
	v_or_b32_e32 v15, 16, v72
	v_cvt_f32_ubyte0_e32 v15, v15
	v_mul_f32_e32 v15, 0x3b800000, v15
	v_sin_f32_e32 v22, v15
	v_cos_f32_e32 v24, v15
	v_mul_f32_e64 v17, v14, -v12
	v_add_f32_e32 v18, v17, v17
	v_mul_f32_e32 v15, v12, v16
	v_fma_f32 v26, v14, v18, -v15
	v_mul_f32_e32 v15, v22, v22
	v_fma_f32 v28, v24, v24, -v15
	v_mul_f32_e64 v15, v24, -v22
	v_add_f32_e32 v30, v15, v15
	v_or_b32_e32 v15, 32, v72
	v_cvt_f32_ubyte0_e32 v15, v15
	v_mul_f32_e32 v15, 0x3b800000, v15
	v_sin_f32_e32 v34, v15
	v_cos_f32_e32 v36, v15
	v_mul_f32_e32 v15, v22, v28
	v_fma_f32 v38, v24, v30, -v15
	v_mul_f32_e32 v15, v34, v34
	v_fma_f32 v40, v36, v36, -v15
	v_mul_f32_e64 v15, v36, -v34
	v_add_f32_e32 v42, v15, v15
	v_or_b32_e32 v15, 48, v72
	v_cvt_f32_ubyte0_e32 v15, v15
	v_mul_f32_e32 v15, 0x3b800000, v15
	v_sin_f32_e32 v46, v15
	v_cos_f32_e32 v48, v15
	v_mul_f32_e32 v15, v34, v40
	v_fma_f32 v50, v36, v42, -v15
	v_mul_f32_e32 v15, v46, v46
	v_cos_f32_e32 v60, v13
	v_fma_f32 v52, v48, v48, -v15
	v_mul_f32_e64 v15, v48, -v46
	v_add_f32_e32 v54, v15, v15
	v_mul_f32_e32 v13, v46, v52
	v_fma_f32 v62, v48, v54, -v13
	v_mul_f32_e32 v13, v58, v58
	v_fma_f32 v64, v60, v60, -v13
	v_mul_f32_e64 v13, v60, -v58
	v_add_f32_e32 v66, v13, v13
	v_mul_f32_e32 v20, v12, v18
	v_mul_f32_e32 v32, v22, v30
	v_mul_f32_e32 v44, v34, v42
	v_mul_f32_e32 v56, v46, v54
	v_mul_f32_e32 v68, v58, v66
	v_mul_f32_e32 v13, v58, v64
	v_fmac_f32_e32 v20, v14, v16
	v_fmac_f32_e32 v32, v24, v28
	v_fmac_f32_e32 v44, v36, v40
	v_fmac_f32_e32 v56, v48, v52
	v_fmac_f32_e32 v68, v60, v64
	v_fma_f32 v70, v60, v66, -v13
	v_mov_b32_e32 v61, v60
	v_mov_b32_e32 v59, v58
	v_mov_b32_e32 v65, v64
	v_mov_b32_e32 v67, v66
	v_mov_b32_e32 v69, v68
	v_mov_b32_e32 v71, v70
	v_mov_b32_e32 v15, v14
	v_mov_b32_e32 v13, v12
	v_mov_b32_e32 v37, v36
	v_mov_b32_e32 v35, v34
	v_mov_b32_e32 v25, v24
	v_mov_b32_e32 v23, v22
	v_mov_b32_e32 v49, v48
	v_mov_b32_e32 v47, v46
	v_mov_b32_e32 v17, v16
	v_mov_b32_e32 v41, v40
	v_mov_b32_e32 v29, v28
	v_mov_b32_e32 v53, v52
	v_mov_b32_e32 v21, v20
	v_mov_b32_e32 v27, v26
	v_mov_b32_e32 v45, v44
	v_mov_b32_e32 v51, v50
	v_mov_b32_e32 v33, v32
	v_mov_b32_e32 v39, v38
	v_mov_b32_e32 v57, v56
	v_mov_b32_e32 v63, v62
	v_mov_b32_e32 v19, v18
	v_mov_b32_e32 v31, v30
	v_mov_b32_e32 v43, v42
	v_mov_b32_e32 v55, v54
	s_mov_b64 s[10:11], 0
	v_mov_b32_e32 v73, v10
	v_and_b32_e32 v241, 0xf, v73
	v_add_u32_e32 v250, 0x0, v241
	v_cvt_f32_u32_e32 v250, v250
	v_mul_f32_e32 v250, 0x3b800000, v250
	v_cos_f32_e32 v218, v250
	v_sin_f32_e32 v219, v250
	s_nop 1
	v_xor_b32_e32 v219, 0x80000000, v219
	s_nop 0
	v_pk_mul_f32 v[128:129], v[218:219], v[218:219] op_sel:[1,1] op_sel_hi:[1,0]
	s_nop 0
	v_pk_fma_f32 v[220:221], v[218:219], v[218:219], v[128:129] op_sel_hi:[0,1,1] neg_lo:[0,0,1]
	s_nop 0
	v_pk_mul_f32 v[128:129], v[220:221], v[218:219] op_sel:[1,1] op_sel_hi:[1,0]
	s_nop 0
	v_pk_fma_f32 v[222:223], v[220:221], v[218:219], v[128:129] op_sel_hi:[0,1,1] neg_lo:[0,0,1]
	s_nop 0
	v_add_u32_e32 v250, 0x10, v241
	v_cvt_f32_u32_e32 v250, v250
	v_mul_f32_e32 v250, 0x3b800000, v250
	v_cos_f32_e32 v224, v250
	v_sin_f32_e32 v225, v250
	s_nop 1
	v_xor_b32_e32 v225, 0x80000000, v225
	s_nop 0
	v_pk_mul_f32 v[128:129], v[224:225], v[224:225] op_sel:[1,1] op_sel_hi:[1,0]
	s_nop 0
	v_pk_fma_f32 v[226:227], v[224:225], v[224:225], v[128:129] op_sel_hi:[0,1,1] neg_lo:[0,0,1]
	s_nop 0
	v_pk_mul_f32 v[128:129], v[226:227], v[224:225] op_sel:[1,1] op_sel_hi:[1,0]
	s_nop 0
	v_pk_fma_f32 v[228:229], v[226:227], v[224:225], v[128:129] op_sel_hi:[0,1,1] neg_lo:[0,0,1]
	s_nop 0
	v_add_u32_e32 v250, 0x20, v241
	v_cvt_f32_u32_e32 v250, v250
	v_mul_f32_e32 v250, 0x3b800000, v250
	v_cos_f32_e32 v230, v250
	v_sin_f32_e32 v231, v250
	s_nop 1
	v_xor_b32_e32 v231, 0x80000000, v231
	s_nop 0
	v_pk_mul_f32 v[128:129], v[230:231], v[230:231] op_sel:[1,1] op_sel_hi:[1,0]
	s_nop 0
	v_pk_fma_f32 v[232:233], v[230:231], v[230:231], v[128:129] op_sel_hi:[0,1,1] neg_lo:[0,0,1]
	s_nop 0
	v_pk_mul_f32 v[128:129], v[232:233], v[230:231] op_sel:[1,1] op_sel_hi:[1,0]
	s_nop 0
	v_pk_fma_f32 v[234:235], v[232:233], v[230:231], v[128:129] op_sel_hi:[0,1,1] neg_lo:[0,0,1]
	s_nop 0
	v_add_u32_e32 v250, 0x30, v241
	v_cvt_f32_u32_e32 v250, v250
	v_mul_f32_e32 v250, 0x3b800000, v250
	v_cos_f32_e32 v236, v250
	v_sin_f32_e32 v237, v250
	s_nop 1
	v_xor_b32_e32 v237, 0x80000000, v237
	s_nop 0
	v_pk_mul_f32 v[128:129], v[236:237], v[236:237] op_sel:[1,1] op_sel_hi:[1,0]
	s_nop 0
	v_pk_fma_f32 v[238:239], v[236:237], v[236:237], v[128:129] op_sel_hi:[0,1,1] neg_lo:[0,0,1]
	s_nop 0
	v_pk_mul_f32 v[128:129], v[238:239], v[236:237] op_sel:[1,1] op_sel_hi:[1,0]
	s_nop 0
	v_pk_fma_f32 v[242:243], v[238:239], v[236:237], v[128:129] op_sel_hi:[0,1,1] neg_lo:[0,0,1]
	s_nop 0
	v_cvt_f32_u32_e32 v250, v241
	v_mul_f32_e32 v250, 0x3c800000, v250
	v_cos_f32_e32 v244, v250
	v_sin_f32_e32 v245, v250
	s_nop 1
	v_xor_b32_e32 v245, 0x80000000, v245
	s_nop 0
	v_pk_mul_f32 v[128:129], v[244:245], v[244:245] op_sel:[1,1] op_sel_hi:[1,0]
	s_nop 0
	v_pk_fma_f32 v[246:247], v[244:245], v[244:245], v[128:129] op_sel_hi:[0,1,1] neg_lo:[0,0,1]
	s_nop 0
	v_pk_mul_f32 v[128:129], v[246:247], v[244:245] op_sel:[1,1] op_sel_hi:[1,0]
	s_nop 0
	v_pk_fma_f32 v[248:249], v[246:247], v[244:245], v[128:129] op_sel_hi:[0,1,1] neg_lo:[0,0,1]
	s_nop 0
; DI float2 twid(float r) { return float2{__builtin_amdgcn_cosf(r), -__builtin_amdgcn_sinf(r)}; }
; DI void bfly_fwd(float2 a0, float2 a1, float2 a2, float2 a3, float r, float2& o0, float2& o1, float2& o2, float2& o3) {
;   float2 t0 = {a0.x + a2.x, a0.y + a2.y}, t1 = {a0.x - a2.x, a0.y - a2.y}, t2 = {a1.x + a3.x, a1.y + a3.y}, t3 = {a1.x - a3.x, a1.y - a3.y};
;   float2 b0 = {t0.x + t2.x, t0.y + t2.y}, b2 = {t0.x - t2.x, t0.y - t2.y}, b1 = {t1.x + t3.y, t1.y - t3.x}, b3 = {t1.x - t3.y, t1.y + t3.x};
;   float2 w1 = twid(r), w2 = cmul(w1, w1), w3 = cmul(w2, w1);
;   o0 = b0; o1 = cmul(b1, w1); o2 = cmul(b2, w2); o3 = cmul(b3, w3);
;     ...
;   for (int gg = tid; gg < NBT * (N / 16); gg += NTHR) { const int g = gg & (N / 16 - 1); float2* z = z0 + (gg / (N / 16)) * N; const int jp = g & (Q2 - 1), base = ((g >> lq2) << (lq2 + 4)) + jp; float2 x[4][4];
; #pragma unroll
;     for (int q1 = 0; q1 < 4; ++q1)
; #pragma unroll
;       for (int q2 = 0; q2 < 4; ++q2) x[q1][q2] = z[base + q1 * Q1 + q2 * Q2];
; #pragma unroll
;     for (int q2 = 0; q2 < 4; ++q2) bfly_fwd(x[0][q2], x[1][q2], x[2][q2], x[3][q2], (float)(jp + q2 * Q2) * invM1, x[0][q2], x[1][q2], x[2][q2], x[3][q2]);
; #pragma unroll
;     for (int q1 = 0; q1 < 4; ++q1) bfly_fwd(x[q1][0], x[q1][1], x[q1][2], x[q1][3], (float)jp * invM2, x[q1][0], x[q1][1], x[q1][2], x[q1][3]);
.LBB0_1521:
	v_ashrrev_i32_e32 v74, 31, v73
	v_lshrrev_b32_e32 v74, 22, v74
	v_add_lshl_u32 v74, v73, v74, 7
	v_and_b32_e32 v74, 0xfffe0000, v74
	v_and_b32_e32 v75, 0x3f00, v11
	v_add_u32_e32 v74, 16, v74
	v_lshlrev_b32_e32 v75, 3, v75
	v_lshlrev_b32_e32 v76, 3, v72
	v_add3_u32 v90, v74, v75, v76
	ds_read2_b64 v[78:81], v90 offset1:16
	ds_read2_b64 v[82:85], v90 offset0:32 offset1:48
	ds_read2_b64 v[86:89], v90 offset0:64 offset1:80
	ds_read2_b64 v[92:95], v90 offset0:96 offset1:112
	ds_read2_b64 v[96:99], v90 offset0:128 offset1:144
	ds_read2_b64 v[100:103], v90 offset0:160 offset1:176
	ds_read2_b64 v[104:107], v90 offset0:192 offset1:208
	ds_read2_b64 v[108:111], v90 offset0:224 offset1:240
	v_cmp_lt_i32_e32 vcc, s5, v73
	s_or_b64 s[10:11], vcc, s[10:11]
	s_waitcnt lgkmcnt(0)
	v_pk_add_f32 v[112:113], v[78:79], v[96:97]
	v_pk_add_f32 v[120:121], v[80:81], v[98:99]
	v_pk_add_f32 v[116:117], v[86:87], v[104:105]
	v_pk_add_f32 v[124:125], v[88:89], v[106:107]
	v_pk_add_f32 v[114:115], v[78:79], v[96:97] neg_lo:[0,1] neg_hi:[0,1]
	v_pk_add_f32 v[122:123], v[80:81], v[98:99] neg_lo:[0,1] neg_hi:[0,1]
	v_pk_add_f32 v[118:119], v[86:87], v[104:105] neg_lo:[0,1] neg_hi:[0,1]
	v_pk_add_f32 v[126:127], v[88:89], v[106:107] neg_lo:[0,1] neg_hi:[0,1]
	v_pk_add_f32 v[78:79], v[112:113], v[116:117]
	v_pk_add_f32 v[80:81], v[120:121], v[124:125]
	v_pk_add_f32 v[112:113], v[112:113], v[116:117] neg_lo:[0,1] neg_hi:[0,1]
	v_pk_add_f32 v[120:121], v[120:121], v[124:125] neg_lo:[0,1] neg_hi:[0,1]
	v_pk_add_f32 v[116:117], v[114:115], v[118:119] op_sel:[0,1] op_sel_hi:[1,0] neg_hi:[0,1]
	v_pk_add_f32 v[124:125], v[122:123], v[126:127] op_sel:[0,1] op_sel_hi:[1,0] neg_hi:[0,1]
	v_pk_add_f32 v[114:115], v[114:115], v[118:119] op_sel:[0,1] op_sel_hi:[1,0] neg_lo:[0,1]
	v_pk_add_f32 v[122:123], v[122:123], v[126:127] op_sel:[0,1] op_sel_hi:[1,0] neg_lo:[0,1]
	v_pk_mul_f32 v[128:129], v[112:113], v[220:221] op_sel:[1,1] op_sel_hi:[1,0]
	v_pk_mul_f32 v[132:133], v[120:121], v[226:227] op_sel:[1,1] op_sel_hi:[1,0]
	v_pk_mul_f32 v[130:131], v[116:117], v[218:219] op_sel:[1,1] op_sel_hi:[1,0]
	v_pk_mul_f32 v[134:135], v[124:125], v[224:225] op_sel:[1,1] op_sel_hi:[1,0]
	v_pk_fma_f32 v[96:97], v[112:113], v[220:221], v[128:129] op_sel_hi:[0,1,1] neg_lo:[0,0,1]
	v_pk_fma_f32 v[98:99], v[120:121], v[226:227], v[132:133] op_sel_hi:[0,1,1] neg_lo:[0,0,1]
	v_pk_mul_f32 v[128:129], v[114:115], v[222:223] op_sel:[1,1] op_sel_hi:[1,0]
	v_pk_mul_f32 v[132:133], v[122:123], v[228:229] op_sel:[1,1] op_sel_hi:[1,0]
	v_pk_fma_f32 v[86:87], v[116:117], v[218:219], v[130:131] op_sel_hi:[0,1,1] neg_lo:[0,0,1]
	v_pk_fma_f32 v[88:89], v[124:125], v[224:225], v[134:135] op_sel_hi:[0,1,1] neg_lo:[0,0,1]
	v_pk_fma_f32 v[104:105], v[114:115], v[222:223], v[128:129] op_sel_hi:[0,1,1] neg_lo:[0,0,1]
	v_pk_fma_f32 v[106:107], v[122:123], v[228:229], v[132:133] op_sel_hi:[0,1,1] neg_lo:[0,0,1]
	v_pk_add_f32 v[112:113], v[82:83], v[100:101]
	v_pk_add_f32 v[120:121], v[84:85], v[102:103]
	v_pk_add_f32 v[116:117], v[92:93], v[108:109]
	v_pk_add_f32 v[124:125], v[94:95], v[110:111]
	v_pk_add_f32 v[114:115], v[82:83], v[100:101] neg_lo:[0,1] neg_hi:[0,1]
	v_pk_add_f32 v[122:123], v[84:85], v[102:103] neg_lo:[0,1] neg_hi:[0,1]
	v_pk_add_f32 v[118:119], v[92:93], v[108:109] neg_lo:[0,1] neg_hi:[0,1]
	v_pk_add_f32 v[126:127], v[94:95], v[110:111] neg_lo:[0,1] neg_hi:[0,1]
	v_pk_add_f32 v[82:83], v[112:113], v[116:117]
	v_pk_add_f32 v[84:85], v[120:121], v[124:125]
	v_pk_add_f32 v[112:113], v[112:113], v[116:117] neg_lo:[0,1] neg_hi:[0,1]
	v_pk_add_f32 v[120:121], v[120:121], v[124:125] neg_lo:[0,1] neg_hi:[0,1]
	v_pk_add_f32 v[116:117], v[114:115], v[118:119] op_sel:[0,1] op_sel_hi:[1,0] neg_hi:[0,1]
	v_pk_add_f32 v[124:125], v[122:123], v[126:127] op_sel:[0,1] op_sel_hi:[1,0] neg_hi:[0,1]
	v_pk_add_f32 v[114:115], v[114:115], v[118:119] op_sel:[0,1] op_sel_hi:[1,0] neg_lo:[0,1]
	v_pk_add_f32 v[122:123], v[122:123], v[126:127] op_sel:[0,1] op_sel_hi:[1,0] neg_lo:[0,1]
	v_pk_mul_f32 v[128:129], v[112:113], v[232:233] op_sel:[1,1] op_sel_hi:[1,0]
	v_pk_mul_f32 v[132:133], v[120:121], v[238:239] op_sel:[1,1] op_sel_hi:[1,0]
	v_pk_mul_f32 v[130:131], v[116:117], v[230:231] op_sel:[1,1] op_sel_hi:[1,0]
	v_pk_mul_f32 v[134:135], v[124:125], v[236:237] op_sel:[1,1] op_sel_hi:[1,0]
	v_pk_fma_f32 v[100:101], v[112:113], v[232:233], v[128:129] op_sel_hi:[0,1,1] neg_lo:[0,0,1]
	v_pk_fma_f32 v[102:103], v[120:121], v[238:239], v[132:133] op_sel_hi:[0,1,1] neg_lo:[0,0,1]
	v_pk_mul_f32 v[128:129], v[114:115], v[234:235] op_sel:[1,1] op_sel_hi:[1,0]
	v_pk_mul_f32 v[132:133], v[122:123], v[242:243] op_sel:[1,1] op_sel_hi:[1,0]
	v_pk_fma_f32 v[92:93], v[116:117], v[230:231], v[130:131] op_sel_hi:[0,1,1] neg_lo:[0,0,1]
	v_pk_fma_f32 v[94:95], v[124:125], v[236:237], v[134:135] op_sel_hi:[0,1,1] neg_lo:[0,0,1]
	v_pk_fma_f32 v[108:109], v[114:115], v[234:235], v[128:129] op_sel_hi:[0,1,1] neg_lo:[0,0,1]
;     ...
;     for (int q1 = 0; q1 < 4; ++q1) bfly_fwd(x[q1][0], x[q1][1], x[q1][2], x[q1][3], (float)jp * invM2, x[q1][0], x[q1][1], x[q1][2], x[q1][3]);
; #pragma unroll
;     for (int q1 = 0; q1 < 4; ++q1)
; #pragma unroll
;       for (int q2 = 0; q2 < 4; ++q2) z[base + q1 * Q1 + q2 * Q2] = x[q1][q2]; }
;   __syncthreads();
	v_pk_fma_f32 v[110:111], v[122:123], v[242:243], v[132:133] op_sel_hi:[0,1,1] neg_lo:[0,0,1]
	v_pk_add_f32 v[112:113], v[78:79], v[82:83]
	v_pk_add_f32 v[120:121], v[86:87], v[92:93]
	v_pk_add_f32 v[116:117], v[80:81], v[84:85]
	v_pk_add_f32 v[124:125], v[88:89], v[94:95]
	v_pk_add_f32 v[114:115], v[78:79], v[82:83] neg_lo:[0,1] neg_hi:[0,1]
	v_pk_add_f32 v[122:123], v[86:87], v[92:93] neg_lo:[0,1] neg_hi:[0,1]
	v_pk_add_f32 v[118:119], v[80:81], v[84:85] neg_lo:[0,1] neg_hi:[0,1]
	v_pk_add_f32 v[126:127], v[88:89], v[94:95] neg_lo:[0,1] neg_hi:[0,1]
	v_pk_add_f32 v[78:79], v[112:113], v[116:117]
	v_pk_add_f32 v[86:87], v[120:121], v[124:125]
	v_pk_add_f32 v[112:113], v[112:113], v[116:117] neg_lo:[0,1] neg_hi:[0,1]
	v_pk_add_f32 v[120:121], v[120:121], v[124:125] neg_lo:[0,1] neg_hi:[0,1]
	v_pk_add_f32 v[116:117], v[114:115], v[118:119] op_sel:[0,1] op_sel_hi:[1,0] neg_hi:[0,1]
	v_pk_add_f32 v[124:125], v[122:123], v[126:127] op_sel:[0,1] op_sel_hi:[1,0] neg_hi:[0,1]
	v_pk_add_f32 v[114:115], v[114:115], v[118:119] op_sel:[0,1] op_sel_hi:[1,0] neg_lo:[0,1]
	v_pk_add_f32 v[122:123], v[122:123], v[126:127] op_sel:[0,1] op_sel_hi:[1,0] neg_lo:[0,1]
	v_pk_mul_f32 v[128:129], v[112:113], v[246:247] op_sel:[1,1] op_sel_hi:[1,0]
	v_pk_mul_f32 v[132:133], v[120:121], v[246:247] op_sel:[1,1] op_sel_hi:[1,0]
	v_pk_mul_f32 v[130:131], v[116:117], v[244:245] op_sel:[1,1] op_sel_hi:[1,0]
	v_pk_mul_f32 v[134:135], v[124:125], v[244:245] op_sel:[1,1] op_sel_hi:[1,0]
	v_pk_fma_f32 v[82:83], v[112:113], v[246:247], v[128:129] op_sel_hi:[0,1,1] neg_lo:[0,0,1]
	v_pk_fma_f32 v[92:93], v[120:121], v[246:247], v[132:133] op_sel_hi:[0,1,1] neg_lo:[0,0,1]
	v_pk_mul_f32 v[128:129], v[114:115], v[248:249] op_sel:[1,1] op_sel_hi:[1,0]
	v_pk_mul_f32 v[132:133], v[122:123], v[248:249] op_sel:[1,1] op_sel_hi:[1,0]
	v_pk_fma_f32 v[80:81], v[116:117], v[244:245], v[130:131] op_sel_hi:[0,1,1] neg_lo:[0,0,1]
	v_pk_fma_f32 v[88:89], v[124:125], v[244:245], v[134:135] op_sel_hi:[0,1,1] neg_lo:[0,0,1]
	v_pk_fma_f32 v[84:85], v[114:115], v[248:249], v[128:129] op_sel_hi:[0,1,1] neg_lo:[0,0,1]
	v_pk_fma_f32 v[94:95], v[122:123], v[248:249], v[132:133] op_sel_hi:[0,1,1] neg_lo:[0,0,1]
	v_pk_add_f32 v[112:113], v[96:97], v[100:101]
	v_pk_add_f32 v[120:121], v[104:105], v[108:109]
	v_pk_add_f32 v[116:117], v[98:99], v[102:103]
	v_pk_add_f32 v[124:125], v[106:107], v[110:111]
	v_pk_add_f32 v[114:115], v[96:97], v[100:101] neg_lo:[0,1] neg_hi:[0,1]
	v_pk_add_f32 v[122:123], v[104:105], v[108:109] neg_lo:[0,1] neg_hi:[0,1]
	v_pk_add_f32 v[118:119], v[98:99], v[102:103] neg_lo:[0,1] neg_hi:[0,1]
	v_pk_add_f32 v[126:127], v[106:107], v[110:111] neg_lo:[0,1] neg_hi:[0,1]
	v_pk_add_f32 v[96:97], v[112:113], v[116:117]
	v_pk_add_f32 v[104:105], v[120:121], v[124:125]
	v_pk_add_f32 v[112:113], v[112:113], v[116:117] neg_lo:[0,1] neg_hi:[0,1]
	v_pk_add_f32 v[120:121], v[120:121], v[124:125] neg_lo:[0,1] neg_hi:[0,1]
	v_pk_add_f32 v[116:117], v[114:115], v[118:119] op_sel:[0,1] op_sel_hi:[1,0] neg_hi:[0,1]
	v_pk_add_f32 v[124:125], v[122:123], v[126:127] op_sel:[0,1] op_sel_hi:[1,0] neg_hi:[0,1]
	v_pk_add_f32 v[114:115], v[114:115], v[118:119] op_sel:[0,1] op_sel_hi:[1,0] neg_lo:[0,1]
	v_pk_add_f32 v[122:123], v[122:123], v[126:127] op_sel:[0,1] op_sel_hi:[1,0] neg_lo:[0,1]
	v_pk_mul_f32 v[128:129], v[112:113], v[246:247] op_sel:[1,1] op_sel_hi:[1,0]
	v_pk_mul_f32 v[132:133], v[120:121], v[246:247] op_sel:[1,1] op_sel_hi:[1,0]
	v_pk_mul_f32 v[130:131], v[116:117], v[244:245] op_sel:[1,1] op_sel_hi:[1,0]
	v_pk_mul_f32 v[134:135], v[124:125], v[244:245] op_sel:[1,1] op_sel_hi:[1,0]
	v_pk_fma_f32 v[100:101], v[112:113], v[246:247], v[128:129] op_sel_hi:[0,1,1] neg_lo:[0,0,1]
	v_pk_fma_f32 v[108:109], v[120:121], v[246:247], v[132:133] op_sel_hi:[0,1,1] neg_lo:[0,0,1]
	v_pk_mul_f32 v[128:129], v[114:115], v[248:249] op_sel:[1,1] op_sel_hi:[1,0]
	v_pk_mul_f32 v[132:133], v[122:123], v[248:249] op_sel:[1,1] op_sel_hi:[1,0]
	v_pk_fma_f32 v[98:99], v[116:117], v[244:245], v[130:131] op_sel_hi:[0,1,1] neg_lo:[0,0,1]
	v_pk_fma_f32 v[106:107], v[124:125], v[244:245], v[134:135] op_sel_hi:[0,1,1] neg_lo:[0,0,1]
	v_pk_fma_f32 v[102:103], v[114:115], v[248:249], v[128:129] op_sel_hi:[0,1,1] neg_lo:[0,0,1]
	v_pk_fma_f32 v[110:111], v[122:123], v[248:249], v[132:133] op_sel_hi:[0,1,1] neg_lo:[0,0,1]
	s_nop 0
	ds_write2_b64 v90, v[78:79], v[80:81] offset1:16
	ds_write2_b64 v90, v[82:83], v[84:85] offset0:32 offset1:48
	ds_write2_b64 v90, v[86:87], v[88:89] offset0:64 offset1:80
	ds_write2_b64 v90, v[92:93], v[94:95] offset0:96 offset1:112
	ds_write2_b64 v90, v[96:97], v[98:99] offset0:128 offset1:144
	ds_write2_b64 v90, v[100:101], v[102:103] offset0:160 offset1:176
	ds_write2_b64 v90, v[104:105], v[106:107] offset0:192 offset1:208
	ds_write2_b64 v90, v[108:109], v[110:111] offset0:224 offset1:240
	v_add_u32_e32 v11, 0x2000, v11
	v_add_u32_e32 v74, 0x200, v73
	v_mov_b32_e32 v73, v74
	s_andn2_b64 exec, exec, s[10:11]
	s_cbranch_execnz .LBB0_1521

; DI float2 twid(float r) { return float2{__builtin_amdgcn_cosf(r), -__builtin_amdgcn_sinf(r)}; }
; DI void bfly_fwd(float2 a0, float2 a1, float2 a2, float2 a3, float r, float2& o0, float2& o1, float2& o2, float2& o3) {
;   float2 t0 = {a0.x + a2.x, a0.y + a2.y}, t1 = {a0.x - a2.x, a0.y - a2.y}, t2 = {a1.x + a3.x, a1.y + a3.y}, t3 = {a1.x - a3.x, a1.y - a3.y};
;   float2 b0 = {t0.x + t2.x, t0.y + t2.y}, b2 = {t0.x - t2.x, t0.y - t2.y}, b1 = {t1.x + t3.y, t1.y - t3.x}, b3 = {t1.x - t3.y, t1.y + t3.x};
;   float2 w1 = twid(r), w2 = cmul(w1, w1), w3 = cmul(w2, w1);
;   o0 = b0; o1 = cmul(b1, w1); o2 = cmul(b2, w2); o3 = cmul(b3, w3);
;   const int lq2 = lq1 - 2, Q1 = 1 << lq1, Q2 = 1 << lq2; const float invM1 = 1.f / (float)(4 << lq1), invM2 = 1.f / (float)(4 << lq2);
;   for (int gg = tid; gg < NBT * (N / 16); gg += NTHR) { const int g = gg & (N / 16 - 1); float2* z = z0 + (gg / (N / 16)) * N; const int jp = g & (Q2 - 1), base = ((g >> lq2) << (lq2 + 4)) + jp; float2 x[4][4];
; #pragma unroll
;     for (int q1 = 0; q1 < 4; ++q1)
; #pragma unroll
;       for (int q2 = 0; q2 < 4; ++q2) x[q1][q2] = z[base + q1 * Q1 + q2 * Q2];
; #pragma unroll
;     for (int q2 = 0; q2 < 4; ++q2) bfly_fwd(x[0][q2], x[1][q2], x[2][q2], x[3][q2], (float)(jp + q2 * Q2) * invM1, x[0][q2], x[1][q2], x[2][q2], x[3][q2]);
; #pragma unroll
;     for (int q1 = 0; q1 < 4; ++q1) bfly_fwd(x[q1][0], x[q1][1], x[q1][2], x[q1][3], (float)jp * invM2, x[q1][0], x[q1][1], x[q1][2], x[q1][3]);
.LBB0_1598:
	s_or_b64 exec, exec, s[0:1]
	s_movk_i32 s0, 0x400
	v_cmp_gt_i32_e32 vcc, s0, v75
	s_movk_i32 s0, 0x100
	v_or_b32_sdwa v77, v75, s0 dst_sel:DWORD dst_unused:UNUSED_PAD src0_sel:BYTE_0 src1_sel:DWORD
	s_movk_i32 s0, 0x200
	v_lshlrev_b32_e32 v62, 7, v75
	v_cvt_f32_ubyte0_e32 v2, v75
	v_or_b32_sdwa v76, v75, s0 dst_sel:DWORD dst_unused:UNUSED_PAD src0_sel:BYTE_0 src1_sel:DWORD
	s_movk_i32 s0, 0x300
	v_and_b32_e32 v79, 0x8000, v62
	v_lshlrev_b32_sdwa v80, v151, v75 dst_sel:DWORD dst_unused:UNUSED_PAD src0_sel:DWORD src1_sel:BYTE_0
	v_mul_f32_e32 v78, 0x39800000, v2
	v_or_b32_sdwa v0, v75, s0 dst_sel:DWORD dst_unused:UNUSED_PAD src0_sel:BYTE_0 src1_sel:DWORD
	v_mul_f32_e32 v81, 0x3a800000, v2
	s_waitcnt lgkmcnt(0)
	s_barrier
	s_and_saveexec_b64 s[0:1], vcc
	s_cbranch_execz .LBB0_1601
	v_sin_f32_e32 v2, v78
	v_cos_f32_e32 v4, v78
	v_sin_f32_e32 v48, v81
	v_cos_f32_e32 v50, v81
	v_mul_f32_e32 v3, v2, v2
	v_fma_f32 v6, v4, v4, -v3
	v_cvt_f32_u32_e32 v3, v77
	v_mul_f32_e64 v5, v4, -v2
	v_add_f32_e32 v8, v5, v5
	v_cvt_f32_u32_e32 v5, v76
	v_mul_f32_e32 v3, 0x39800000, v3
	v_sin_f32_e32 v12, v3
	v_cos_f32_e32 v14, v3
	v_mul_f32_e32 v3, v2, v6
	v_fma_f32 v16, v4, v8, -v3
	v_mul_f32_e32 v3, v12, v12
	v_fma_f32 v18, v14, v14, -v3
	v_mul_f32_e64 v3, v14, -v12
	v_add_f32_e32 v20, v3, v3
	v_mul_f32_e32 v3, 0x39800000, v5
	v_sin_f32_e32 v24, v3
	v_cos_f32_e32 v26, v3
	v_cvt_f32_u32_e32 v5, v0
	v_mul_f32_e32 v3, v12, v18
	v_fma_f32 v28, v14, v20, -v3
	v_mul_f32_e32 v3, v24, v24
	v_fma_f32 v30, v26, v26, -v3
	v_mul_f32_e64 v3, v26, -v24
	v_add_f32_e32 v32, v3, v3
	v_mul_f32_e32 v3, 0x39800000, v5
	v_sin_f32_e32 v36, v3
	v_cos_f32_e32 v38, v3
	v_mul_f32_e32 v3, v24, v30
	v_fma_f32 v40, v26, v32, -v3
	v_mul_f32_e32 v3, v36, v36
	v_fma_f32 v42, v38, v38, -v3
	v_mul_f32_e64 v3, v38, -v36
	v_add_f32_e32 v44, v3, v3
	v_mul_f32_e32 v3, v36, v42
	v_fma_f32 v52, v38, v44, -v3
	v_mul_f32_e32 v3, v48, v48
	v_fma_f32 v54, v50, v50, -v3
	v_mul_f32_e64 v3, v50, -v48
	v_add_f32_e32 v56, v3, v3
	v_mul_f32_e32 v10, v2, v8
	v_mul_f32_e32 v22, v12, v20
	v_mul_f32_e32 v34, v24, v32
	v_mul_f32_e32 v46, v36, v44
	v_mul_f32_e32 v58, v48, v56
	v_mul_f32_e32 v3, v48, v54
	v_fmac_f32_e32 v10, v4, v6
	v_fmac_f32_e32 v22, v14, v18
	v_fmac_f32_e32 v34, v26, v30
	v_fmac_f32_e32 v46, v38, v42
	v_fmac_f32_e32 v58, v50, v54
	v_fma_f32 v60, v50, v56, -v3
	v_add3_u32 v63, 16, v79, v80
	v_mov_b32_e32 v51, v50
	v_mov_b32_e32 v49, v48
	v_mov_b32_e32 v55, v54
	v_mov_b32_e32 v57, v56
	v_mov_b32_e32 v59, v58
	v_mov_b32_e32 v61, v60
	v_mov_b32_e32 v5, v4
	v_mov_b32_e32 v3, v2
	v_mov_b32_e32 v27, v26
	v_mov_b32_e32 v25, v24
	v_mov_b32_e32 v15, v14
	v_mov_b32_e32 v13, v12
	v_mov_b32_e32 v39, v38
	v_mov_b32_e32 v37, v36
	v_mov_b32_e32 v7, v6
	v_mov_b32_e32 v31, v30
	v_mov_b32_e32 v19, v18
	v_mov_b32_e32 v43, v42
	v_mov_b32_e32 v11, v10
	v_mov_b32_e32 v17, v16
	v_mov_b32_e32 v35, v34
	v_mov_b32_e32 v41, v40
	v_mov_b32_e32 v23, v22
	v_mov_b32_e32 v29, v28
	v_mov_b32_e32 v47, v46
	v_mov_b32_e32 v53, v52
	v_mov_b32_e32 v9, v8
	v_mov_b32_e32 v21, v20
	v_mov_b32_e32 v33, v32
	v_mov_b32_e32 v45, v44
	s_mov_b64 s[80:81], 0
	v_mov_b32_e32 v64, v75
	v_and_b32_e32 v241, 0xff, v64
	v_add_u32_e32 v250, 0x0, v241
	v_cvt_f32_u32_e32 v250, v250
	v_mul_f32_e32 v250, 0x39800000, v250
	v_cos_f32_e32 v218, v250
	v_sin_f32_e32 v219, v250
	s_nop 1
	v_xor_b32_e32 v219, 0x80000000, v219
	s_nop 0
	v_pk_mul_f32 v[122:123], v[218:219], v[218:219] op_sel:[1,1] op_sel_hi:[1,0]
	s_nop 0
	v_pk_fma_f32 v[220:221], v[218:219], v[218:219], v[122:123] op_sel_hi:[0,1,1] neg_lo:[0,0,1]
	s_nop 0
	v_pk_mul_f32 v[122:123], v[220:221], v[218:219] op_sel:[1,1] op_sel_hi:[1,0]
	s_nop 0
	v_pk_fma_f32 v[222:223], v[220:221], v[218:219], v[122:123] op_sel_hi:[0,1,1] neg_lo:[0,0,1]
	s_nop 0
	v_add_u32_e32 v250, 0x100, v241
	v_cvt_f32_u32_e32 v250, v250
	v_mul_f32_e32 v250, 0x39800000, v250
	v_cos_f32_e32 v224, v250
	v_sin_f32_e32 v225, v250
	s_nop 1
	v_xor_b32_e32 v225, 0x80000000, v225
	s_nop 0
	v_pk_mul_f32 v[122:123], v[224:225], v[224:225] op_sel:[1,1] op_sel_hi:[1,0]
	s_nop 0
	v_pk_fma_f32 v[226:227], v[224:225], v[224:225], v[122:123] op_sel_hi:[0,1,1] neg_lo:[0,0,1]
	s_nop 0
	v_pk_mul_f32 v[122:123], v[226:227], v[224:225] op_sel:[1,1] op_sel_hi:[1,0]
	s_nop 0
	v_pk_fma_f32 v[228:229], v[226:227], v[224:225], v[122:123] op_sel_hi:[0,1,1] neg_lo:[0,0,1]
	s_nop 0
	v_add_u32_e32 v250, 0x200, v241
	v_cvt_f32_u32_e32 v250, v250
	v_mul_f32_e32 v250, 0x39800000, v250
	v_cos_f32_e32 v230, v250
	v_sin_f32_e32 v231, v250
	s_nop 1
	v_xor_b32_e32 v231, 0x80000000, v231
	s_nop 0
	v_pk_mul_f32 v[122:123], v[230:231], v[230:231] op_sel:[1,1] op_sel_hi:[1,0]
	s_nop 0
	v_pk_fma_f32 v[232:233], v[230:231], v[230:231], v[122:123] op_sel_hi:[0,1,1] neg_lo:[0,0,1]
	s_nop 0
	v_pk_mul_f32 v[122:123], v[232:233], v[230:231] op_sel:[1,1] op_sel_hi:[1,0]
	s_nop 0
	v_pk_fma_f32 v[234:235], v[232:233], v[230:231], v[122:123] op_sel_hi:[0,1,1] neg_lo:[0,0,1]
	s_nop 0
	v_add_u32_e32 v250, 0x300, v241
	v_cvt_f32_u32_e32 v250, v250
	v_mul_f32_e32 v250, 0x39800000, v250
	v_cos_f32_e32 v236, v250
	v_sin_f32_e32 v237, v250
	s_nop 1
	v_xor_b32_e32 v237, 0x80000000, v237
	s_nop 0
	v_pk_mul_f32 v[122:123], v[236:237], v[236:237] op_sel:[1,1] op_sel_hi:[1,0]
	s_nop 0
	v_pk_fma_f32 v[238:239], v[236:237], v[236:237], v[122:123] op_sel_hi:[0,1,1] neg_lo:[0,0,1]
	s_nop 0
	v_pk_mul_f32 v[122:123], v[238:239], v[236:237] op_sel:[1,1] op_sel_hi:[1,0]
	s_nop 0
	v_pk_fma_f32 v[242:243], v[238:239], v[236:237], v[122:123] op_sel_hi:[0,1,1] neg_lo:[0,0,1]
	s_nop 0
	v_cvt_f32_u32_e32 v250, v241
	v_mul_f32_e32 v250, 0x3a800000, v250
	v_cos_f32_e32 v244, v250
	v_sin_f32_e32 v245, v250
	s_nop 1
	v_xor_b32_e32 v245, 0x80000000, v245
	s_nop 0
	v_pk_mul_f32 v[122:123], v[244:245], v[244:245] op_sel:[1,1] op_sel_hi:[1,0]
	s_nop 0
	v_pk_fma_f32 v[246:247], v[244:245], v[244:245], v[122:123] op_sel_hi:[0,1,1] neg_lo:[0,0,1]
	s_nop 0
	v_pk_mul_f32 v[122:123], v[246:247], v[244:245] op_sel:[1,1] op_sel_hi:[1,0]
	s_nop 0
	v_pk_fma_f32 v[248:249], v[246:247], v[244:245], v[122:123] op_sel_hi:[0,1,1] neg_lo:[0,0,1]
	s_nop 0
;     ...
;   for (int gg = tid; gg < NBT * (N / 16); gg += NTHR) { const int g = gg & (N / 16 - 1); float2* z = z0 + (gg / (N / 16)) * N; const int jp = g & (Q2 - 1), base = ((g >> lq2) << (lq2 + 4)) + jp; float2 x[4][4];
; #pragma unroll
;     for (int q1 = 0; q1 < 4; ++q1)
; #pragma unroll
;       for (int q2 = 0; q2 < 4; ++q2) x[q1][q2] = z[base + q1 * Q1 + q2 * Q2];
; #pragma unroll
;     for (int q2 = 0; q2 < 4; ++q2) bfly_fwd(x[0][q2], x[1][q2], x[2][q2], x[3][q2], (float)(jp + q2 * Q2) * invM1, x[0][q2], x[1][q2], x[2][q2], x[3][q2]);
; #pragma unroll
;     for (int q1 = 0; q1 < 4; ++q1) bfly_fwd(x[q1][0], x[q1][1], x[q1][2], x[q1][3], (float)jp * invM2, x[q1][0], x[q1][1], x[q1][2], x[q1][3]);
.LBB0_1600:
	v_ashrrev_i32_e32 v65, 31, v64
	v_lshrrev_b32_e32 v65, 23, v65
	v_add_lshl_u32 v65, v64, v65, 7
	v_and_b32_e32 v65, 0xffff0000, v65
	v_add_u32_e32 v65, v63, v65
	ds_read2st64_b64 v[66:69], v65 offset1:4
	ds_read2st64_b64 v[70:73], v65 offset0:8 offset1:12
	ds_read2st64_b64 v[82:85], v65 offset0:16 offset1:20
	ds_read2st64_b64 v[86:89], v65 offset0:24 offset1:28
	ds_read2st64_b64 v[90:93], v65 offset0:32 offset1:36
	ds_read2st64_b64 v[94:97], v65 offset0:40 offset1:44
	ds_read2st64_b64 v[98:101], v65 offset0:48 offset1:52
	ds_read2st64_b64 v[102:105], v65 offset0:56 offset1:60
	v_cmp_lt_i32_e64 s[12:13], s5, v64
	s_or_b64 s[80:81], s[12:13], s[80:81]
	s_waitcnt lgkmcnt(0)
	v_pk_add_f32 v[106:107], v[66:67], v[90:91]
	v_pk_add_f32 v[114:115], v[68:69], v[92:93]
	v_pk_add_f32 v[110:111], v[82:83], v[98:99]
	v_pk_add_f32 v[118:119], v[84:85], v[100:101]
	v_pk_add_f32 v[108:109], v[66:67], v[90:91] neg_lo:[0,1] neg_hi:[0,1]
	v_pk_add_f32 v[116:117], v[68:69], v[92:93] neg_lo:[0,1] neg_hi:[0,1]
	v_pk_add_f32 v[112:113], v[82:83], v[98:99] neg_lo:[0,1] neg_hi:[0,1]
	v_pk_add_f32 v[120:121], v[84:85], v[100:101] neg_lo:[0,1] neg_hi:[0,1]
	v_pk_add_f32 v[66:67], v[106:107], v[110:111]
	v_pk_add_f32 v[68:69], v[114:115], v[118:119]
	v_pk_add_f32 v[106:107], v[106:107], v[110:111] neg_lo:[0,1] neg_hi:[0,1]
	v_pk_add_f32 v[114:115], v[114:115], v[118:119] neg_lo:[0,1] neg_hi:[0,1]
	v_pk_add_f32 v[110:111], v[108:109], v[112:113] op_sel:[0,1] op_sel_hi:[1,0] neg_hi:[0,1]
	v_pk_add_f32 v[118:119], v[116:117], v[120:121] op_sel:[0,1] op_sel_hi:[1,0] neg_hi:[0,1]
	v_pk_add_f32 v[108:109], v[108:109], v[112:113] op_sel:[0,1] op_sel_hi:[1,0] neg_lo:[0,1]
	v_pk_add_f32 v[116:117], v[116:117], v[120:121] op_sel:[0,1] op_sel_hi:[1,0] neg_lo:[0,1]
	v_pk_mul_f32 v[122:123], v[106:107], v[220:221] op_sel:[1,1] op_sel_hi:[1,0]
	v_pk_mul_f32 v[126:127], v[114:115], v[226:227] op_sel:[1,1] op_sel_hi:[1,0]
	v_pk_mul_f32 v[124:125], v[110:111], v[218:219] op_sel:[1,1] op_sel_hi:[1,0]
	v_pk_mul_f32 v[128:129], v[118:119], v[224:225] op_sel:[1,1] op_sel_hi:[1,0]
	v_pk_fma_f32 v[90:91], v[106:107], v[220:221], v[122:123] op_sel_hi:[0,1,1] neg_lo:[0,0,1]
	v_pk_fma_f32 v[92:93], v[114:115], v[226:227], v[126:127] op_sel_hi:[0,1,1] neg_lo:[0,0,1]
	v_pk_mul_f32 v[122:123], v[108:109], v[222:223] op_sel:[1,1] op_sel_hi:[1,0]
	v_pk_mul_f32 v[126:127], v[116:117], v[228:229] op_sel:[1,1] op_sel_hi:[1,0]
	v_pk_fma_f32 v[82:83], v[110:111], v[218:219], v[124:125] op_sel_hi:[0,1,1] neg_lo:[0,0,1]
	v_pk_fma_f32 v[84:85], v[118:119], v[224:225], v[128:129] op_sel_hi:[0,1,1] neg_lo:[0,0,1]
	v_pk_fma_f32 v[98:99], v[108:109], v[222:223], v[122:123] op_sel_hi:[0,1,1] neg_lo:[0,0,1]
	v_pk_fma_f32 v[100:101], v[116:117], v[228:229], v[126:127] op_sel_hi:[0,1,1] neg_lo:[0,0,1]
	v_pk_add_f32 v[106:107], v[70:71], v[94:95]
	v_pk_add_f32 v[114:115], v[72:73], v[96:97]
	v_pk_add_f32 v[110:111], v[86:87], v[102:103]
	v_pk_add_f32 v[118:119], v[88:89], v[104:105]
	v_pk_add_f32 v[108:109], v[70:71], v[94:95] neg_lo:[0,1] neg_hi:[0,1]
	v_pk_add_f32 v[116:117], v[72:73], v[96:97] neg_lo:[0,1] neg_hi:[0,1]
	v_pk_add_f32 v[112:113], v[86:87], v[102:103] neg_lo:[0,1] neg_hi:[0,1]
	v_pk_add_f32 v[120:121], v[88:89], v[104:105] neg_lo:[0,1] neg_hi:[0,1]
	v_pk_add_f32 v[70:71], v[106:107], v[110:111]
	v_pk_add_f32 v[72:73], v[114:115], v[118:119]
	v_pk_add_f32 v[106:107], v[106:107], v[110:111] neg_lo:[0,1] neg_hi:[0,1]
	v_pk_add_f32 v[114:115], v[114:115], v[118:119] neg_lo:[0,1] neg_hi:[0,1]
	v_pk_add_f32 v[110:111], v[108:109], v[112:113] op_sel:[0,1] op_sel_hi:[1,0] neg_hi:[0,1]
	v_pk_add_f32 v[118:119], v[116:117], v[120:121] op_sel:[0,1] op_sel_hi:[1,0] neg_hi:[0,1]
	v_pk_add_f32 v[108:109], v[108:109], v[112:113] op_sel:[0,1] op_sel_hi:[1,0] neg_lo:[0,1]
	v_pk_add_f32 v[116:117], v[116:117], v[120:121] op_sel:[0,1] op_sel_hi:[1,0] neg_lo:[0,1]
	v_pk_mul_f32 v[122:123], v[106:107], v[232:233] op_sel:[1,1] op_sel_hi:[1,0]
	v_pk_mul_f32 v[126:127], v[114:115], v[238:239] op_sel:[1,1] op_sel_hi:[1,0]
	v_pk_mul_f32 v[124:125], v[110:111], v[230:231] op_sel:[1,1] op_sel_hi:[1,0]
	v_pk_mul_f32 v[128:129], v[118:119], v[236:237] op_sel:[1,1] op_sel_hi:[1,0]
	v_pk_fma_f32 v[94:95], v[106:107], v[232:233], v[122:123] op_sel_hi:[0,1,1] neg_lo:[0,0,1]
	v_pk_fma_f32 v[96:97], v[114:115], v[238:239], v[126:127] op_sel_hi:[0,1,1] neg_lo:[0,0,1]
	v_pk_mul_f32 v[122:123], v[108:109], v[234:235] op_sel:[1,1] op_sel_hi:[1,0]
	v_pk_mul_f32 v[126:127], v[116:117], v[242:243] op_sel:[1,1] op_sel_hi:[1,0]
	v_pk_fma_f32 v[86:87], v[110:111], v[230:231], v[124:125] op_sel_hi:[0,1,1] neg_lo:[0,0,1]
	v_pk_fma_f32 v[88:89], v[118:119], v[236:237], v[128:129] op_sel_hi:[0,1,1] neg_lo:[0,0,1]
	v_pk_fma_f32 v[102:103], v[108:109], v[234:235], v[122:123] op_sel_hi:[0,1,1] neg_lo:[0,0,1]
	v_pk_fma_f32 v[104:105], v[116:117], v[242:243], v[126:127] op_sel_hi:[0,1,1] neg_lo:[0,0,1]
	v_pk_add_f32 v[106:107], v[66:67], v[70:71]
	v_pk_add_f32 v[114:115], v[82:83], v[86:87]
	v_pk_add_f32 v[110:111], v[68:69], v[72:73]
	v_pk_add_f32 v[118:119], v[84:85], v[88:89]
	v_pk_add_f32 v[108:109], v[66:67], v[70:71] neg_lo:[0,1] neg_hi:[0,1]
	v_pk_add_f32 v[116:117], v[82:83], v[86:87] neg_lo:[0,1] neg_hi:[0,1]
	v_pk_add_f32 v[112:113], v[68:69], v[72:73] neg_lo:[0,1] neg_hi:[0,1]
	v_pk_add_f32 v[120:121], v[84:85], v[88:89] neg_lo:[0,1] neg_hi:[0,1]
	v_pk_add_f32 v[66:67], v[106:107], v[110:111]
	v_pk_add_f32 v[82:83], v[114:115], v[118:119]
	v_pk_add_f32 v[106:107], v[106:107], v[110:111] neg_lo:[0,1] neg_hi:[0,1]
	v_pk_add_f32 v[114:115], v[114:115], v[118:119] neg_lo:[0,1] neg_hi:[0,1]
;     ...
;     for (int q1 = 0; q1 < 4; ++q1) bfly_fwd(x[q1][0], x[q1][1], x[q1][2], x[q1][3], (float)jp * invM2, x[q1][0], x[q1][1], x[q1][2], x[q1][3]);
; #pragma unroll
;     for (int q1 = 0; q1 < 4; ++q1)
; #pragma unroll
;       for (int q2 = 0; q2 < 4; ++q2) z[base + q1 * Q1 + q2 * Q2] = x[q1][q2]; }
;   __syncthreads();
	v_pk_add_f32 v[110:111], v[108:109], v[112:113] op_sel:[0,1] op_sel_hi:[1,0] neg_hi:[0,1]
	v_pk_add_f32 v[118:119], v[116:117], v[120:121] op_sel:[0,1] op_sel_hi:[1,0] neg_hi:[0,1]
	v_pk_add_f32 v[108:109], v[108:109], v[112:113] op_sel:[0,1] op_sel_hi:[1,0] neg_lo:[0,1]
	v_pk_add_f32 v[116:117], v[116:117], v[120:121] op_sel:[0,1] op_sel_hi:[1,0] neg_lo:[0,1]
	v_pk_mul_f32 v[122:123], v[106:107], v[246:247] op_sel:[1,1] op_sel_hi:[1,0]
	v_pk_mul_f32 v[126:127], v[114:115], v[246:247] op_sel:[1,1] op_sel_hi:[1,0]
	v_pk_mul_f32 v[124:125], v[110:111], v[244:245] op_sel:[1,1] op_sel_hi:[1,0]
	v_pk_mul_f32 v[128:129], v[118:119], v[244:245] op_sel:[1,1] op_sel_hi:[1,0]
	v_pk_fma_f32 v[70:71], v[106:107], v[246:247], v[122:123] op_sel_hi:[0,1,1] neg_lo:[0,0,1]
	v_pk_fma_f32 v[86:87], v[114:115], v[246:247], v[126:127] op_sel_hi:[0,1,1] neg_lo:[0,0,1]
	v_pk_mul_f32 v[122:123], v[108:109], v[248:249] op_sel:[1,1] op_sel_hi:[1,0]
	v_pk_mul_f32 v[126:127], v[116:117], v[248:249] op_sel:[1,1] op_sel_hi:[1,0]
	v_pk_fma_f32 v[68:69], v[110:111], v[244:245], v[124:125] op_sel_hi:[0,1,1] neg_lo:[0,0,1]
	v_pk_fma_f32 v[84:85], v[118:119], v[244:245], v[128:129] op_sel_hi:[0,1,1] neg_lo:[0,0,1]
	v_pk_fma_f32 v[72:73], v[108:109], v[248:249], v[122:123] op_sel_hi:[0,1,1] neg_lo:[0,0,1]
	v_pk_fma_f32 v[88:89], v[116:117], v[248:249], v[126:127] op_sel_hi:[0,1,1] neg_lo:[0,0,1]
	v_pk_add_f32 v[106:107], v[90:91], v[94:95]
	v_pk_add_f32 v[114:115], v[98:99], v[102:103]
	v_pk_add_f32 v[110:111], v[92:93], v[96:97]
	v_pk_add_f32 v[118:119], v[100:101], v[104:105]
	v_pk_add_f32 v[108:109], v[90:91], v[94:95] neg_lo:[0,1] neg_hi:[0,1]
	v_pk_add_f32 v[116:117], v[98:99], v[102:103] neg_lo:[0,1] neg_hi:[0,1]
	v_pk_add_f32 v[112:113], v[92:93], v[96:97] neg_lo:[0,1] neg_hi:[0,1]
	v_pk_add_f32 v[120:121], v[100:101], v[104:105] neg_lo:[0,1] neg_hi:[0,1]
	v_pk_add_f32 v[90:91], v[106:107], v[110:111]
	v_pk_add_f32 v[98:99], v[114:115], v[118:119]
	v_pk_add_f32 v[106:107], v[106:107], v[110:111] neg_lo:[0,1] neg_hi:[0,1]
	v_pk_add_f32 v[114:115], v[114:115], v[118:119] neg_lo:[0,1] neg_hi:[0,1]
	v_pk_add_f32 v[110:111], v[108:109], v[112:113] op_sel:[0,1] op_sel_hi:[1,0] neg_hi:[0,1]
	v_pk_add_f32 v[118:119], v[116:117], v[120:121] op_sel:[0,1] op_sel_hi:[1,0] neg_hi:[0,1]
	v_pk_add_f32 v[108:109], v[108:109], v[112:113] op_sel:[0,1] op_sel_hi:[1,0] neg_lo:[0,1]
	v_pk_add_f32 v[116:117], v[116:117], v[120:121] op_sel:[0,1] op_sel_hi:[1,0] neg_lo:[0,1]
	v_pk_mul_f32 v[122:123], v[106:107], v[246:247] op_sel:[1,1] op_sel_hi:[1,0]
	v_pk_mul_f32 v[126:127], v[114:115], v[246:247] op_sel:[1,1] op_sel_hi:[1,0]
	v_pk_mul_f32 v[124:125], v[110:111], v[244:245] op_sel:[1,1] op_sel_hi:[1,0]
	v_pk_mul_f32 v[128:129], v[118:119], v[244:245] op_sel:[1,1] op_sel_hi:[1,0]
	v_pk_fma_f32 v[94:95], v[106:107], v[246:247], v[122:123] op_sel_hi:[0,1,1] neg_lo:[0,0,1]
	v_pk_fma_f32 v[102:103], v[114:115], v[246:247], v[126:127] op_sel_hi:[0,1,1] neg_lo:[0,0,1]
	v_pk_mul_f32 v[122:123], v[108:109], v[248:249] op_sel:[1,1] op_sel_hi:[1,0]
	v_pk_mul_f32 v[126:127], v[116:117], v[248:249] op_sel:[1,1] op_sel_hi:[1,0]
	v_pk_fma_f32 v[92:93], v[110:111], v[244:245], v[124:125] op_sel_hi:[0,1,1] neg_lo:[0,0,1]
	v_pk_fma_f32 v[100:101], v[118:119], v[244:245], v[128:129] op_sel_hi:[0,1,1] neg_lo:[0,0,1]
	v_pk_fma_f32 v[96:97], v[108:109], v[248:249], v[122:123] op_sel_hi:[0,1,1] neg_lo:[0,0,1]
	v_pk_fma_f32 v[104:105], v[116:117], v[248:249], v[126:127] op_sel_hi:[0,1,1] neg_lo:[0,0,1]
	s_nop 0
	ds_write2st64_b64 v65, v[66:67], v[68:69] offset1:4
	ds_write2st64_b64 v65, v[70:71], v[72:73] offset0:8 offset1:12
	ds_write2st64_b64 v65, v[82:83], v[84:85] offset0:16 offset1:20
	ds_write2st64_b64 v65, v[86:87], v[88:89] offset0:24 offset1:28
	ds_write2st64_b64 v65, v[90:91], v[92:93] offset0:32 offset1:36
	ds_write2st64_b64 v65, v[94:95], v[96:97] offset0:40 offset1:44
	ds_write2st64_b64 v65, v[98:99], v[100:101] offset0:48 offset1:52
	ds_write2st64_b64 v65, v[102:103], v[104:105] offset0:56 offset1:60
	v_add_u32_e32 v65, 0x200, v64
	v_mov_b32_e32 v64, v65
	s_andn2_b64 exec, exec, s[80:81]
	s_cbranch_execnz .LBB0_1600
.LBB0_1601:
	s_or_b64 exec, exec, s[0:1]
	v_and_b32_e32 v2, 15, v75
	v_and_b32_e32 v66, 0xf800, v62
	v_lshlrev_b32_e32 v67, 3, v2
	v_cvt_f32_ubyte0_e32 v65, v2
	v_or_b32_e32 v64, 16, v2
	v_or_b32_e32 v63, 32, v2
	v_or_b32_e32 v62, 48, v2
	s_waitcnt lgkmcnt(0)
	s_barrier
	s_and_saveexec_b64 s[0:1], vcc
	s_cbranch_execz .LBB0_1604
; DI float2 twid(float r) { return float2{__builtin_amdgcn_cosf(r), -__builtin_amdgcn_sinf(r)}; }
; DI void bfly_fwd(float2 a0, float2 a1, float2 a2, float2 a3, float r, float2& o0, float2& o1, float2& o2, float2& o3) {
;   float2 t0 = {a0.x + a2.x, a0.y + a2.y}, t1 = {a0.x - a2.x, a0.y - a2.y}, t2 = {a1.x + a3.x, a1.y + a3.y}, t3 = {a1.x - a3.x, a1.y - a3.y};
;   float2 b0 = {t0.x + t2.x, t0.y + t2.y}, b2 = {t0.x - t2.x, t0.y - t2.y}, b1 = {t1.x + t3.y, t1.y - t3.x}, b3 = {t1.x - t3.y, t1.y + t3.x};
;   float2 w1 = twid(r), w2 = cmul(w1, w1), w3 = cmul(w2, w1);
;   o0 = b0; o1 = cmul(b1, w1); o2 = cmul(b2, w2); o3 = cmul(b3, w3);
;   const int lq2 = lq1 - 2, Q1 = 1 << lq1, Q2 = 1 << lq2; const float invM1 = 1.f / (float)(4 << lq1), invM2 = 1.f / (float)(4 << lq2);
;   for (int gg = tid; gg < NBT * (N / 16); gg += NTHR) { const int g = gg & (N / 16 - 1); float2* z = z0 + (gg / (N / 16)) * N; const int jp = g & (Q2 - 1), base = ((g >> lq2) << (lq2 + 4)) + jp; float2 x[4][4];
; #pragma unroll
;     for (int q1 = 0; q1 < 4; ++q1)
; #pragma unroll
;       for (int q2 = 0; q2 < 4; ++q2) x[q1][q2] = z[base + q1 * Q1 + q2 * Q2];
; #pragma unroll
;     for (int q2 = 0; q2 < 4; ++q2) bfly_fwd(x[0][q2], x[1][q2], x[2][q2], x[3][q2], (float)(jp + q2 * Q2) * invM1, x[0][q2], x[1][q2], x[2][q2], x[3][q2]);
; #pragma unroll
;     for (int q1 = 0; q1 < 4; ++q1) bfly_fwd(x[q1][0], x[q1][1], x[q1][2], x[q1][3], (float)jp * invM2, x[q1][0], x[q1][1], x[q1][2], x[q1][3]);
	v_mul_f32_e32 v3, 0x3b800000, v65
	v_sin_f32_e32 v2, v3
	v_cos_f32_e32 v4, v3
	v_add3_u32 v68, 16, v66, v67
	s_mov_b64 s[80:81], 0
	v_mul_f32_e32 v3, v2, v2
	v_fma_f32 v6, v4, v4, -v3
	v_cvt_f32_ubyte0_e32 v3, v64
	v_mul_f32_e32 v3, 0x3b800000, v3
	v_sin_f32_e32 v12, v3
	v_cos_f32_e32 v14, v3
	v_mul_f32_e64 v5, v4, -v2
	v_add_f32_e32 v8, v5, v5
	v_mul_f32_e32 v3, v2, v6
	v_fma_f32 v16, v4, v8, -v3
	v_mul_f32_e32 v3, v12, v12
	v_fma_f32 v18, v14, v14, -v3
	v_mul_f32_e64 v3, v14, -v12
	v_add_f32_e32 v20, v3, v3
	v_cvt_f32_ubyte0_e32 v3, v63
	v_mul_f32_e32 v3, 0x3b800000, v3
	v_sin_f32_e32 v24, v3
	v_cos_f32_e32 v26, v3
	v_mul_f32_e32 v3, v12, v18
	v_fma_f32 v28, v14, v20, -v3
	v_mul_f32_e32 v3, v24, v24
	v_fma_f32 v30, v26, v26, -v3
	v_mul_f32_e64 v3, v26, -v24
	v_add_f32_e32 v32, v3, v3
	v_cvt_f32_ubyte0_e32 v3, v62
	v_mul_f32_e32 v3, 0x3b800000, v3
	v_sin_f32_e32 v36, v3
	v_cos_f32_e32 v38, v3
	v_mul_f32_e32 v3, v24, v30
	v_fma_f32 v40, v26, v32, -v3
	v_mul_f32_e32 v3, v36, v36
	v_fma_f32 v42, v38, v38, -v3
	v_mul_f32_e64 v3, v38, -v36
	v_add_f32_e32 v44, v3, v3
	v_mul_f32_e32 v3, 0x3c800000, v65
	v_sin_f32_e32 v48, v3
	v_cos_f32_e32 v50, v3
	v_mul_f32_e32 v3, v36, v42
	v_fma_f32 v52, v38, v44, -v3
	v_mul_f32_e32 v3, v48, v48
	v_fma_f32 v54, v50, v50, -v3
	v_mul_f32_e64 v3, v50, -v48
	v_add_f32_e32 v56, v3, v3
	v_mul_f32_e32 v10, v2, v8
	v_mul_f32_e32 v22, v12, v20
	v_mul_f32_e32 v34, v24, v32
	v_mul_f32_e32 v46, v36, v44
	v_mul_f32_e32 v58, v48, v56
	v_mul_f32_e32 v3, v48, v54
	v_fmac_f32_e32 v10, v4, v6
	v_fmac_f32_e32 v22, v14, v18
	v_fmac_f32_e32 v34, v26, v30
	v_fmac_f32_e32 v46, v38, v42
	v_fmac_f32_e32 v58, v50, v54
	v_fma_f32 v60, v50, v56, -v3
	v_mov_b32_e32 v51, v50
	v_mov_b32_e32 v49, v48
	v_mov_b32_e32 v55, v54
	v_mov_b32_e32 v57, v56
	v_mov_b32_e32 v59, v58
	v_mov_b32_e32 v61, v60
	v_mov_b32_e32 v5, v4
	v_mov_b32_e32 v3, v2
	v_mov_b32_e32 v27, v26
	v_mov_b32_e32 v25, v24
	v_mov_b32_e32 v15, v14
	v_mov_b32_e32 v13, v12
	v_mov_b32_e32 v39, v38
	v_mov_b32_e32 v37, v36
	v_mov_b32_e32 v7, v6
	v_mov_b32_e32 v31, v30
	v_mov_b32_e32 v19, v18
	v_mov_b32_e32 v43, v42
	v_mov_b32_e32 v11, v10
	v_mov_b32_e32 v17, v16
	v_mov_b32_e32 v35, v34
	v_mov_b32_e32 v41, v40
	v_mov_b32_e32 v23, v22
	v_mov_b32_e32 v29, v28
	v_mov_b32_e32 v47, v46
	v_mov_b32_e32 v53, v52
	v_mov_b32_e32 v9, v8
	v_mov_b32_e32 v21, v20
	v_mov_b32_e32 v33, v32
	v_mov_b32_e32 v45, v44
	v_mov_b32_e32 v69, v75
	v_and_b32_e32 v241, 0xf, v69
	v_add_u32_e32 v250, 0x0, v241
	v_cvt_f32_u32_e32 v250, v250
	v_mul_f32_e32 v250, 0x3b800000, v250
	v_cos_f32_e32 v218, v250
	v_sin_f32_e32 v219, v250
	s_nop 1
	v_xor_b32_e32 v219, 0x80000000, v219
	s_nop 0
	v_pk_mul_f32 v[128:129], v[218:219], v[218:219] op_sel:[1,1] op_sel_hi:[1,0]
	s_nop 0
	v_pk_fma_f32 v[220:221], v[218:219], v[218:219], v[128:129] op_sel_hi:[0,1,1] neg_lo:[0,0,1]
	s_nop 0
	v_pk_mul_f32 v[128:129], v[220:221], v[218:219] op_sel:[1,1] op_sel_hi:[1,0]
	s_nop 0
	v_pk_fma_f32 v[222:223], v[220:221], v[218:219], v[128:129] op_sel_hi:[0,1,1] neg_lo:[0,0,1]
	s_nop 0
	v_add_u32_e32 v250, 0x10, v241
	v_cvt_f32_u32_e32 v250, v250
	v_mul_f32_e32 v250, 0x3b800000, v250
	v_cos_f32_e32 v224, v250
	v_sin_f32_e32 v225, v250
	s_nop 1
	v_xor_b32_e32 v225, 0x80000000, v225
	s_nop 0
	v_pk_mul_f32 v[128:129], v[224:225], v[224:225] op_sel:[1,1] op_sel_hi:[1,0]
	s_nop 0
	v_pk_fma_f32 v[226:227], v[224:225], v[224:225], v[128:129] op_sel_hi:[0,1,1] neg_lo:[0,0,1]
	s_nop 0
	v_pk_mul_f32 v[128:129], v[226:227], v[224:225] op_sel:[1,1] op_sel_hi:[1,0]
	s_nop 0
	v_pk_fma_f32 v[228:229], v[226:227], v[224:225], v[128:129] op_sel_hi:[0,1,1] neg_lo:[0,0,1]
	s_nop 0
	v_add_u32_e32 v250, 0x20, v241
	v_cvt_f32_u32_e32 v250, v250
	v_mul_f32_e32 v250, 0x3b800000, v250
	v_cos_f32_e32 v230, v250
	v_sin_f32_e32 v231, v250
	s_nop 1
	v_xor_b32_e32 v231, 0x80000000, v231
	s_nop 0
	v_pk_mul_f32 v[128:129], v[230:231], v[230:231] op_sel:[1,1] op_sel_hi:[1,0]
	s_nop 0
	v_pk_fma_f32 v[232:233], v[230:231], v[230:231], v[128:129] op_sel_hi:[0,1,1] neg_lo:[0,0,1]
	s_nop 0
	v_pk_mul_f32 v[128:129], v[232:233], v[230:231] op_sel:[1,1] op_sel_hi:[1,0]
	s_nop 0
	v_pk_fma_f32 v[234:235], v[232:233], v[230:231], v[128:129] op_sel_hi:[0,1,1] neg_lo:[0,0,1]
	s_nop 0
	v_add_u32_e32 v250, 0x30, v241
	v_cvt_f32_u32_e32 v250, v250
	v_mul_f32_e32 v250, 0x3b800000, v250
	v_cos_f32_e32 v236, v250
	v_sin_f32_e32 v237, v250
	s_nop 1
	v_xor_b32_e32 v237, 0x80000000, v237
	s_nop 0
	v_pk_mul_f32 v[128:129], v[236:237], v[236:237] op_sel:[1,1] op_sel_hi:[1,0]
	s_nop 0
	v_pk_fma_f32 v[238:239], v[236:237], v[236:237], v[128:129] op_sel_hi:[0,1,1] neg_lo:[0,0,1]
	s_nop 0
	v_pk_mul_f32 v[128:129], v[238:239], v[236:237] op_sel:[1,1] op_sel_hi:[1,0]
	s_nop 0
	v_pk_fma_f32 v[242:243], v[238:239], v[236:237], v[128:129] op_sel_hi:[0,1,1] neg_lo:[0,0,1]
	s_nop 0
	v_cvt_f32_u32_e32 v250, v241
	v_mul_f32_e32 v250, 0x3c800000, v250
	v_cos_f32_e32 v244, v250
	v_sin_f32_e32 v245, v250
	s_nop 1
	v_xor_b32_e32 v245, 0x80000000, v245
	s_nop 0
	v_pk_mul_f32 v[128:129], v[244:245], v[244:245] op_sel:[1,1] op_sel_hi:[1,0]
	s_nop 0
	v_pk_fma_f32 v[246:247], v[244:245], v[244:245], v[128:129] op_sel_hi:[0,1,1] neg_lo:[0,0,1]
	s_nop 0
	v_pk_mul_f32 v[128:129], v[246:247], v[244:245] op_sel:[1,1] op_sel_hi:[1,0]
	s_nop 0
	v_pk_fma_f32 v[248:249], v[246:247], v[244:245], v[128:129] op_sel_hi:[0,1,1] neg_lo:[0,0,1]
	s_nop 0
;     ...
;   for (int gg = tid; gg < NBT * (N / 16); gg += NTHR) { const int g = gg & (N / 16 - 1); float2* z = z0 + (gg / (N / 16)) * N; const int jp = g & (Q2 - 1), base = ((g >> lq2) << (lq2 + 4)) + jp; float2 x[4][4];
; #pragma unroll
;     for (int q1 = 0; q1 < 4; ++q1)
; #pragma unroll
;       for (int q2 = 0; q2 < 4; ++q2) x[q1][q2] = z[base + q1 * Q1 + q2 * Q2];
; #pragma unroll
;     for (int q2 = 0; q2 < 4; ++q2) bfly_fwd(x[0][q2], x[1][q2], x[2][q2], x[3][q2], (float)(jp + q2 * Q2) * invM1, x[0][q2], x[1][q2], x[2][q2], x[3][q2]);
; #pragma unroll
;     for (int q1 = 0; q1 < 4; ++q1) bfly_fwd(x[q1][0], x[q1][1], x[q1][2], x[q1][3], (float)jp * invM2, x[q1][0], x[q1][1], x[q1][2], x[q1][3]);
.LBB0_1603:
	v_ashrrev_i32_e32 v70, 31, v69
	v_lshrrev_b32_e32 v70, 23, v70
	v_add_lshl_u32 v70, v69, v70, 7
	v_and_b32_e32 v70, 0xffff0000, v70
	v_add_u32_e32 v142, v68, v70
	ds_read2_b64 v[82:85], v142 offset1:16
	ds_read2_b64 v[86:89], v142 offset0:32 offset1:48
	ds_read2_b64 v[90:93], v142 offset0:64 offset1:80
	ds_read2_b64 v[94:97], v142 offset0:96 offset1:112
	ds_read2_b64 v[98:101], v142 offset0:128 offset1:144
	ds_read2_b64 v[102:105], v142 offset0:160 offset1:176
	ds_read2_b64 v[106:109], v142 offset0:192 offset1:208
	ds_read2_b64 v[110:113], v142 offset0:224 offset1:240
	v_cmp_lt_i32_e64 s[12:13], s5, v69
	s_or_b64 s[80:81], s[12:13], s[80:81]
	s_waitcnt lgkmcnt(0)
	v_pk_add_f32 v[72:73], v[82:83], v[98:99]
	v_pk_add_f32 v[120:121], v[84:85], v[100:101]
	v_pk_add_f32 v[116:117], v[90:91], v[106:107]
	v_pk_add_f32 v[124:125], v[92:93], v[108:109]
	v_pk_add_f32 v[114:115], v[82:83], v[98:99] neg_lo:[0,1] neg_hi:[0,1]
	v_pk_add_f32 v[122:123], v[84:85], v[100:101] neg_lo:[0,1] neg_hi:[0,1]
	v_pk_add_f32 v[118:119], v[90:91], v[106:107] neg_lo:[0,1] neg_hi:[0,1]
	v_pk_add_f32 v[126:127], v[92:93], v[108:109] neg_lo:[0,1] neg_hi:[0,1]
	v_pk_add_f32 v[82:83], v[72:73], v[116:117]
	v_pk_add_f32 v[84:85], v[120:121], v[124:125]
	v_pk_add_f32 v[72:73], v[72:73], v[116:117] neg_lo:[0,1] neg_hi:[0,1]
	v_pk_add_f32 v[120:121], v[120:121], v[124:125] neg_lo:[0,1] neg_hi:[0,1]
	v_pk_add_f32 v[116:117], v[114:115], v[118:119] op_sel:[0,1] op_sel_hi:[1,0] neg_hi:[0,1]
	v_pk_add_f32 v[124:125], v[122:123], v[126:127] op_sel:[0,1] op_sel_hi:[1,0] neg_hi:[0,1]
	v_pk_add_f32 v[114:115], v[114:115], v[118:119] op_sel:[0,1] op_sel_hi:[1,0] neg_lo:[0,1]
	v_pk_add_f32 v[122:123], v[122:123], v[126:127] op_sel:[0,1] op_sel_hi:[1,0] neg_lo:[0,1]
	v_pk_mul_f32 v[128:129], v[72:73], v[220:221] op_sel:[1,1] op_sel_hi:[1,0]
	v_pk_mul_f32 v[132:133], v[120:121], v[226:227] op_sel:[1,1] op_sel_hi:[1,0]
	v_pk_mul_f32 v[130:131], v[116:117], v[218:219] op_sel:[1,1] op_sel_hi:[1,0]
	v_pk_mul_f32 v[134:135], v[124:125], v[224:225] op_sel:[1,1] op_sel_hi:[1,0]
	v_pk_fma_f32 v[98:99], v[72:73], v[220:221], v[128:129] op_sel_hi:[0,1,1] neg_lo:[0,0,1]
	v_pk_fma_f32 v[100:101], v[120:121], v[226:227], v[132:133] op_sel_hi:[0,1,1] neg_lo:[0,0,1]
	v_pk_mul_f32 v[128:129], v[114:115], v[222:223] op_sel:[1,1] op_sel_hi:[1,0]
	v_pk_mul_f32 v[132:133], v[122:123], v[228:229] op_sel:[1,1] op_sel_hi:[1,0]
	v_pk_fma_f32 v[90:91], v[116:117], v[218:219], v[130:131] op_sel_hi:[0,1,1] neg_lo:[0,0,1]
	v_pk_fma_f32 v[92:93], v[124:125], v[224:225], v[134:135] op_sel_hi:[0,1,1] neg_lo:[0,0,1]
	v_pk_fma_f32 v[106:107], v[114:115], v[222:223], v[128:129] op_sel_hi:[0,1,1] neg_lo:[0,0,1]
	v_pk_fma_f32 v[108:109], v[122:123], v[228:229], v[132:133] op_sel_hi:[0,1,1] neg_lo:[0,0,1]
	v_pk_add_f32 v[72:73], v[86:87], v[102:103]
	v_pk_add_f32 v[120:121], v[88:89], v[104:105]
	v_pk_add_f32 v[116:117], v[94:95], v[110:111]
	v_pk_add_f32 v[124:125], v[96:97], v[112:113]
	v_pk_add_f32 v[114:115], v[86:87], v[102:103] neg_lo:[0,1] neg_hi:[0,1]
	v_pk_add_f32 v[122:123], v[88:89], v[104:105] neg_lo:[0,1] neg_hi:[0,1]
	v_pk_add_f32 v[118:119], v[94:95], v[110:111] neg_lo:[0,1] neg_hi:[0,1]
	v_pk_add_f32 v[126:127], v[96:97], v[112:113] neg_lo:[0,1] neg_hi:[0,1]
	v_pk_add_f32 v[86:87], v[72:73], v[116:117]
	v_pk_add_f32 v[88:89], v[120:121], v[124:125]
	v_pk_add_f32 v[72:73], v[72:73], v[116:117] neg_lo:[0,1] neg_hi:[0,1]
	v_pk_add_f32 v[120:121], v[120:121], v[124:125] neg_lo:[0,1] neg_hi:[0,1]
	v_pk_add_f32 v[116:117], v[114:115], v[118:119] op_sel:[0,1] op_sel_hi:[1,0] neg_hi:[0,1]
	v_pk_add_f32 v[124:125], v[122:123], v[126:127] op_sel:[0,1] op_sel_hi:[1,0] neg_hi:[0,1]
	v_pk_add_f32 v[114:115], v[114:115], v[118:119] op_sel:[0,1] op_sel_hi:[1,0] neg_lo:[0,1]
	v_pk_add_f32 v[122:123], v[122:123], v[126:127] op_sel:[0,1] op_sel_hi:[1,0] neg_lo:[0,1]
	v_pk_mul_f32 v[128:129], v[72:73], v[232:233] op_sel:[1,1] op_sel_hi:[1,0]
	v_pk_mul_f32 v[132:133], v[120:121], v[238:239] op_sel:[1,1] op_sel_hi:[1,0]
	v_pk_mul_f32 v[130:131], v[116:117], v[230:231] op_sel:[1,1] op_sel_hi:[1,0]
	v_pk_mul_f32 v[134:135], v[124:125], v[236:237] op_sel:[1,1] op_sel_hi:[1,0]
	v_pk_fma_f32 v[102:103], v[72:73], v[232:233], v[128:129] op_sel_hi:[0,1,1] neg_lo:[0,0,1]
	v_pk_fma_f32 v[104:105], v[120:121], v[238:239], v[132:133] op_sel_hi:[0,1,1] neg_lo:[0,0,1]
	v_pk_mul_f32 v[128:129], v[114:115], v[234:235] op_sel:[1,1] op_sel_hi:[1,0]
	v_pk_mul_f32 v[132:133], v[122:123], v[242:243] op_sel:[1,1] op_sel_hi:[1,0]
	v_pk_fma_f32 v[94:95], v[116:117], v[230:231], v[130:131] op_sel_hi:[0,1,1] neg_lo:[0,0,1]
	v_pk_fma_f32 v[96:97], v[124:125], v[236:237], v[134:135] op_sel_hi:[0,1,1] neg_lo:[0,0,1]
	v_pk_fma_f32 v[110:111], v[114:115], v[234:235], v[128:129] op_sel_hi:[0,1,1] neg_lo:[0,0,1]
	v_pk_fma_f32 v[112:113], v[122:123], v[242:243], v[132:133] op_sel_hi:[0,1,1] neg_lo:[0,0,1]
;     ...
;     for (int q1 = 0; q1 < 4; ++q1) bfly_fwd(x[q1][0], x[q1][1], x[q1][2], x[q1][3], (float)jp * invM2, x[q1][0], x[q1][1], x[q1][2], x[q1][3]);
; #pragma unroll
;     for (int q1 = 0; q1 < 4; ++q1)
; #pragma unroll
;       for (int q2 = 0; q2 < 4; ++q2) z[base + q1 * Q1 + q2 * Q2] = x[q1][q2]; }
;   __syncthreads();
	v_pk_add_f32 v[72:73], v[82:83], v[86:87]
	v_pk_add_f32 v[120:121], v[90:91], v[94:95]
	v_pk_add_f32 v[116:117], v[84:85], v[88:89]
	v_pk_add_f32 v[124:125], v[92:93], v[96:97]
	v_pk_add_f32 v[114:115], v[82:83], v[86:87] neg_lo:[0,1] neg_hi:[0,1]
	v_pk_add_f32 v[122:123], v[90:91], v[94:95] neg_lo:[0,1] neg_hi:[0,1]
	v_pk_add_f32 v[118:119], v[84:85], v[88:89] neg_lo:[0,1] neg_hi:[0,1]
	v_pk_add_f32 v[126:127], v[92:93], v[96:97] neg_lo:[0,1] neg_hi:[0,1]
	v_pk_add_f32 v[82:83], v[72:73], v[116:117]
	v_pk_add_f32 v[90:91], v[120:121], v[124:125]
	v_pk_add_f32 v[72:73], v[72:73], v[116:117] neg_lo:[0,1] neg_hi:[0,1]
	v_pk_add_f32 v[120:121], v[120:121], v[124:125] neg_lo:[0,1] neg_hi:[0,1]
	v_pk_add_f32 v[116:117], v[114:115], v[118:119] op_sel:[0,1] op_sel_hi:[1,0] neg_hi:[0,1]
	v_pk_add_f32 v[124:125], v[122:123], v[126:127] op_sel:[0,1] op_sel_hi:[1,0] neg_hi:[0,1]
	v_pk_add_f32 v[114:115], v[114:115], v[118:119] op_sel:[0,1] op_sel_hi:[1,0] neg_lo:[0,1]
	v_pk_add_f32 v[122:123], v[122:123], v[126:127] op_sel:[0,1] op_sel_hi:[1,0] neg_lo:[0,1]
	v_pk_mul_f32 v[128:129], v[72:73], v[246:247] op_sel:[1,1] op_sel_hi:[1,0]
	v_pk_mul_f32 v[132:133], v[120:121], v[246:247] op_sel:[1,1] op_sel_hi:[1,0]
	v_pk_mul_f32 v[130:131], v[116:117], v[244:245] op_sel:[1,1] op_sel_hi:[1,0]
	v_pk_mul_f32 v[134:135], v[124:125], v[244:245] op_sel:[1,1] op_sel_hi:[1,0]
	v_pk_fma_f32 v[86:87], v[72:73], v[246:247], v[128:129] op_sel_hi:[0,1,1] neg_lo:[0,0,1]
	v_pk_fma_f32 v[94:95], v[120:121], v[246:247], v[132:133] op_sel_hi:[0,1,1] neg_lo:[0,0,1]
	v_pk_mul_f32 v[128:129], v[114:115], v[248:249] op_sel:[1,1] op_sel_hi:[1,0]
	v_pk_mul_f32 v[132:133], v[122:123], v[248:249] op_sel:[1,1] op_sel_hi:[1,0]
	v_pk_fma_f32 v[84:85], v[116:117], v[244:245], v[130:131] op_sel_hi:[0,1,1] neg_lo:[0,0,1]
	v_pk_fma_f32 v[92:93], v[124:125], v[244:245], v[134:135] op_sel_hi:[0,1,1] neg_lo:[0,0,1]
	v_pk_fma_f32 v[88:89], v[114:115], v[248:249], v[128:129] op_sel_hi:[0,1,1] neg_lo:[0,0,1]
	v_pk_fma_f32 v[96:97], v[122:123], v[248:249], v[132:133] op_sel_hi:[0,1,1] neg_lo:[0,0,1]
	v_pk_add_f32 v[72:73], v[98:99], v[102:103]
	v_pk_add_f32 v[120:121], v[106:107], v[110:111]
	v_pk_add_f32 v[116:117], v[100:101], v[104:105]
	v_pk_add_f32 v[124:125], v[108:109], v[112:113]
	v_pk_add_f32 v[114:115], v[98:99], v[102:103] neg_lo:[0,1] neg_hi:[0,1]
	v_pk_add_f32 v[122:123], v[106:107], v[110:111] neg_lo:[0,1] neg_hi:[0,1]
	v_pk_add_f32 v[118:119], v[100:101], v[104:105] neg_lo:[0,1] neg_hi:[0,1]
	v_pk_add_f32 v[126:127], v[108:109], v[112:113] neg_lo:[0,1] neg_hi:[0,1]
	v_pk_add_f32 v[98:99], v[72:73], v[116:117]
	v_pk_add_f32 v[106:107], v[120:121], v[124:125]
	v_pk_add_f32 v[72:73], v[72:73], v[116:117] neg_lo:[0,1] neg_hi:[0,1]
	v_pk_add_f32 v[120:121], v[120:121], v[124:125] neg_lo:[0,1] neg_hi:[0,1]
	v_pk_add_f32 v[116:117], v[114:115], v[118:119] op_sel:[0,1] op_sel_hi:[1,0] neg_hi:[0,1]
	v_pk_add_f32 v[124:125], v[122:123], v[126:127] op_sel:[0,1] op_sel_hi:[1,0] neg_hi:[0,1]
	v_pk_add_f32 v[114:115], v[114:115], v[118:119] op_sel:[0,1] op_sel_hi:[1,0] neg_lo:[0,1]
	v_pk_add_f32 v[122:123], v[122:123], v[126:127] op_sel:[0,1] op_sel_hi:[1,0] neg_lo:[0,1]
	v_pk_mul_f32 v[128:129], v[72:73], v[246:247] op_sel:[1,1] op_sel_hi:[1,0]
	v_pk_mul_f32 v[132:133], v[120:121], v[246:247] op_sel:[1,1] op_sel_hi:[1,0]
	v_pk_mul_f32 v[130:131], v[116:117], v[244:245] op_sel:[1,1] op_sel_hi:[1,0]
	v_pk_mul_f32 v[134:135], v[124:125], v[244:245] op_sel:[1,1] op_sel_hi:[1,0]
	v_pk_fma_f32 v[102:103], v[72:73], v[246:247], v[128:129] op_sel_hi:[0,1,1] neg_lo:[0,0,1]
	v_pk_fma_f32 v[110:111], v[120:121], v[246:247], v[132:133] op_sel_hi:[0,1,1] neg_lo:[0,0,1]
	v_pk_mul_f32 v[128:129], v[114:115], v[248:249] op_sel:[1,1] op_sel_hi:[1,0]
	v_pk_mul_f32 v[132:133], v[122:123], v[248:249] op_sel:[1,1] op_sel_hi:[1,0]
	v_pk_fma_f32 v[100:101], v[116:117], v[244:245], v[130:131] op_sel_hi:[0,1,1] neg_lo:[0,0,1]
	v_pk_fma_f32 v[108:109], v[124:125], v[244:245], v[134:135] op_sel_hi:[0,1,1] neg_lo:[0,0,1]
	v_pk_fma_f32 v[104:105], v[114:115], v[248:249], v[128:129] op_sel_hi:[0,1,1] neg_lo:[0,0,1]
	v_pk_fma_f32 v[112:113], v[122:123], v[248:249], v[132:133] op_sel_hi:[0,1,1] neg_lo:[0,0,1]
	s_nop 0
	ds_write2_b64 v142, v[82:83], v[84:85] offset1:16
	ds_write2_b64 v142, v[86:87], v[88:89] offset0:32 offset1:48
	ds_write2_b64 v142, v[90:91], v[92:93] offset0:64 offset1:80
	ds_write2_b64 v142, v[94:95], v[96:97] offset0:96 offset1:112
	ds_write2_b64 v142, v[98:99], v[100:101] offset0:128 offset1:144
	ds_write2_b64 v142, v[102:103], v[104:105] offset0:160 offset1:176
	ds_write2_b64 v142, v[106:107], v[108:109] offset0:192 offset1:208
	ds_write2_b64 v142, v[110:111], v[112:113] offset0:224 offset1:240
	v_add_u32_e32 v70, 0x200, v69
	v_mov_b32_e32 v69, v70
	s_andn2_b64 exec, exec, s[80:81]
	s_cbranch_execnz .LBB0_1603

; DI float2 twid(float r) { return float2{__builtin_amdgcn_cosf(r), -__builtin_amdgcn_sinf(r)}; }
; DI void bfly_inv(float2 s0, float2 s1, float2 s2, float2 s3, float r, float2& o0, float2& o1, float2& o2, float2& o3) {
;   float2 w1 = twid(r), w2 = cmul(w1, w1), w3 = cmul(w2, w1);
;   float2 c0 = s0, c1 = cmulc(s1, w1), c2 = cmulc(s2, w2), c3 = cmulc(s3, w3);
;   const int lq1 = lq2 + 2, Q1 = 1 << lq1, Q2 = 1 << lq2; const float invM1 = 1.f / (float)(4 << lq1), invM2 = 1.f / (float)(4 << lq2);
;   for (int gg = tid; gg < NBT * (N / 16); gg += NTHR) { const int g = gg & (N / 16 - 1); float2* z = z0 + (gg / (N / 16)) * N; const int jp = g & (Q2 - 1), base = ((g >> lq2) << (lq2 + 4)) + jp; float2 x[4][4];
; #pragma unroll
;     for (int q1 = 0; q1 < 4; ++q1)
; #pragma unroll
;       for (int q2 = 0; q2 < 4; ++q2) x[q1][q2] = z[base + q1 * Q1 + q2 * Q2];
; #pragma unroll
;     for (int q1 = 0; q1 < 4; ++q1) bfly_inv(x[q1][0], x[q1][1], x[q1][2], x[q1][3], (float)jp * invM2, x[q1][0], x[q1][1], x[q1][2], x[q1][3]);
; #pragma unroll
;     for (int q2 = 0; q2 < 4; ++q2) bfly_inv(x[0][q2], x[1][q2], x[2][q2], x[3][q2], (float)(jp + q2 * Q2) * invM1, x[0][q2], x[1][q2], x[2][q2], x[3][q2]);
.LBB0_1616:
	s_or_b64 exec, exec, s[0:1]
	s_waitcnt lgkmcnt(0)
	s_barrier
	s_and_saveexec_b64 s[0:1], vcc
	s_cbranch_execz .LBB0_1619
	v_mul_f32_e32 v2, 0x3c800000, v65
	v_sin_f32_e32 v3, v2
	v_cos_f32_e32 v4, v2
	v_add3_u32 v20, 16, v66, v67
	s_mov_b64 s[80:81], 0
	v_xor_b32_e32 v8, 0x80000000, v3
	v_mov_b32_e32 v2, v4
	v_mov_b32_e32 v6, v8
	v_mov_b32_e32 v7, v3
	v_mov_b32_e32 v5, v4
	v_mov_b32_e32 v9, v4
	v_pk_mul_f32 v[10:11], v[2:3], v[6:7]
	v_mov_b32_e32 v56, v4
	v_pk_fma_f32 v[6:7], v[4:5], v[8:9], v[10:11] op_sel_hi:[0,1,1] neg_lo:[0,0,1] neg_hi:[0,0,1]
	v_pk_fma_f32 v[8:9], v[4:5], v[8:9], v[10:11] op_sel_hi:[0,1,1]
	v_pk_mov_b32 v[10:11], v[6:7], v[8:9] op_sel:[1,0]
	v_mul_f32_e32 v6, 0x3b800000, v65
	v_sin_f32_e32 v12, v6
	v_cos_f32_e32 v14, v6
	v_mov_b32_e32 v16, v8
	v_mov_b32_e32 v17, v7
	v_mul_f32_e32 v6, v12, v12
	v_fma_f32 v22, v14, v14, -v6
	v_cvt_f32_ubyte0_e32 v6, v64
	v_mul_f32_e32 v6, 0x3b800000, v6
	v_sin_f32_e32 v25, v6
	v_cos_f32_e32 v27, v6
	v_pk_mul_f32 v[18:19], v[2:3], v[10:11] op_sel:[1,0]
	v_mul_f32_e64 v9, v14, -v12
	v_pk_fma_f32 v[10:11], v[4:5], v[16:17], v[18:19] op_sel_hi:[0,1,1]
	v_pk_fma_f32 v[16:17], v[4:5], v[16:17], v[18:19] op_sel_hi:[0,1,1] neg_lo:[0,0,1] neg_hi:[0,0,1]
	v_add_f32_e32 v18, v9, v9
	v_mul_f32_e32 v6, v12, v22
	v_fma_f32 v60, v14, v18, -v6
	v_mul_f32_e32 v6, v25, v25
	v_fma_f32 v28, v27, v27, -v6
	v_mul_f32_e64 v6, v27, -v25
	v_add_f32_e32 v30, v6, v6
	v_cvt_f32_ubyte0_e32 v6, v63
	v_mul_f32_e32 v6, 0x3b800000, v6
	v_sin_f32_e32 v33, v6
	v_cos_f32_e32 v35, v6
	v_mul_f32_e32 v6, v25, v28
	v_fma_f32 v26, v27, v30, -v6
	v_mul_f32_e32 v6, v33, v33
	v_fma_f32 v36, v35, v35, -v6
	v_mul_f32_e64 v6, v35, -v33
	v_add_f32_e32 v38, v6, v6
	v_cvt_f32_ubyte0_e32 v6, v62
	v_mul_f32_e32 v6, 0x3b800000, v6
	v_sin_f32_e32 v40, v6
	v_cos_f32_e32 v42, v6
	v_mul_f32_e32 v21, v12, v18
	v_mul_f32_e32 v24, v25, v30
	v_xor_b32_e32 v43, 0x80000000, v40
	v_mov_b32_e32 v41, v42
	v_mov_b32_e32 v44, v40
	v_mov_b32_e32 v45, v43
	v_pk_mul_f32 v[46:47], v[40:41], v[44:45]
	v_mul_f32_e32 v32, v33, v38
	v_pk_fma_f32 v[44:45], v[42:43], v[42:43], v[46:47] op_sel_hi:[0,1,1] neg_lo:[0,0,1] neg_hi:[0,0,1]
	v_pk_fma_f32 v[62:63], v[42:43], v[42:43], v[46:47] op_sel_hi:[0,1,1]
	v_pk_mov_b32 v[48:49], v[62:63], v[44:45] op_sel:[1,0]
	v_mul_f32_e32 v6, v33, v36
	v_mov_b32_e32 v46, v44
	v_mov_b32_e32 v47, v63
	v_pk_mul_f32 v[48:49], v[40:41], v[48:49] op_sel_hi:[0,1]
	v_fmac_f32_e32 v21, v14, v22
	v_fmac_f32_e32 v24, v27, v28
	v_fmac_f32_e32 v32, v35, v36
	v_fma_f32 v34, v35, v38, -v6
	v_pk_fma_f32 v[58:59], v[42:43], v[46:47], v[48:49] op_sel_hi:[0,1,1]
	v_pk_fma_f32 v[46:47], v[42:43], v[46:47], v[48:49] op_sel_hi:[0,1,1] neg_lo:[0,0,1] neg_hi:[0,0,1]
	v_mov_b32_e32 v19, v12
	v_mov_b32_e32 v17, v11
	v_mov_b32_e32 v46, v58
	v_mov_b32_e32 v9, v8
	v_mov_b32_e32 v29, v28
	v_mov_b32_e32 v31, v30
	v_pk_mov_b32 v[48:49], v[26:27], v[24:25] op_sel:[1,0]
	v_pk_mov_b32 v[50:51], v[24:25], v[26:27] op_sel:[1,0]
	v_mov_b32_e32 v37, v36
	v_pk_mov_b32 v[52:53], v[34:35], v[32:33] op_sel:[1,0]
	v_pk_mov_b32 v[54:55], v[32:33], v[34:35] op_sel:[1,0]
	v_mov_b32_e32 v57, v16
	v_mov_b32_e32 v10, v3
	v_pk_mov_b32 v[58:59], v[62:63], v[58:59] op_sel:[1,0]
	v_mov_b32_e32 v45, v47
	v_mov_b32_e32 v43, v44
	v_mov_b32_e32 v41, v63
	v_mov_b32_e32 v61, v16
	v_mov_b32_e32 v62, v3
	v_mov_b32_e32 v63, v3
	v_mov_b32_e32 v6, v7
	v_mov_b32_e32 v64, v4
	v_mov_b32_e32 v65, v11
	v_mov_b32_e32 v66, v3
	v_mov_b32_e32 v67, v16
	v_mov_b32_e32 v68, v11
	v_mov_b32_e32 v69, v11
	v_mov_b32_e32 v70, v16
	v_mov_b32_e32 v71, v16
	v_mov_b32_e32 v23, v14
	v_pk_mov_b32 v[72:73], v[20:21], v[18:19] op_sel:[1,0]
	v_mov_b32_e32 v39, v38
	v_mov_b32_e32 v82, v75
	v_and_b32_e32 v241, 0xf, v82
	v_add_u32_e32 v250, 0x0, v241
	v_cvt_f32_u32_e32 v250, v250
	v_mul_f32_e32 v250, 0x3b800000, v250
	v_cos_f32_e32 v218, v250
	v_sin_f32_e32 v219, v250
	s_nop 1
	v_xor_b32_e32 v219, 0x80000000, v219
	s_nop 0
	v_pk_mul_f32 v[132:133], v[218:219], v[218:219] op_sel:[1,1] op_sel_hi:[1,0]
	s_nop 0
	v_pk_fma_f32 v[220:221], v[218:219], v[218:219], v[132:133] op_sel_hi:[0,1,1] neg_lo:[0,0,1]
	s_nop 0
	v_pk_mul_f32 v[132:133], v[220:221], v[218:219] op_sel:[1,1] op_sel_hi:[1,0]
	s_nop 0
	v_pk_fma_f32 v[222:223], v[220:221], v[218:219], v[132:133] op_sel_hi:[0,1,1] neg_lo:[0,0,1]
	s_nop 0
	v_xor_b32_e32 v219, 0x80000000, v219
	v_xor_b32_e32 v221, 0x80000000, v221
	v_xor_b32_e32 v223, 0x80000000, v223
	v_add_u32_e32 v250, 0x10, v241
	v_cvt_f32_u32_e32 v250, v250
	v_mul_f32_e32 v250, 0x3b800000, v250
	v_cos_f32_e32 v224, v250
	v_sin_f32_e32 v225, v250
	s_nop 1
	v_xor_b32_e32 v225, 0x80000000, v225
	s_nop 0
	v_pk_mul_f32 v[132:133], v[224:225], v[224:225] op_sel:[1,1] op_sel_hi:[1,0]
	s_nop 0
	v_pk_fma_f32 v[226:227], v[224:225], v[224:225], v[132:133] op_sel_hi:[0,1,1] neg_lo:[0,0,1]
	s_nop 0
	v_pk_mul_f32 v[132:133], v[226:227], v[224:225] op_sel:[1,1] op_sel_hi:[1,0]
	s_nop 0
	v_pk_fma_f32 v[228:229], v[226:227], v[224:225], v[132:133] op_sel_hi:[0,1,1] neg_lo:[0,0,1]
	s_nop 0
	v_xor_b32_e32 v225, 0x80000000, v225
	v_xor_b32_e32 v227, 0x80000000, v227
	v_xor_b32_e32 v229, 0x80000000, v229
	v_add_u32_e32 v250, 0x20, v241
	v_cvt_f32_u32_e32 v250, v250
	v_mul_f32_e32 v250, 0x3b800000, v250
	v_cos_f32_e32 v230, v250
	v_sin_f32_e32 v231, v250
	s_nop 1
	v_xor_b32_e32 v231, 0x80000000, v231
	s_nop 0
	v_pk_mul_f32 v[132:133], v[230:231], v[230:231] op_sel:[1,1] op_sel_hi:[1,0]
	s_nop 0
	v_pk_fma_f32 v[232:233], v[230:231], v[230:231], v[132:133] op_sel_hi:[0,1,1] neg_lo:[0,0,1]
	s_nop 0
	v_pk_mul_f32 v[132:133], v[232:233], v[230:231] op_sel:[1,1] op_sel_hi:[1,0]
	s_nop 0
; DI float2 twid(float r) { return float2{__builtin_amdgcn_cosf(r), -__builtin_amdgcn_sinf(r)}; }
; DI void bfly_inv(float2 s0, float2 s1, float2 s2, float2 s3, float r, float2& o0, float2& o1, float2& o2, float2& o3) {
;   float2 w1 = twid(r), w2 = cmul(w1, w1), w3 = cmul(w2, w1);
;   float2 c0 = s0, c1 = cmulc(s1, w1), c2 = cmulc(s2, w2), c3 = cmulc(s3, w3);
;   float2 t0 = {c0.x + c2.x, c0.y + c2.y}, t1 = {c0.x - c2.x, c0.y - c2.y}, t2 = {c1.x + c3.x, c1.y + c3.y}, t3 = {c1.x - c3.x, c1.y - c3.y};
;   o0 = float2{t0.x + t2.x, t0.y + t2.y}; o2 = float2{t0.x - t2.x, t0.y - t2.y}; o1 = float2{t1.x - t3.y, t1.y + t3.x}; o3 = float2{t1.x + t3.y, t1.y - t3.x};
;     ...
;   for (int gg = tid; gg < NBT * (N / 16); gg += NTHR) { const int g = gg & (N / 16 - 1); float2* z = z0 + (gg / (N / 16)) * N; const int jp = g & (Q2 - 1), base = ((g >> lq2) << (lq2 + 4)) + jp; float2 x[4][4];
; #pragma unroll
;     for (int q1 = 0; q1 < 4; ++q1)
; #pragma unroll
;       for (int q2 = 0; q2 < 4; ++q2) x[q1][q2] = z[base + q1 * Q1 + q2 * Q2];
; #pragma unroll
;     for (int q1 = 0; q1 < 4; ++q1) bfly_inv(x[q1][0], x[q1][1], x[q1][2], x[q1][3], (float)jp * invM2, x[q1][0], x[q1][1], x[q1][2], x[q1][3]);
; #pragma unroll
;     for (int q2 = 0; q2 < 4; ++q2) bfly_inv(x[0][q2], x[1][q2], x[2][q2], x[3][q2], (float)(jp + q2 * Q2) * invM1, x[0][q2], x[1][q2], x[2][q2], x[3][q2]);
	v_pk_fma_f32 v[234:235], v[232:233], v[230:231], v[132:133] op_sel_hi:[0,1,1] neg_lo:[0,0,1]
	s_nop 0
	v_xor_b32_e32 v231, 0x80000000, v231
	v_xor_b32_e32 v233, 0x80000000, v233
	v_xor_b32_e32 v235, 0x80000000, v235
	v_add_u32_e32 v250, 0x30, v241
	v_cvt_f32_u32_e32 v250, v250
	v_mul_f32_e32 v250, 0x3b800000, v250
	v_cos_f32_e32 v236, v250
	v_sin_f32_e32 v237, v250
	s_nop 1
	v_xor_b32_e32 v237, 0x80000000, v237
	s_nop 0
	v_pk_mul_f32 v[132:133], v[236:237], v[236:237] op_sel:[1,1] op_sel_hi:[1,0]
	s_nop 0
	v_pk_fma_f32 v[238:239], v[236:237], v[236:237], v[132:133] op_sel_hi:[0,1,1] neg_lo:[0,0,1]
	s_nop 0
	v_pk_mul_f32 v[132:133], v[238:239], v[236:237] op_sel:[1,1] op_sel_hi:[1,0]
	s_nop 0
	v_pk_fma_f32 v[242:243], v[238:239], v[236:237], v[132:133] op_sel_hi:[0,1,1] neg_lo:[0,0,1]
	s_nop 0
	v_xor_b32_e32 v237, 0x80000000, v237
	v_xor_b32_e32 v239, 0x80000000, v239
	v_xor_b32_e32 v243, 0x80000000, v243
	v_cvt_f32_u32_e32 v250, v241
	v_mul_f32_e32 v250, 0x3c800000, v250
	v_cos_f32_e32 v244, v250
	v_sin_f32_e32 v245, v250
	s_nop 1
	v_xor_b32_e32 v245, 0x80000000, v245
	s_nop 0
	v_pk_mul_f32 v[132:133], v[244:245], v[244:245] op_sel:[1,1] op_sel_hi:[1,0]
	s_nop 0
	v_pk_fma_f32 v[246:247], v[244:245], v[244:245], v[132:133] op_sel_hi:[0,1,1] neg_lo:[0,0,1]
	s_nop 0
	v_pk_mul_f32 v[132:133], v[246:247], v[244:245] op_sel:[1,1] op_sel_hi:[1,0]
	s_nop 0
	v_pk_fma_f32 v[248:249], v[246:247], v[244:245], v[132:133] op_sel_hi:[0,1,1] neg_lo:[0,0,1]
	s_nop 0
	v_xor_b32_e32 v245, 0x80000000, v245
	v_xor_b32_e32 v247, 0x80000000, v247
	v_xor_b32_e32 v249, 0x80000000, v249
.LBB0_1618:
	v_ashrrev_i32_e32 v13, 31, v82
	v_lshrrev_b32_e32 v13, 23, v13
	v_add_lshl_u32 v13, v82, v13, 7
	v_and_b32_e32 v13, 0xffff0000, v13
	v_add_u32_e32 v83, v20, v13
	ds_read2_b64 v[84:87], v83 offset0:32 offset1:48
	ds_read2_b64 v[88:91], v83 offset1:16
	ds_read2_b64 v[92:95], v83 offset0:64 offset1:80
	ds_read2_b64 v[96:99], v83 offset0:96 offset1:112
	ds_read2_b64 v[100:103], v83 offset0:128 offset1:144
	ds_read2_b64 v[104:107], v83 offset0:160 offset1:176
	ds_read2_b64 v[108:111], v83 offset0:192 offset1:208
	ds_read2_b64 v[112:115], v83 offset0:224 offset1:240
	v_cmp_lt_i32_e64 s[12:13], s5, v82
	s_or_b64 s[80:81], s[12:13], s[80:81]
	s_waitcnt lgkmcnt(0)
	v_pk_mul_f32 v[132:133], v[90:91], v[244:245] op_sel:[1,1] op_sel_hi:[1,0]
	v_pk_mul_f32 v[136:137], v[94:95], v[244:245] op_sel:[1,1] op_sel_hi:[1,0]
	v_pk_mul_f32 v[134:135], v[84:85], v[246:247] op_sel:[1,1] op_sel_hi:[1,0]
	v_pk_mul_f32 v[138:139], v[96:97], v[246:247] op_sel:[1,1] op_sel_hi:[1,0]
	v_pk_fma_f32 v[90:91], v[90:91], v[244:245], v[132:133] op_sel_hi:[0,1,1] neg_lo:[0,0,1]
	v_pk_fma_f32 v[94:95], v[94:95], v[244:245], v[136:137] op_sel_hi:[0,1,1] neg_lo:[0,0,1]
	v_pk_mul_f32 v[132:133], v[86:87], v[248:249] op_sel:[1,1] op_sel_hi:[1,0]
	v_pk_mul_f32 v[136:137], v[98:99], v[248:249] op_sel:[1,1] op_sel_hi:[1,0]
	v_pk_fma_f32 v[84:85], v[84:85], v[246:247], v[134:135] op_sel_hi:[0,1,1] neg_lo:[0,0,1]
	v_pk_fma_f32 v[96:97], v[96:97], v[246:247], v[138:139] op_sel_hi:[0,1,1] neg_lo:[0,0,1]
	v_pk_fma_f32 v[86:87], v[86:87], v[248:249], v[132:133] op_sel_hi:[0,1,1] neg_lo:[0,0,1]
	v_pk_fma_f32 v[98:99], v[98:99], v[248:249], v[136:137] op_sel_hi:[0,1,1] neg_lo:[0,0,1]
	v_pk_add_f32 v[116:117], v[88:89], v[84:85]
	v_pk_add_f32 v[124:125], v[92:93], v[96:97]
	v_pk_add_f32 v[120:121], v[90:91], v[86:87]
	v_pk_add_f32 v[128:129], v[94:95], v[98:99]
	v_pk_add_f32 v[118:119], v[88:89], v[84:85] neg_lo:[0,1] neg_hi:[0,1]
	v_pk_add_f32 v[126:127], v[92:93], v[96:97] neg_lo:[0,1] neg_hi:[0,1]
	v_pk_add_f32 v[122:123], v[90:91], v[86:87] neg_lo:[0,1] neg_hi:[0,1]
	v_pk_add_f32 v[130:131], v[94:95], v[98:99] neg_lo:[0,1] neg_hi:[0,1]
	v_pk_add_f32 v[88:89], v[116:117], v[120:121]
	v_pk_add_f32 v[92:93], v[124:125], v[128:129]
	v_pk_add_f32 v[84:85], v[116:117], v[120:121] neg_lo:[0,1] neg_hi:[0,1]
	v_pk_add_f32 v[96:97], v[124:125], v[128:129] neg_lo:[0,1] neg_hi:[0,1]
	v_pk_add_f32 v[90:91], v[118:119], v[122:123] op_sel:[0,1] op_sel_hi:[1,0] neg_lo:[0,1]
	v_pk_add_f32 v[94:95], v[126:127], v[130:131] op_sel:[0,1] op_sel_hi:[1,0] neg_lo:[0,1]
	v_pk_add_f32 v[86:87], v[118:119], v[122:123] op_sel:[0,1] op_sel_hi:[1,0] neg_hi:[0,1]
	v_pk_add_f32 v[98:99], v[126:127], v[130:131] op_sel:[0,1] op_sel_hi:[1,0] neg_hi:[0,1]
	v_pk_mul_f32 v[132:133], v[102:103], v[244:245] op_sel:[1,1] op_sel_hi:[1,0]
	v_pk_mul_f32 v[136:137], v[110:111], v[244:245] op_sel:[1,1] op_sel_hi:[1,0]
	v_pk_mul_f32 v[134:135], v[104:105], v[246:247] op_sel:[1,1] op_sel_hi:[1,0]
	v_pk_mul_f32 v[138:139], v[112:113], v[246:247] op_sel:[1,1] op_sel_hi:[1,0]
	v_pk_fma_f32 v[102:103], v[102:103], v[244:245], v[132:133] op_sel_hi:[0,1,1] neg_lo:[0,0,1]
	v_pk_fma_f32 v[110:111], v[110:111], v[244:245], v[136:137] op_sel_hi:[0,1,1] neg_lo:[0,0,1]
	v_pk_mul_f32 v[132:133], v[106:107], v[248:249] op_sel:[1,1] op_sel_hi:[1,0]
	v_pk_mul_f32 v[136:137], v[114:115], v[248:249] op_sel:[1,1] op_sel_hi:[1,0]
	v_pk_fma_f32 v[104:105], v[104:105], v[246:247], v[134:135] op_sel_hi:[0,1,1] neg_lo:[0,0,1]
	v_pk_fma_f32 v[112:113], v[112:113], v[246:247], v[138:139] op_sel_hi:[0,1,1] neg_lo:[0,0,1]
	v_pk_fma_f32 v[106:107], v[106:107], v[248:249], v[132:133] op_sel_hi:[0,1,1] neg_lo:[0,0,1]
	v_pk_fma_f32 v[114:115], v[114:115], v[248:249], v[136:137] op_sel_hi:[0,1,1] neg_lo:[0,0,1]
	v_pk_add_f32 v[116:117], v[100:101], v[104:105]
	v_pk_add_f32 v[124:125], v[108:109], v[112:113]
	v_pk_add_f32 v[120:121], v[102:103], v[106:107]
	v_pk_add_f32 v[128:129], v[110:111], v[114:115]
	v_pk_add_f32 v[118:119], v[100:101], v[104:105] neg_lo:[0,1] neg_hi:[0,1]
; DI float2 twid(float r) { return float2{__builtin_amdgcn_cosf(r), -__builtin_amdgcn_sinf(r)}; }
; DI void bfly_inv(float2 s0, float2 s1, float2 s2, float2 s3, float r, float2& o0, float2& o1, float2& o2, float2& o3) {
;   float2 w1 = twid(r), w2 = cmul(w1, w1), w3 = cmul(w2, w1);
;   float2 c0 = s0, c1 = cmulc(s1, w1), c2 = cmulc(s2, w2), c3 = cmulc(s3, w3);
;   float2 t0 = {c0.x + c2.x, c0.y + c2.y}, t1 = {c0.x - c2.x, c0.y - c2.y}, t2 = {c1.x + c3.x, c1.y + c3.y}, t3 = {c1.x - c3.x, c1.y - c3.y};
;   o0 = float2{t0.x + t2.x, t0.y + t2.y}; o2 = float2{t0.x - t2.x, t0.y - t2.y}; o1 = float2{t1.x - t3.y, t1.y + t3.x}; o3 = float2{t1.x + t3.y, t1.y - t3.x};
;     ...
;     for (int q2 = 0; q2 < 4; ++q2) bfly_inv(x[0][q2], x[1][q2], x[2][q2], x[3][q2], (float)(jp + q2 * Q2) * invM1, x[0][q2], x[1][q2], x[2][q2], x[3][q2]);
; #pragma unroll
;     for (int q1 = 0; q1 < 4; ++q1)
; #pragma unroll
;       for (int q2 = 0; q2 < 4; ++q2) z[base + q1 * Q1 + q2 * Q2] = x[q1][q2]; }
;   __syncthreads();
	v_pk_add_f32 v[126:127], v[108:109], v[112:113] neg_lo:[0,1] neg_hi:[0,1]
	v_pk_add_f32 v[122:123], v[102:103], v[106:107] neg_lo:[0,1] neg_hi:[0,1]
	v_pk_add_f32 v[130:131], v[110:111], v[114:115] neg_lo:[0,1] neg_hi:[0,1]
	v_pk_add_f32 v[100:101], v[116:117], v[120:121]
	v_pk_add_f32 v[108:109], v[124:125], v[128:129]
	v_pk_add_f32 v[104:105], v[116:117], v[120:121] neg_lo:[0,1] neg_hi:[0,1]
	v_pk_add_f32 v[112:113], v[124:125], v[128:129] neg_lo:[0,1] neg_hi:[0,1]
	v_pk_add_f32 v[102:103], v[118:119], v[122:123] op_sel:[0,1] op_sel_hi:[1,0] neg_lo:[0,1]
	v_pk_add_f32 v[110:111], v[126:127], v[130:131] op_sel:[0,1] op_sel_hi:[1,0] neg_lo:[0,1]
	v_pk_add_f32 v[106:107], v[118:119], v[122:123] op_sel:[0,1] op_sel_hi:[1,0] neg_hi:[0,1]
	v_pk_add_f32 v[114:115], v[126:127], v[130:131] op_sel:[0,1] op_sel_hi:[1,0] neg_hi:[0,1]
	v_pk_mul_f32 v[132:133], v[92:93], v[218:219] op_sel:[1,1] op_sel_hi:[1,0]
	v_pk_mul_f32 v[136:137], v[94:95], v[224:225] op_sel:[1,1] op_sel_hi:[1,0]
	v_pk_mul_f32 v[134:135], v[100:101], v[220:221] op_sel:[1,1] op_sel_hi:[1,0]
	v_pk_mul_f32 v[138:139], v[102:103], v[226:227] op_sel:[1,1] op_sel_hi:[1,0]
	v_pk_fma_f32 v[92:93], v[92:93], v[218:219], v[132:133] op_sel_hi:[0,1,1] neg_lo:[0,0,1]
	v_pk_fma_f32 v[94:95], v[94:95], v[224:225], v[136:137] op_sel_hi:[0,1,1] neg_lo:[0,0,1]
	v_pk_mul_f32 v[132:133], v[108:109], v[222:223] op_sel:[1,1] op_sel_hi:[1,0]
	v_pk_mul_f32 v[136:137], v[110:111], v[228:229] op_sel:[1,1] op_sel_hi:[1,0]
	v_pk_fma_f32 v[100:101], v[100:101], v[220:221], v[134:135] op_sel_hi:[0,1,1] neg_lo:[0,0,1]
	v_pk_fma_f32 v[102:103], v[102:103], v[226:227], v[138:139] op_sel_hi:[0,1,1] neg_lo:[0,0,1]
	v_pk_fma_f32 v[108:109], v[108:109], v[222:223], v[132:133] op_sel_hi:[0,1,1] neg_lo:[0,0,1]
	v_pk_fma_f32 v[110:111], v[110:111], v[228:229], v[136:137] op_sel_hi:[0,1,1] neg_lo:[0,0,1]
	v_pk_add_f32 v[116:117], v[88:89], v[100:101]
	v_pk_add_f32 v[124:125], v[90:91], v[102:103]
	v_pk_add_f32 v[120:121], v[92:93], v[108:109]
	v_pk_add_f32 v[128:129], v[94:95], v[110:111]
	v_pk_add_f32 v[118:119], v[88:89], v[100:101] neg_lo:[0,1] neg_hi:[0,1]
	v_pk_add_f32 v[126:127], v[90:91], v[102:103] neg_lo:[0,1] neg_hi:[0,1]
	v_pk_add_f32 v[122:123], v[92:93], v[108:109] neg_lo:[0,1] neg_hi:[0,1]
	v_pk_add_f32 v[130:131], v[94:95], v[110:111] neg_lo:[0,1] neg_hi:[0,1]
	v_pk_add_f32 v[88:89], v[116:117], v[120:121]
	v_pk_add_f32 v[90:91], v[124:125], v[128:129]
	v_pk_add_f32 v[100:101], v[116:117], v[120:121] neg_lo:[0,1] neg_hi:[0,1]
	v_pk_add_f32 v[102:103], v[124:125], v[128:129] neg_lo:[0,1] neg_hi:[0,1]
	v_pk_add_f32 v[92:93], v[118:119], v[122:123] op_sel:[0,1] op_sel_hi:[1,0] neg_lo:[0,1]
	v_pk_add_f32 v[94:95], v[126:127], v[130:131] op_sel:[0,1] op_sel_hi:[1,0] neg_lo:[0,1]
	v_pk_add_f32 v[108:109], v[118:119], v[122:123] op_sel:[0,1] op_sel_hi:[1,0] neg_hi:[0,1]
	v_pk_add_f32 v[110:111], v[126:127], v[130:131] op_sel:[0,1] op_sel_hi:[1,0] neg_hi:[0,1]
	v_pk_mul_f32 v[132:133], v[96:97], v[230:231] op_sel:[1,1] op_sel_hi:[1,0]
	v_pk_mul_f32 v[136:137], v[98:99], v[236:237] op_sel:[1,1] op_sel_hi:[1,0]
	v_pk_mul_f32 v[134:135], v[104:105], v[232:233] op_sel:[1,1] op_sel_hi:[1,0]
	v_pk_mul_f32 v[138:139], v[106:107], v[238:239] op_sel:[1,1] op_sel_hi:[1,0]
	v_pk_fma_f32 v[96:97], v[96:97], v[230:231], v[132:133] op_sel_hi:[0,1,1] neg_lo:[0,0,1]
	v_pk_fma_f32 v[98:99], v[98:99], v[236:237], v[136:137] op_sel_hi:[0,1,1] neg_lo:[0,0,1]
	v_pk_mul_f32 v[132:133], v[112:113], v[234:235] op_sel:[1,1] op_sel_hi:[1,0]
	v_pk_mul_f32 v[136:137], v[114:115], v[242:243] op_sel:[1,1] op_sel_hi:[1,0]
	v_pk_fma_f32 v[104:105], v[104:105], v[232:233], v[134:135] op_sel_hi:[0,1,1] neg_lo:[0,0,1]
	v_pk_fma_f32 v[106:107], v[106:107], v[238:239], v[138:139] op_sel_hi:[0,1,1] neg_lo:[0,0,1]
	v_pk_fma_f32 v[112:113], v[112:113], v[234:235], v[132:133] op_sel_hi:[0,1,1] neg_lo:[0,0,1]
	v_pk_fma_f32 v[114:115], v[114:115], v[242:243], v[136:137] op_sel_hi:[0,1,1] neg_lo:[0,0,1]
	v_pk_add_f32 v[116:117], v[84:85], v[104:105]
	v_pk_add_f32 v[124:125], v[86:87], v[106:107]
	v_pk_add_f32 v[120:121], v[96:97], v[112:113]
	v_pk_add_f32 v[128:129], v[98:99], v[114:115]
	v_pk_add_f32 v[118:119], v[84:85], v[104:105] neg_lo:[0,1] neg_hi:[0,1]
	v_pk_add_f32 v[126:127], v[86:87], v[106:107] neg_lo:[0,1] neg_hi:[0,1]
	v_pk_add_f32 v[122:123], v[96:97], v[112:113] neg_lo:[0,1] neg_hi:[0,1]
	v_pk_add_f32 v[130:131], v[98:99], v[114:115] neg_lo:[0,1] neg_hi:[0,1]
	v_pk_add_f32 v[84:85], v[116:117], v[120:121]
	v_pk_add_f32 v[86:87], v[124:125], v[128:129]
	v_pk_add_f32 v[104:105], v[116:117], v[120:121] neg_lo:[0,1] neg_hi:[0,1]
	v_pk_add_f32 v[106:107], v[124:125], v[128:129] neg_lo:[0,1] neg_hi:[0,1]
	v_pk_add_f32 v[96:97], v[118:119], v[122:123] op_sel:[0,1] op_sel_hi:[1,0] neg_lo:[0,1]
	v_pk_add_f32 v[98:99], v[126:127], v[130:131] op_sel:[0,1] op_sel_hi:[1,0] neg_lo:[0,1]
	v_pk_add_f32 v[112:113], v[118:119], v[122:123] op_sel:[0,1] op_sel_hi:[1,0] neg_hi:[0,1]
	v_pk_add_f32 v[114:115], v[126:127], v[130:131] op_sel:[0,1] op_sel_hi:[1,0] neg_hi:[0,1]
	s_nop 0
	ds_write2_b64 v83, v[88:89], v[90:91] offset1:16
	ds_write2_b64 v83, v[84:85], v[86:87] offset0:32 offset1:48
	ds_write2_b64 v83, v[92:93], v[94:95] offset0:64 offset1:80
	ds_write2_b64 v83, v[96:97], v[98:99] offset0:96 offset1:112
	ds_write2_b64 v83, v[100:101], v[102:103] offset0:128 offset1:144
	ds_write2_b64 v83, v[104:105], v[106:107] offset0:160 offset1:176
	ds_write2_b64 v83, v[108:109], v[110:111] offset0:192 offset1:208
	ds_write2_b64 v83, v[112:113], v[114:115] offset0:224 offset1:240
	v_add_u32_e32 v13, 0x200, v82
	v_mov_b32_e32 v82, v13
	s_andn2_b64 exec, exec, s[80:81]
	s_cbranch_execnz .LBB0_1618
; DI float2 twid(float r) { return float2{__builtin_amdgcn_cosf(r), -__builtin_amdgcn_sinf(r)}; }
; DI void bfly_inv(float2 s0, float2 s1, float2 s2, float2 s3, float r, float2& o0, float2& o1, float2& o2, float2& o3) {
;   float2 w1 = twid(r), w2 = cmul(w1, w1), w3 = cmul(w2, w1);
;   float2 c0 = s0, c1 = cmulc(s1, w1), c2 = cmulc(s2, w2), c3 = cmulc(s3, w3);
;   const int lq1 = lq2 + 2, Q1 = 1 << lq1, Q2 = 1 << lq2; const float invM1 = 1.f / (float)(4 << lq1), invM2 = 1.f / (float)(4 << lq2);
;   for (int gg = tid; gg < NBT * (N / 16); gg += NTHR) { const int g = gg & (N / 16 - 1); float2* z = z0 + (gg / (N / 16)) * N; const int jp = g & (Q2 - 1), base = ((g >> lq2) << (lq2 + 4)) + jp; float2 x[4][4];
; #pragma unroll
;     for (int q1 = 0; q1 < 4; ++q1)
; #pragma unroll
;       for (int q2 = 0; q2 < 4; ++q2) x[q1][q2] = z[base + q1 * Q1 + q2 * Q2];
; #pragma unroll
;     for (int q1 = 0; q1 < 4; ++q1) bfly_inv(x[q1][0], x[q1][1], x[q1][2], x[q1][3], (float)jp * invM2, x[q1][0], x[q1][1], x[q1][2], x[q1][3]);
; #pragma unroll
;     for (int q2 = 0; q2 < 4; ++q2) bfly_inv(x[0][q2], x[1][q2], x[2][q2], x[3][q2], (float)(jp + q2 * Q2) * invM1, x[0][q2], x[1][q2], x[2][q2], x[3][q2]);
.LBB0_1619:
	s_or_b64 exec, exec, s[0:1]
	s_waitcnt lgkmcnt(0)
	s_barrier
	s_and_saveexec_b64 s[12:13], vcc
	s_cbranch_execz .LBB0_1622
	v_sin_f32_e32 v3, v81
	v_cos_f32_e32 v4, v81
	v_sin_f32_e32 v12, v78
	v_cos_f32_e32 v14, v78
	v_xor_b32_e32 v8, 0x80000000, v3
	v_mov_b32_e32 v2, v4
	v_mov_b32_e32 v6, v8
	v_mov_b32_e32 v7, v3
	v_mov_b32_e32 v5, v4
	v_mov_b32_e32 v9, v4
	v_pk_mul_f32 v[10:11], v[2:3], v[6:7]
	v_cvt_f32_u32_e32 v0, v0
	v_pk_fma_f32 v[6:7], v[4:5], v[8:9], v[10:11] op_sel_hi:[0,1,1] neg_lo:[0,0,1] neg_hi:[0,0,1]
	v_pk_fma_f32 v[8:9], v[4:5], v[8:9], v[10:11] op_sel_hi:[0,1,1]
	v_pk_mov_b32 v[10:11], v[6:7], v[8:9] op_sel:[1,0]
	v_mov_b32_e32 v16, v8
	v_mov_b32_e32 v17, v7
	v_pk_mul_f32 v[18:19], v[2:3], v[10:11] op_sel:[1,0]
	v_mul_f32_e64 v9, v14, -v12
	v_pk_fma_f32 v[10:11], v[4:5], v[16:17], v[18:19] op_sel_hi:[0,1,1]
	v_pk_fma_f32 v[16:17], v[4:5], v[16:17], v[18:19] op_sel_hi:[0,1,1] neg_lo:[0,0,1] neg_hi:[0,0,1]
	v_add_f32_e32 v18, v9, v9
	v_cvt_f32_u32_e32 v9, v77
	v_mul_f32_e32 v6, v12, v12
	v_fma_f32 v22, v14, v14, -v6
	v_mul_f32_e32 v0, 0x39800000, v0
	v_mul_f32_e32 v6, 0x39800000, v9
	v_sin_f32_e32 v25, v6
	v_cos_f32_e32 v27, v6
	v_cvt_f32_u32_e32 v9, v76
	v_mul_f32_e32 v6, v12, v22
	v_fma_f32 v60, v14, v18, -v6
	v_mul_f32_e32 v6, v25, v25
	v_fma_f32 v28, v27, v27, -v6
	v_mul_f32_e64 v6, v27, -v25
	v_sin_f32_e32 v40, v0
	v_add_f32_e32 v30, v6, v6
	v_mul_f32_e32 v6, 0x39800000, v9
	v_cos_f32_e32 v42, v0
	v_sin_f32_e32 v33, v6
	v_cos_f32_e32 v35, v6
	v_xor_b32_e32 v43, 0x80000000, v40
	v_mul_f32_e32 v6, v25, v28
	v_mov_b32_e32 v41, v42
	v_mov_b32_e32 v44, v40
	v_mov_b32_e32 v45, v43
	v_fma_f32 v26, v27, v30, -v6
	v_mul_f32_e32 v6, v33, v33
	v_pk_mul_f32 v[46:47], v[40:41], v[44:45]
	v_fma_f32 v36, v35, v35, -v6
	v_mul_f32_e64 v6, v35, -v33
	v_pk_fma_f32 v[44:45], v[42:43], v[42:43], v[46:47] op_sel_hi:[0,1,1] neg_lo:[0,0,1] neg_hi:[0,0,1]
	v_pk_fma_f32 v[62:63], v[42:43], v[42:43], v[46:47] op_sel_hi:[0,1,1]
	v_add_f32_e32 v38, v6, v6
	v_pk_mov_b32 v[48:49], v[62:63], v[44:45] op_sel:[1,0]
	v_mul_f32_e32 v21, v12, v18
	v_mul_f32_e32 v24, v25, v30
	v_mul_f32_e32 v32, v33, v38
	v_mul_f32_e32 v0, v33, v36
	v_mov_b32_e32 v46, v44
	v_mov_b32_e32 v47, v63
	v_pk_mul_f32 v[48:49], v[40:41], v[48:49] op_sel_hi:[0,1]
	v_add3_u32 v20, 16, v79, v80
	v_fmac_f32_e32 v21, v14, v22
	v_fmac_f32_e32 v24, v27, v28
	v_fmac_f32_e32 v32, v35, v36
	v_fma_f32 v34, v35, v38, -v0
	v_pk_fma_f32 v[58:59], v[42:43], v[46:47], v[48:49] op_sel_hi:[0,1,1]
	v_pk_fma_f32 v[46:47], v[42:43], v[46:47], v[48:49] op_sel_hi:[0,1,1] neg_lo:[0,0,1] neg_hi:[0,0,1]
	v_mov_b32_e32 v19, v12
	v_mov_b32_e32 v17, v11
	v_mov_b32_e32 v46, v58
	v_mov_b32_e32 v9, v8
	v_mov_b32_e32 v29, v28
	v_mov_b32_e32 v31, v30
	v_pk_mov_b32 v[48:49], v[26:27], v[24:25] op_sel:[1,0]
	v_pk_mov_b32 v[50:51], v[24:25], v[26:27] op_sel:[1,0]
	v_mov_b32_e32 v37, v36
	v_pk_mov_b32 v[52:53], v[34:35], v[32:33] op_sel:[1,0]
	v_pk_mov_b32 v[54:55], v[32:33], v[34:35] op_sel:[1,0]
	v_mov_b32_e32 v56, v4
	v_mov_b32_e32 v57, v16
	v_mov_b32_e32 v10, v3
	v_pk_mov_b32 v[58:59], v[62:63], v[58:59] op_sel:[1,0]
	v_mov_b32_e32 v45, v47
	v_mov_b32_e32 v43, v44
	v_mov_b32_e32 v41, v63
	v_mov_b32_e32 v61, v16
	v_mov_b32_e32 v62, v3
	v_mov_b32_e32 v63, v3
	v_mov_b32_e32 v6, v7
	v_mov_b32_e32 v64, v4
	v_mov_b32_e32 v65, v11
	v_mov_b32_e32 v66, v3
	v_mov_b32_e32 v67, v16
	v_mov_b32_e32 v68, v11
	v_mov_b32_e32 v69, v11
	v_mov_b32_e32 v70, v16
	v_mov_b32_e32 v71, v16
	v_mov_b32_e32 v23, v14
	v_pk_mov_b32 v[72:73], v[20:21], v[18:19] op_sel:[1,0]
	v_mov_b32_e32 v39, v38
	s_mov_b64 s[0:1], 0
	v_and_b32_e32 v241, 0xff, v75
	v_add_u32_e32 v250, 0x0, v241
	v_cvt_f32_u32_e32 v250, v250
	v_mul_f32_e32 v250, 0x39800000, v250
	v_cos_f32_e32 v218, v250
	v_sin_f32_e32 v219, v250
	s_nop 1
	v_xor_b32_e32 v219, 0x80000000, v219
	s_nop 0
	v_pk_mul_f32 v[124:125], v[218:219], v[218:219] op_sel:[1,1] op_sel_hi:[1,0]
	s_nop 0
	v_pk_fma_f32 v[220:221], v[218:219], v[218:219], v[124:125] op_sel_hi:[0,1,1] neg_lo:[0,0,1]
	s_nop 0
	v_pk_mul_f32 v[124:125], v[220:221], v[218:219] op_sel:[1,1] op_sel_hi:[1,0]
	s_nop 0
	v_pk_fma_f32 v[222:223], v[220:221], v[218:219], v[124:125] op_sel_hi:[0,1,1] neg_lo:[0,0,1]
	s_nop 0
	v_xor_b32_e32 v219, 0x80000000, v219
	v_xor_b32_e32 v221, 0x80000000, v221
	v_xor_b32_e32 v223, 0x80000000, v223
	v_add_u32_e32 v250, 0x100, v241
	v_cvt_f32_u32_e32 v250, v250
	v_mul_f32_e32 v250, 0x39800000, v250
	v_cos_f32_e32 v224, v250
	v_sin_f32_e32 v225, v250
	s_nop 1
	v_xor_b32_e32 v225, 0x80000000, v225
	s_nop 0
	v_pk_mul_f32 v[124:125], v[224:225], v[224:225] op_sel:[1,1] op_sel_hi:[1,0]
	s_nop 0
	v_pk_fma_f32 v[226:227], v[224:225], v[224:225], v[124:125] op_sel_hi:[0,1,1] neg_lo:[0,0,1]
	s_nop 0
	v_pk_mul_f32 v[124:125], v[226:227], v[224:225] op_sel:[1,1] op_sel_hi:[1,0]
	s_nop 0
	v_pk_fma_f32 v[228:229], v[226:227], v[224:225], v[124:125] op_sel_hi:[0,1,1] neg_lo:[0,0,1]
	s_nop 0
	v_xor_b32_e32 v225, 0x80000000, v225
	v_xor_b32_e32 v227, 0x80000000, v227
	v_xor_b32_e32 v229, 0x80000000, v229
	v_add_u32_e32 v250, 0x200, v241
	v_cvt_f32_u32_e32 v250, v250
	v_mul_f32_e32 v250, 0x39800000, v250
	v_cos_f32_e32 v230, v250
	v_sin_f32_e32 v231, v250
	s_nop 1
	v_xor_b32_e32 v231, 0x80000000, v231
	s_nop 0
	v_pk_mul_f32 v[124:125], v[230:231], v[230:231] op_sel:[1,1] op_sel_hi:[1,0]
	s_nop 0
	v_pk_fma_f32 v[232:233], v[230:231], v[230:231], v[124:125] op_sel_hi:[0,1,1] neg_lo:[0,0,1]
	s_nop 0
	v_pk_mul_f32 v[124:125], v[232:233], v[230:231] op_sel:[1,1] op_sel_hi:[1,0]
	s_nop 0
	v_pk_fma_f32 v[234:235], v[232:233], v[230:231], v[124:125] op_sel_hi:[0,1,1] neg_lo:[0,0,1]
	s_nop 0
	v_xor_b32_e32 v231, 0x80000000, v231
; DI float2 twid(float r) { return float2{__builtin_amdgcn_cosf(r), -__builtin_amdgcn_sinf(r)}; }
; DI void bfly_inv(float2 s0, float2 s1, float2 s2, float2 s3, float r, float2& o0, float2& o1, float2& o2, float2& o3) {
;   float2 w1 = twid(r), w2 = cmul(w1, w1), w3 = cmul(w2, w1);
;   float2 c0 = s0, c1 = cmulc(s1, w1), c2 = cmulc(s2, w2), c3 = cmulc(s3, w3);
;   float2 t0 = {c0.x + c2.x, c0.y + c2.y}, t1 = {c0.x - c2.x, c0.y - c2.y}, t2 = {c1.x + c3.x, c1.y + c3.y}, t3 = {c1.x - c3.x, c1.y - c3.y};
;   o0 = float2{t0.x + t2.x, t0.y + t2.y}; o2 = float2{t0.x - t2.x, t0.y - t2.y}; o1 = float2{t1.x - t3.y, t1.y + t3.x}; o3 = float2{t1.x + t3.y, t1.y - t3.x};
;     ...
;   for (int gg = tid; gg < NBT * (N / 16); gg += NTHR) { const int g = gg & (N / 16 - 1); float2* z = z0 + (gg / (N / 16)) * N; const int jp = g & (Q2 - 1), base = ((g >> lq2) << (lq2 + 4)) + jp; float2 x[4][4];
; #pragma unroll
;     for (int q1 = 0; q1 < 4; ++q1)
; #pragma unroll
;       for (int q2 = 0; q2 < 4; ++q2) x[q1][q2] = z[base + q1 * Q1 + q2 * Q2];
; #pragma unroll
;     for (int q1 = 0; q1 < 4; ++q1) bfly_inv(x[q1][0], x[q1][1], x[q1][2], x[q1][3], (float)jp * invM2, x[q1][0], x[q1][1], x[q1][2], x[q1][3]);
; #pragma unroll
;     for (int q2 = 0; q2 < 4; ++q2) bfly_inv(x[0][q2], x[1][q2], x[2][q2], x[3][q2], (float)(jp + q2 * Q2) * invM1, x[0][q2], x[1][q2], x[2][q2], x[3][q2]);
	v_xor_b32_e32 v233, 0x80000000, v233
	v_xor_b32_e32 v235, 0x80000000, v235
	v_add_u32_e32 v250, 0x300, v241
	v_cvt_f32_u32_e32 v250, v250
	v_mul_f32_e32 v250, 0x39800000, v250
	v_cos_f32_e32 v236, v250
	v_sin_f32_e32 v237, v250
	s_nop 1
	v_xor_b32_e32 v237, 0x80000000, v237
	s_nop 0
	v_pk_mul_f32 v[124:125], v[236:237], v[236:237] op_sel:[1,1] op_sel_hi:[1,0]
	s_nop 0
	v_pk_fma_f32 v[238:239], v[236:237], v[236:237], v[124:125] op_sel_hi:[0,1,1] neg_lo:[0,0,1]
	s_nop 0
	v_pk_mul_f32 v[124:125], v[238:239], v[236:237] op_sel:[1,1] op_sel_hi:[1,0]
	s_nop 0
	v_pk_fma_f32 v[242:243], v[238:239], v[236:237], v[124:125] op_sel_hi:[0,1,1] neg_lo:[0,0,1]
	s_nop 0
	v_xor_b32_e32 v237, 0x80000000, v237
	v_xor_b32_e32 v239, 0x80000000, v239
	v_xor_b32_e32 v243, 0x80000000, v243
	v_cvt_f32_u32_e32 v250, v241
	v_mul_f32_e32 v250, 0x3a800000, v250
	v_cos_f32_e32 v244, v250
	v_sin_f32_e32 v245, v250
	s_nop 1
	v_xor_b32_e32 v245, 0x80000000, v245
	s_nop 0
	v_pk_mul_f32 v[124:125], v[244:245], v[244:245] op_sel:[1,1] op_sel_hi:[1,0]
	s_nop 0
	v_pk_fma_f32 v[246:247], v[244:245], v[244:245], v[124:125] op_sel_hi:[0,1,1] neg_lo:[0,0,1]
	s_nop 0
	v_pk_mul_f32 v[124:125], v[246:247], v[244:245] op_sel:[1,1] op_sel_hi:[1,0]
	s_nop 0
	v_pk_fma_f32 v[248:249], v[246:247], v[244:245], v[124:125] op_sel_hi:[0,1,1] neg_lo:[0,0,1]
	s_nop 0
	v_xor_b32_e32 v245, 0x80000000, v245
	v_xor_b32_e32 v247, 0x80000000, v247
	v_xor_b32_e32 v249, 0x80000000, v249
.LBB0_1621:
	v_ashrrev_i32_e32 v0, 31, v75
	v_lshrrev_b32_e32 v0, 23, v0
	v_add_lshl_u32 v0, v75, v0, 7
	v_and_b32_e32 v0, 0xffff0000, v0
	v_add_u32_e32 v176, v20, v0
	ds_read2st64_b64 v[76:79], v176 offset0:8 offset1:12
	ds_read2st64_b64 v[80:83], v176 offset1:4
	ds_read2st64_b64 v[84:87], v176 offset0:16 offset1:20
	ds_read2st64_b64 v[88:91], v176 offset0:24 offset1:28
	ds_read2st64_b64 v[92:95], v176 offset0:32 offset1:36
	ds_read2st64_b64 v[96:99], v176 offset0:40 offset1:44
	ds_read2st64_b64 v[100:103], v176 offset0:48 offset1:52
	ds_read2st64_b64 v[104:107], v176 offset0:56 offset1:60
	v_cmp_lt_i32_e32 vcc, s5, v75
	s_or_b64 s[0:1], vcc, s[0:1]
	s_waitcnt lgkmcnt(0)
	v_pk_mul_f32 v[124:125], v[82:83], v[244:245] op_sel:[1,1] op_sel_hi:[1,0]
	v_pk_mul_f32 v[128:129], v[86:87], v[244:245] op_sel:[1,1] op_sel_hi:[1,0]
	v_pk_mul_f32 v[126:127], v[76:77], v[246:247] op_sel:[1,1] op_sel_hi:[1,0]
	v_pk_mul_f32 v[130:131], v[88:89], v[246:247] op_sel:[1,1] op_sel_hi:[1,0]
	v_pk_fma_f32 v[82:83], v[82:83], v[244:245], v[124:125] op_sel_hi:[0,1,1] neg_lo:[0,0,1]
	v_pk_fma_f32 v[86:87], v[86:87], v[244:245], v[128:129] op_sel_hi:[0,1,1] neg_lo:[0,0,1]
	v_pk_mul_f32 v[124:125], v[78:79], v[248:249] op_sel:[1,1] op_sel_hi:[1,0]
	v_pk_mul_f32 v[128:129], v[90:91], v[248:249] op_sel:[1,1] op_sel_hi:[1,0]
	v_pk_fma_f32 v[76:77], v[76:77], v[246:247], v[126:127] op_sel_hi:[0,1,1] neg_lo:[0,0,1]
	v_pk_fma_f32 v[88:89], v[88:89], v[246:247], v[130:131] op_sel_hi:[0,1,1] neg_lo:[0,0,1]
	v_pk_fma_f32 v[78:79], v[78:79], v[248:249], v[124:125] op_sel_hi:[0,1,1] neg_lo:[0,0,1]
	v_pk_fma_f32 v[90:91], v[90:91], v[248:249], v[128:129] op_sel_hi:[0,1,1] neg_lo:[0,0,1]
	v_pk_add_f32 v[108:109], v[80:81], v[76:77]
	v_pk_add_f32 v[116:117], v[84:85], v[88:89]
	v_pk_add_f32 v[112:113], v[82:83], v[78:79]
	v_pk_add_f32 v[120:121], v[86:87], v[90:91]
	v_pk_add_f32 v[110:111], v[80:81], v[76:77] neg_lo:[0,1] neg_hi:[0,1]
	v_pk_add_f32 v[118:119], v[84:85], v[88:89] neg_lo:[0,1] neg_hi:[0,1]
	v_pk_add_f32 v[114:115], v[82:83], v[78:79] neg_lo:[0,1] neg_hi:[0,1]
	v_pk_add_f32 v[122:123], v[86:87], v[90:91] neg_lo:[0,1] neg_hi:[0,1]
	v_pk_add_f32 v[80:81], v[108:109], v[112:113]
	v_pk_add_f32 v[84:85], v[116:117], v[120:121]
	v_pk_add_f32 v[76:77], v[108:109], v[112:113] neg_lo:[0,1] neg_hi:[0,1]
	v_pk_add_f32 v[88:89], v[116:117], v[120:121] neg_lo:[0,1] neg_hi:[0,1]
	v_pk_add_f32 v[82:83], v[110:111], v[114:115] op_sel:[0,1] op_sel_hi:[1,0] neg_lo:[0,1]
	v_pk_add_f32 v[86:87], v[118:119], v[122:123] op_sel:[0,1] op_sel_hi:[1,0] neg_lo:[0,1]
	v_pk_add_f32 v[78:79], v[110:111], v[114:115] op_sel:[0,1] op_sel_hi:[1,0] neg_hi:[0,1]
	v_pk_add_f32 v[90:91], v[118:119], v[122:123] op_sel:[0,1] op_sel_hi:[1,0] neg_hi:[0,1]
	v_pk_mul_f32 v[124:125], v[94:95], v[244:245] op_sel:[1,1] op_sel_hi:[1,0]
	v_pk_mul_f32 v[128:129], v[102:103], v[244:245] op_sel:[1,1] op_sel_hi:[1,0]
	v_pk_mul_f32 v[126:127], v[96:97], v[246:247] op_sel:[1,1] op_sel_hi:[1,0]
	v_pk_mul_f32 v[130:131], v[104:105], v[246:247] op_sel:[1,1] op_sel_hi:[1,0]
	v_pk_fma_f32 v[94:95], v[94:95], v[244:245], v[124:125] op_sel_hi:[0,1,1] neg_lo:[0,0,1]
	v_pk_fma_f32 v[102:103], v[102:103], v[244:245], v[128:129] op_sel_hi:[0,1,1] neg_lo:[0,0,1]
	v_pk_mul_f32 v[124:125], v[98:99], v[248:249] op_sel:[1,1] op_sel_hi:[1,0]
	v_pk_mul_f32 v[128:129], v[106:107], v[248:249] op_sel:[1,1] op_sel_hi:[1,0]
	v_pk_fma_f32 v[96:97], v[96:97], v[246:247], v[126:127] op_sel_hi:[0,1,1] neg_lo:[0,0,1]
	v_pk_fma_f32 v[104:105], v[104:105], v[246:247], v[130:131] op_sel_hi:[0,1,1] neg_lo:[0,0,1]
	v_pk_fma_f32 v[98:99], v[98:99], v[248:249], v[124:125] op_sel_hi:[0,1,1] neg_lo:[0,0,1]
	v_pk_fma_f32 v[106:107], v[106:107], v[248:249], v[128:129] op_sel_hi:[0,1,1] neg_lo:[0,0,1]
	v_pk_add_f32 v[108:109], v[92:93], v[96:97]
	v_pk_add_f32 v[116:117], v[100:101], v[104:105]
	v_pk_add_f32 v[112:113], v[94:95], v[98:99]
	v_pk_add_f32 v[120:121], v[102:103], v[106:107]
	v_pk_add_f32 v[110:111], v[92:93], v[96:97] neg_lo:[0,1] neg_hi:[0,1]
	v_pk_add_f32 v[118:119], v[100:101], v[104:105] neg_lo:[0,1] neg_hi:[0,1]
;     ...
;     for (int q2 = 0; q2 < 4; ++q2) bfly_inv(x[0][q2], x[1][q2], x[2][q2], x[3][q2], (float)(jp + q2 * Q2) * invM1, x[0][q2], x[1][q2], x[2][q2], x[3][q2]);
; #pragma unroll
;     for (int q1 = 0; q1 < 4; ++q1)
; #pragma unroll
;       for (int q2 = 0; q2 < 4; ++q2) z[base + q1 * Q1 + q2 * Q2] = x[q1][q2]; }
;   __syncthreads();
	v_pk_add_f32 v[114:115], v[94:95], v[98:99] neg_lo:[0,1] neg_hi:[0,1]
	v_pk_add_f32 v[122:123], v[102:103], v[106:107] neg_lo:[0,1] neg_hi:[0,1]
	v_pk_add_f32 v[92:93], v[108:109], v[112:113]
	v_pk_add_f32 v[100:101], v[116:117], v[120:121]
	v_pk_add_f32 v[96:97], v[108:109], v[112:113] neg_lo:[0,1] neg_hi:[0,1]
	v_pk_add_f32 v[104:105], v[116:117], v[120:121] neg_lo:[0,1] neg_hi:[0,1]
	v_pk_add_f32 v[94:95], v[110:111], v[114:115] op_sel:[0,1] op_sel_hi:[1,0] neg_lo:[0,1]
	v_pk_add_f32 v[102:103], v[118:119], v[122:123] op_sel:[0,1] op_sel_hi:[1,0] neg_lo:[0,1]
	v_pk_add_f32 v[98:99], v[110:111], v[114:115] op_sel:[0,1] op_sel_hi:[1,0] neg_hi:[0,1]
	v_pk_add_f32 v[106:107], v[118:119], v[122:123] op_sel:[0,1] op_sel_hi:[1,0] neg_hi:[0,1]
	v_pk_mul_f32 v[124:125], v[84:85], v[218:219] op_sel:[1,1] op_sel_hi:[1,0]
	v_pk_mul_f32 v[128:129], v[86:87], v[224:225] op_sel:[1,1] op_sel_hi:[1,0]
	v_pk_mul_f32 v[126:127], v[92:93], v[220:221] op_sel:[1,1] op_sel_hi:[1,0]
	v_pk_mul_f32 v[130:131], v[94:95], v[226:227] op_sel:[1,1] op_sel_hi:[1,0]
	v_pk_fma_f32 v[84:85], v[84:85], v[218:219], v[124:125] op_sel_hi:[0,1,1] neg_lo:[0,0,1]
	v_pk_fma_f32 v[86:87], v[86:87], v[224:225], v[128:129] op_sel_hi:[0,1,1] neg_lo:[0,0,1]
	v_pk_mul_f32 v[124:125], v[100:101], v[222:223] op_sel:[1,1] op_sel_hi:[1,0]
	v_pk_mul_f32 v[128:129], v[102:103], v[228:229] op_sel:[1,1] op_sel_hi:[1,0]
	v_pk_fma_f32 v[92:93], v[92:93], v[220:221], v[126:127] op_sel_hi:[0,1,1] neg_lo:[0,0,1]
	v_pk_fma_f32 v[94:95], v[94:95], v[226:227], v[130:131] op_sel_hi:[0,1,1] neg_lo:[0,0,1]
	v_pk_fma_f32 v[100:101], v[100:101], v[222:223], v[124:125] op_sel_hi:[0,1,1] neg_lo:[0,0,1]
	v_pk_fma_f32 v[102:103], v[102:103], v[228:229], v[128:129] op_sel_hi:[0,1,1] neg_lo:[0,0,1]
	v_pk_add_f32 v[108:109], v[80:81], v[92:93]
	v_pk_add_f32 v[116:117], v[82:83], v[94:95]
	v_pk_add_f32 v[112:113], v[84:85], v[100:101]
	v_pk_add_f32 v[120:121], v[86:87], v[102:103]
	v_pk_add_f32 v[110:111], v[80:81], v[92:93] neg_lo:[0,1] neg_hi:[0,1]
	v_pk_add_f32 v[118:119], v[82:83], v[94:95] neg_lo:[0,1] neg_hi:[0,1]
	v_pk_add_f32 v[114:115], v[84:85], v[100:101] neg_lo:[0,1] neg_hi:[0,1]
	v_pk_add_f32 v[122:123], v[86:87], v[102:103] neg_lo:[0,1] neg_hi:[0,1]
	v_pk_add_f32 v[80:81], v[108:109], v[112:113]
	v_pk_add_f32 v[82:83], v[116:117], v[120:121]
	v_pk_add_f32 v[92:93], v[108:109], v[112:113] neg_lo:[0,1] neg_hi:[0,1]
	v_pk_add_f32 v[94:95], v[116:117], v[120:121] neg_lo:[0,1] neg_hi:[0,1]
	v_pk_add_f32 v[84:85], v[110:111], v[114:115] op_sel:[0,1] op_sel_hi:[1,0] neg_lo:[0,1]
	v_pk_add_f32 v[86:87], v[118:119], v[122:123] op_sel:[0,1] op_sel_hi:[1,0] neg_lo:[0,1]
	v_pk_add_f32 v[100:101], v[110:111], v[114:115] op_sel:[0,1] op_sel_hi:[1,0] neg_hi:[0,1]
	v_pk_add_f32 v[102:103], v[118:119], v[122:123] op_sel:[0,1] op_sel_hi:[1,0] neg_hi:[0,1]
	v_pk_mul_f32 v[124:125], v[88:89], v[230:231] op_sel:[1,1] op_sel_hi:[1,0]
	v_pk_mul_f32 v[128:129], v[90:91], v[236:237] op_sel:[1,1] op_sel_hi:[1,0]
	v_pk_mul_f32 v[126:127], v[96:97], v[232:233] op_sel:[1,1] op_sel_hi:[1,0]
	v_pk_mul_f32 v[130:131], v[98:99], v[238:239] op_sel:[1,1] op_sel_hi:[1,0]
	v_pk_fma_f32 v[88:89], v[88:89], v[230:231], v[124:125] op_sel_hi:[0,1,1] neg_lo:[0,0,1]
	v_pk_fma_f32 v[90:91], v[90:91], v[236:237], v[128:129] op_sel_hi:[0,1,1] neg_lo:[0,0,1]
	v_pk_mul_f32 v[124:125], v[104:105], v[234:235] op_sel:[1,1] op_sel_hi:[1,0]
	v_pk_mul_f32 v[128:129], v[106:107], v[242:243] op_sel:[1,1] op_sel_hi:[1,0]
	v_pk_fma_f32 v[96:97], v[96:97], v[232:233], v[126:127] op_sel_hi:[0,1,1] neg_lo:[0,0,1]
	v_pk_fma_f32 v[98:99], v[98:99], v[238:239], v[130:131] op_sel_hi:[0,1,1] neg_lo:[0,0,1]
	v_pk_fma_f32 v[104:105], v[104:105], v[234:235], v[124:125] op_sel_hi:[0,1,1] neg_lo:[0,0,1]
	v_pk_fma_f32 v[106:107], v[106:107], v[242:243], v[128:129] op_sel_hi:[0,1,1] neg_lo:[0,0,1]
	v_pk_add_f32 v[108:109], v[76:77], v[96:97]
	v_pk_add_f32 v[116:117], v[78:79], v[98:99]
	v_pk_add_f32 v[112:113], v[88:89], v[104:105]
	v_pk_add_f32 v[120:121], v[90:91], v[106:107]
	v_pk_add_f32 v[110:111], v[76:77], v[96:97] neg_lo:[0,1] neg_hi:[0,1]
	v_pk_add_f32 v[118:119], v[78:79], v[98:99] neg_lo:[0,1] neg_hi:[0,1]
	v_pk_add_f32 v[114:115], v[88:89], v[104:105] neg_lo:[0,1] neg_hi:[0,1]
	v_pk_add_f32 v[122:123], v[90:91], v[106:107] neg_lo:[0,1] neg_hi:[0,1]
	v_pk_add_f32 v[76:77], v[108:109], v[112:113]
	v_pk_add_f32 v[78:79], v[116:117], v[120:121]
	v_pk_add_f32 v[96:97], v[108:109], v[112:113] neg_lo:[0,1] neg_hi:[0,1]
	v_pk_add_f32 v[98:99], v[116:117], v[120:121] neg_lo:[0,1] neg_hi:[0,1]
	v_pk_add_f32 v[88:89], v[110:111], v[114:115] op_sel:[0,1] op_sel_hi:[1,0] neg_lo:[0,1]
	v_pk_add_f32 v[90:91], v[118:119], v[122:123] op_sel:[0,1] op_sel_hi:[1,0] neg_lo:[0,1]
	v_pk_add_f32 v[104:105], v[110:111], v[114:115] op_sel:[0,1] op_sel_hi:[1,0] neg_hi:[0,1]
	v_pk_add_f32 v[106:107], v[118:119], v[122:123] op_sel:[0,1] op_sel_hi:[1,0] neg_hi:[0,1]
	s_nop 0
	ds_write2st64_b64 v176, v[80:81], v[82:83] offset1:4
	ds_write2st64_b64 v176, v[76:77], v[78:79] offset0:8 offset1:12
	ds_write2st64_b64 v176, v[84:85], v[86:87] offset0:16 offset1:20
	ds_write2st64_b64 v176, v[88:89], v[90:91] offset0:24 offset1:28
	ds_write2st64_b64 v176, v[92:93], v[94:95] offset0:32 offset1:36
	ds_write2st64_b64 v176, v[96:97], v[98:99] offset0:40 offset1:44
	ds_write2st64_b64 v176, v[100:101], v[102:103] offset0:48 offset1:52
	ds_write2st64_b64 v176, v[104:105], v[106:107] offset0:56 offset1:60
	v_add_u32_e32 v0, 0x200, v75
	v_mov_b32_e32 v75, v0
	s_andn2_b64 exec, exec, s[0:1]
	s_cbranch_execnz .LBB0_1621

; DI float2 twid(float r) { return float2{__builtin_amdgcn_cosf(r), -__builtin_amdgcn_sinf(r)}; }
; DI void bfly_fwd(float2 a0, float2 a1, float2 a2, float2 a3, float r, float2& o0, float2& o1, float2& o2, float2& o3) {
;   float2 t0 = {a0.x + a2.x, a0.y + a2.y}, t1 = {a0.x - a2.x, a0.y - a2.y}, t2 = {a1.x + a3.x, a1.y + a3.y}, t3 = {a1.x - a3.x, a1.y - a3.y};
;   float2 b0 = {t0.x + t2.x, t0.y + t2.y}, b2 = {t0.x - t2.x, t0.y - t2.y}, b1 = {t1.x + t3.y, t1.y - t3.x}, b3 = {t1.x - t3.y, t1.y + t3.x};
;   float2 w1 = twid(r), w2 = cmul(w1, w1), w3 = cmul(w2, w1);
;   o0 = b0; o1 = cmul(b1, w1); o2 = cmul(b2, w2); o3 = cmul(b3, w3);
;   const int lq2 = lq1 - 2, Q1 = 1 << lq1, Q2 = 1 << lq2; const float invM1 = 1.f / (float)(4 << lq1), invM2 = 1.f / (float)(4 << lq2);
;   for (int gg = tid; gg < NBT * (N / 16); gg += NTHR) { const int g = gg & (N / 16 - 1); float2* z = z0 + (gg / (N / 16)) * N; const int jp = g & (Q2 - 1), base = ((g >> lq2) << (lq2 + 4)) + jp; float2 x[4][4];
; #pragma unroll
;     for (int q1 = 0; q1 < 4; ++q1)
; #pragma unroll
;       for (int q2 = 0; q2 < 4; ++q2) x[q1][q2] = z[base + q1 * Q1 + q2 * Q2];
; #pragma unroll
;     for (int q2 = 0; q2 < 4; ++q2) bfly_fwd(x[0][q2], x[1][q2], x[2][q2], x[3][q2], (float)(jp + q2 * Q2) * invM1, x[0][q2], x[1][q2], x[2][q2], x[3][q2]);
; #pragma unroll
;     for (int q1 = 0; q1 < 4; ++q1) bfly_fwd(x[q1][0], x[q1][1], x[q1][2], x[q1][3], (float)jp * invM2, x[q1][0], x[q1][1], x[q1][2], x[q1][3]);
.LBB0_1630:
	s_or_b64 exec, exec, s[0:1]
	s_movk_i32 s0, 0x400
	v_cmp_gt_i32_e32 vcc, s0, v76
	s_movk_i32 s0, 0x100
	v_or_b32_sdwa v80, v76, s0 dst_sel:DWORD dst_unused:UNUSED_PAD src0_sel:BYTE_0 src1_sel:DWORD
	s_movk_i32 s0, 0x200
	v_cvt_f32_ubyte0_e32 v4, v76
	v_or_b32_sdwa v79, v76, s0 dst_sel:DWORD dst_unused:UNUSED_PAD src0_sel:BYTE_0 src1_sel:DWORD
	s_movk_i32 s0, 0x300
	v_mul_f32_e32 v81, 0x39800000, v4
	v_or_b32_sdwa v78, v76, s0 dst_sel:DWORD dst_unused:UNUSED_PAD src0_sel:BYTE_0 src1_sel:DWORD
	v_mul_f32_e32 v82, 0x3a800000, v4
	v_lshlrev_b32_e32 v77, 4, v76
	s_waitcnt lgkmcnt(0)
	s_barrier
	s_and_saveexec_b64 s[0:1], vcc
	s_cbranch_execz .LBB0_1633
	v_cvt_f32_u32_e32 v5, v80
	v_sin_f32_e32 v4, v81
	v_cos_f32_e32 v6, v81
	v_sin_f32_e32 v50, v82
	v_mul_f32_e32 v5, 0x39800000, v5
	v_sin_f32_e32 v14, v5
	v_mul_f32_e32 v7, v4, v4
	v_cos_f32_e32 v16, v5
	v_mul_f32_e64 v9, v6, -v4
	v_fma_f32 v8, v6, v6, -v7
	v_cvt_f32_u32_e32 v7, v79
	v_add_f32_e32 v10, v9, v9
	v_mul_f32_e32 v5, v4, v8
	v_fma_f32 v18, v6, v10, -v5
	v_mul_f32_e32 v5, v14, v14
	v_fma_f32 v20, v16, v16, -v5
	v_mul_f32_e64 v5, v16, -v14
	v_add_f32_e32 v22, v5, v5
	v_mul_f32_e32 v5, 0x39800000, v7
	v_sin_f32_e32 v26, v5
	v_cos_f32_e32 v28, v5
	v_cvt_f32_u32_e32 v7, v78
	v_mul_f32_e32 v5, v14, v20
	v_fma_f32 v30, v16, v22, -v5
	v_mul_f32_e32 v5, v26, v26
	v_fma_f32 v32, v28, v28, -v5
	v_mul_f32_e64 v5, v28, -v26
	v_add_f32_e32 v34, v5, v5
	v_mul_f32_e32 v5, 0x39800000, v7
	v_sin_f32_e32 v38, v5
	v_cos_f32_e32 v40, v5
	v_mul_f32_e32 v5, v26, v32
	v_fma_f32 v42, v28, v34, -v5
	v_mul_f32_e32 v5, v38, v38
	v_cos_f32_e32 v52, v82
	v_fma_f32 v44, v40, v40, -v5
	v_mul_f32_e64 v5, v40, -v38
	v_add_f32_e32 v46, v5, v5
	v_mul_f32_e32 v5, v38, v44
	v_fma_f32 v54, v40, v46, -v5
	v_mul_f32_e32 v5, v50, v50
	v_fma_f32 v56, v52, v52, -v5
	v_mul_f32_e64 v5, v52, -v50
	v_add_f32_e32 v58, v5, v5
	v_mul_f32_e32 v12, v4, v10
	v_mul_f32_e32 v24, v14, v22
	v_mul_f32_e32 v36, v26, v34
	v_mul_f32_e32 v48, v38, v46
	v_mul_f32_e32 v60, v50, v58
	v_mul_f32_e32 v5, v50, v56
	v_fmac_f32_e32 v12, v6, v8
	v_fmac_f32_e32 v24, v16, v20
	v_fmac_f32_e32 v36, v28, v32
	v_fmac_f32_e32 v48, v40, v44
	v_fmac_f32_e32 v60, v52, v56
	v_fma_f32 v62, v52, v58, -v5
	v_mov_b32_e32 v53, v52
	v_mov_b32_e32 v51, v50
	v_mov_b32_e32 v57, v56
	v_mov_b32_e32 v59, v58
	v_mov_b32_e32 v61, v60
	v_mov_b32_e32 v63, v62
	v_mov_b32_e32 v7, v6
	v_mov_b32_e32 v5, v4
	v_mov_b32_e32 v29, v28
	v_mov_b32_e32 v27, v26
	v_mov_b32_e32 v17, v16
	v_mov_b32_e32 v15, v14
	v_mov_b32_e32 v41, v40
	v_mov_b32_e32 v39, v38
	v_mov_b32_e32 v9, v8
	v_mov_b32_e32 v33, v32
	v_mov_b32_e32 v21, v20
	v_mov_b32_e32 v45, v44
	v_mov_b32_e32 v13, v12
	v_mov_b32_e32 v19, v18
	v_mov_b32_e32 v37, v36
	v_mov_b32_e32 v43, v42
	v_mov_b32_e32 v25, v24
	v_mov_b32_e32 v31, v30
	v_mov_b32_e32 v49, v48
	v_mov_b32_e32 v55, v54
	v_mov_b32_e32 v11, v10
	v_mov_b32_e32 v23, v22
	v_mov_b32_e32 v35, v34
	v_mov_b32_e32 v47, v46
	v_lshlrev_b32_e32 v64, 4, v76
	s_mov_b64 s[14:15], 0
	v_mov_b32_e32 v65, v76
	v_and_b32_e32 v241, 0xff, v65
	v_add_u32_e32 v250, 0x0, v241
	v_cvt_f32_u32_e32 v250, v250
	v_mul_f32_e32 v250, 0x39800000, v250
	v_cos_f32_e32 v218, v250
	v_sin_f32_e32 v219, v250
	s_nop 1
	v_xor_b32_e32 v219, 0x80000000, v219
	s_nop 0
	v_pk_mul_f32 v[126:127], v[218:219], v[218:219] op_sel:[1,1] op_sel_hi:[1,0]
	s_nop 0
	v_pk_fma_f32 v[220:221], v[218:219], v[218:219], v[126:127] op_sel_hi:[0,1,1] neg_lo:[0,0,1]
	s_nop 0
	v_pk_mul_f32 v[126:127], v[220:221], v[218:219] op_sel:[1,1] op_sel_hi:[1,0]
	s_nop 0
	v_pk_fma_f32 v[222:223], v[220:221], v[218:219], v[126:127] op_sel_hi:[0,1,1] neg_lo:[0,0,1]
	s_nop 0
	v_add_u32_e32 v250, 0x100, v241
	v_cvt_f32_u32_e32 v250, v250
	v_mul_f32_e32 v250, 0x39800000, v250
	v_cos_f32_e32 v224, v250
	v_sin_f32_e32 v225, v250
	s_nop 1
	v_xor_b32_e32 v225, 0x80000000, v225
	s_nop 0
	v_pk_mul_f32 v[126:127], v[224:225], v[224:225] op_sel:[1,1] op_sel_hi:[1,0]
	s_nop 0
	v_pk_fma_f32 v[226:227], v[224:225], v[224:225], v[126:127] op_sel_hi:[0,1,1] neg_lo:[0,0,1]
	s_nop 0
	v_pk_mul_f32 v[126:127], v[226:227], v[224:225] op_sel:[1,1] op_sel_hi:[1,0]
	s_nop 0
	v_pk_fma_f32 v[228:229], v[226:227], v[224:225], v[126:127] op_sel_hi:[0,1,1] neg_lo:[0,0,1]
	s_nop 0
	v_add_u32_e32 v250, 0x200, v241
	v_cvt_f32_u32_e32 v250, v250
	v_mul_f32_e32 v250, 0x39800000, v250
	v_cos_f32_e32 v230, v250
	v_sin_f32_e32 v231, v250
	s_nop 1
	v_xor_b32_e32 v231, 0x80000000, v231
	s_nop 0
	v_pk_mul_f32 v[126:127], v[230:231], v[230:231] op_sel:[1,1] op_sel_hi:[1,0]
	s_nop 0
	v_pk_fma_f32 v[232:233], v[230:231], v[230:231], v[126:127] op_sel_hi:[0,1,1] neg_lo:[0,0,1]
	s_nop 0
	v_pk_mul_f32 v[126:127], v[232:233], v[230:231] op_sel:[1,1] op_sel_hi:[1,0]
	s_nop 0
	v_pk_fma_f32 v[234:235], v[232:233], v[230:231], v[126:127] op_sel_hi:[0,1,1] neg_lo:[0,0,1]
	s_nop 0
	v_add_u32_e32 v250, 0x300, v241
	v_cvt_f32_u32_e32 v250, v250
	v_mul_f32_e32 v250, 0x39800000, v250
	v_cos_f32_e32 v236, v250
	v_sin_f32_e32 v237, v250
	s_nop 1
	v_xor_b32_e32 v237, 0x80000000, v237
	s_nop 0
	v_pk_mul_f32 v[126:127], v[236:237], v[236:237] op_sel:[1,1] op_sel_hi:[1,0]
	s_nop 0
	v_pk_fma_f32 v[238:239], v[236:237], v[236:237], v[126:127] op_sel_hi:[0,1,1] neg_lo:[0,0,1]
	s_nop 0
	v_pk_mul_f32 v[126:127], v[238:239], v[236:237] op_sel:[1,1] op_sel_hi:[1,0]
	s_nop 0
	v_pk_fma_f32 v[242:243], v[238:239], v[236:237], v[126:127] op_sel_hi:[0,1,1] neg_lo:[0,0,1]
	s_nop 0
	v_cvt_f32_u32_e32 v250, v241
	v_mul_f32_e32 v250, 0x3a800000, v250
	v_cos_f32_e32 v244, v250
	v_sin_f32_e32 v245, v250
	s_nop 1
	v_xor_b32_e32 v245, 0x80000000, v245
	s_nop 0
	v_pk_mul_f32 v[126:127], v[244:245], v[244:245] op_sel:[1,1] op_sel_hi:[1,0]
	s_nop 0
	v_pk_fma_f32 v[246:247], v[244:245], v[244:245], v[126:127] op_sel_hi:[0,1,1] neg_lo:[0,0,1]
	s_nop 0
	v_pk_mul_f32 v[126:127], v[246:247], v[244:245] op_sel:[1,1] op_sel_hi:[1,0]
	s_nop 0
	v_pk_fma_f32 v[248:249], v[246:247], v[244:245], v[126:127] op_sel_hi:[0,1,1] neg_lo:[0,0,1]
	s_nop 0
; DI float2 twid(float r) { return float2{__builtin_amdgcn_cosf(r), -__builtin_amdgcn_sinf(r)}; }
; DI void bfly_fwd(float2 a0, float2 a1, float2 a2, float2 a3, float r, float2& o0, float2& o1, float2& o2, float2& o3) {
;   float2 t0 = {a0.x + a2.x, a0.y + a2.y}, t1 = {a0.x - a2.x, a0.y - a2.y}, t2 = {a1.x + a3.x, a1.y + a3.y}, t3 = {a1.x - a3.x, a1.y - a3.y};
;   float2 b0 = {t0.x + t2.x, t0.y + t2.y}, b2 = {t0.x - t2.x, t0.y - t2.y}, b1 = {t1.x + t3.y, t1.y - t3.x}, b3 = {t1.x - t3.y, t1.y + t3.x};
;   float2 w1 = twid(r), w2 = cmul(w1, w1), w3 = cmul(w2, w1);
;   o0 = b0; o1 = cmul(b1, w1); o2 = cmul(b2, w2); o3 = cmul(b3, w3);
; }
;     ...
;   for (int gg = tid; gg < NBT * (N / 16); gg += NTHR) { const int g = gg & (N / 16 - 1); float2* z = z0 + (gg / (N / 16)) * N; const int jp = g & (Q2 - 1), base = ((g >> lq2) << (lq2 + 4)) + jp; float2 x[4][4];
; #pragma unroll
;     for (int q1 = 0; q1 < 4; ++q1)
; #pragma unroll
;       for (int q2 = 0; q2 < 4; ++q2) x[q1][q2] = z[base + q1 * Q1 + q2 * Q2];
; #pragma unroll
;     for (int q2 = 0; q2 < 4; ++q2) bfly_fwd(x[0][q2], x[1][q2], x[2][q2], x[3][q2], (float)(jp + q2 * Q2) * invM1, x[0][q2], x[1][q2], x[2][q2], x[3][q2]);
; #pragma unroll
;     for (int q1 = 0; q1 < 4; ++q1) bfly_fwd(x[q1][0], x[q1][1], x[q1][2], x[q1][3], (float)jp * invM2, x[q1][0], x[q1][1], x[q1][2], x[q1][3]);
; #pragma unroll
;     for (int q1 = 0; q1 < 4; ++q1)
; #pragma unroll
;       for (int q2 = 0; q2 < 4; ++q2) z[base + q1 * Q1 + q2 * Q2] = x[q1][q2]; }
.LBB0_1632:
	v_ashrrev_i32_e32 v66, 31, v65
	v_lshrrev_b32_e32 v66, 22, v66
	v_add_lshl_u32 v66, v65, v66, 7
	v_and_b32_e32 v66, 0xfffe0000, v66
	v_and_b32_e32 v67, 0x3000, v64
	v_add_u32_e32 v66, 16, v66
	v_lshlrev_b32_e32 v67, 3, v67
	v_lshlrev_b32_sdwa v68, v151, v76 dst_sel:DWORD dst_unused:UNUSED_PAD src0_sel:DWORD src1_sel:BYTE_0
	v_add3_u32 v83, v66, v67, v68
	ds_read2st64_b64 v[70:73], v83 offset1:4
	ds_read2st64_b64 v[84:87], v83 offset0:8 offset1:12
	ds_read2st64_b64 v[88:91], v83 offset0:16 offset1:20
	ds_read2st64_b64 v[92:95], v83 offset0:24 offset1:28
	ds_read2st64_b64 v[96:99], v83 offset0:32 offset1:36
	ds_read2st64_b64 v[100:103], v83 offset0:40 offset1:44
	ds_read2st64_b64 v[104:107], v83 offset0:48 offset1:52
	ds_read2st64_b64 v[108:111], v83 offset0:56 offset1:60
	v_cmp_lt_i32_e64 s[12:13], s5, v65
	s_or_b64 s[14:15], s[12:13], s[14:15]
	s_waitcnt lgkmcnt(0)
	v_pk_add_f32 v[74:75], v[70:71], v[96:97]
	v_pk_add_f32 v[118:119], v[72:73], v[98:99]
	v_pk_add_f32 v[114:115], v[88:89], v[104:105]
	v_pk_add_f32 v[122:123], v[90:91], v[106:107]
	v_pk_add_f32 v[112:113], v[70:71], v[96:97] neg_lo:[0,1] neg_hi:[0,1]
	v_pk_add_f32 v[120:121], v[72:73], v[98:99] neg_lo:[0,1] neg_hi:[0,1]
	v_pk_add_f32 v[116:117], v[88:89], v[104:105] neg_lo:[0,1] neg_hi:[0,1]
	v_pk_add_f32 v[124:125], v[90:91], v[106:107] neg_lo:[0,1] neg_hi:[0,1]
	v_pk_add_f32 v[70:71], v[74:75], v[114:115]
	v_pk_add_f32 v[72:73], v[118:119], v[122:123]
	v_pk_add_f32 v[74:75], v[74:75], v[114:115] neg_lo:[0,1] neg_hi:[0,1]
	v_pk_add_f32 v[118:119], v[118:119], v[122:123] neg_lo:[0,1] neg_hi:[0,1]
	v_pk_add_f32 v[114:115], v[112:113], v[116:117] op_sel:[0,1] op_sel_hi:[1,0] neg_hi:[0,1]
	v_pk_add_f32 v[122:123], v[120:121], v[124:125] op_sel:[0,1] op_sel_hi:[1,0] neg_hi:[0,1]
	v_pk_add_f32 v[112:113], v[112:113], v[116:117] op_sel:[0,1] op_sel_hi:[1,0] neg_lo:[0,1]
	v_pk_add_f32 v[120:121], v[120:121], v[124:125] op_sel:[0,1] op_sel_hi:[1,0] neg_lo:[0,1]
	v_pk_mul_f32 v[126:127], v[74:75], v[220:221] op_sel:[1,1] op_sel_hi:[1,0]
	v_pk_mul_f32 v[130:131], v[118:119], v[226:227] op_sel:[1,1] op_sel_hi:[1,0]
	v_pk_mul_f32 v[128:129], v[114:115], v[218:219] op_sel:[1,1] op_sel_hi:[1,0]
	v_pk_mul_f32 v[132:133], v[122:123], v[224:225] op_sel:[1,1] op_sel_hi:[1,0]
	v_pk_fma_f32 v[96:97], v[74:75], v[220:221], v[126:127] op_sel_hi:[0,1,1] neg_lo:[0,0,1]
	v_pk_fma_f32 v[98:99], v[118:119], v[226:227], v[130:131] op_sel_hi:[0,1,1] neg_lo:[0,0,1]
	v_pk_mul_f32 v[126:127], v[112:113], v[222:223] op_sel:[1,1] op_sel_hi:[1,0]
	v_pk_mul_f32 v[130:131], v[120:121], v[228:229] op_sel:[1,1] op_sel_hi:[1,0]
	v_pk_fma_f32 v[88:89], v[114:115], v[218:219], v[128:129] op_sel_hi:[0,1,1] neg_lo:[0,0,1]
	v_pk_fma_f32 v[90:91], v[122:123], v[224:225], v[132:133] op_sel_hi:[0,1,1] neg_lo:[0,0,1]
	v_pk_fma_f32 v[104:105], v[112:113], v[222:223], v[126:127] op_sel_hi:[0,1,1] neg_lo:[0,0,1]
	v_pk_fma_f32 v[106:107], v[120:121], v[228:229], v[130:131] op_sel_hi:[0,1,1] neg_lo:[0,0,1]
	v_pk_add_f32 v[74:75], v[84:85], v[100:101]
	v_pk_add_f32 v[118:119], v[86:87], v[102:103]
	v_pk_add_f32 v[114:115], v[92:93], v[108:109]
	v_pk_add_f32 v[122:123], v[94:95], v[110:111]
	v_pk_add_f32 v[112:113], v[84:85], v[100:101] neg_lo:[0,1] neg_hi:[0,1]
	v_pk_add_f32 v[120:121], v[86:87], v[102:103] neg_lo:[0,1] neg_hi:[0,1]
	v_pk_add_f32 v[116:117], v[92:93], v[108:109] neg_lo:[0,1] neg_hi:[0,1]
	v_pk_add_f32 v[124:125], v[94:95], v[110:111] neg_lo:[0,1] neg_hi:[0,1]
	v_pk_add_f32 v[84:85], v[74:75], v[114:115]
	v_pk_add_f32 v[86:87], v[118:119], v[122:123]
	v_pk_add_f32 v[74:75], v[74:75], v[114:115] neg_lo:[0,1] neg_hi:[0,1]
	v_pk_add_f32 v[118:119], v[118:119], v[122:123] neg_lo:[0,1] neg_hi:[0,1]
	v_pk_add_f32 v[114:115], v[112:113], v[116:117] op_sel:[0,1] op_sel_hi:[1,0] neg_hi:[0,1]
	v_pk_add_f32 v[122:123], v[120:121], v[124:125] op_sel:[0,1] op_sel_hi:[1,0] neg_hi:[0,1]
	v_pk_add_f32 v[112:113], v[112:113], v[116:117] op_sel:[0,1] op_sel_hi:[1,0] neg_lo:[0,1]
	v_pk_add_f32 v[120:121], v[120:121], v[124:125] op_sel:[0,1] op_sel_hi:[1,0] neg_lo:[0,1]
	v_pk_mul_f32 v[126:127], v[74:75], v[232:233] op_sel:[1,1] op_sel_hi:[1,0]
	v_pk_mul_f32 v[130:131], v[118:119], v[238:239] op_sel:[1,1] op_sel_hi:[1,0]
	v_pk_mul_f32 v[128:129], v[114:115], v[230:231] op_sel:[1,1] op_sel_hi:[1,0]
	v_pk_mul_f32 v[132:133], v[122:123], v[236:237] op_sel:[1,1] op_sel_hi:[1,0]
	v_pk_fma_f32 v[100:101], v[74:75], v[232:233], v[126:127] op_sel_hi:[0,1,1] neg_lo:[0,0,1]
	v_pk_fma_f32 v[102:103], v[118:119], v[238:239], v[130:131] op_sel_hi:[0,1,1] neg_lo:[0,0,1]
	v_pk_mul_f32 v[126:127], v[112:113], v[234:235] op_sel:[1,1] op_sel_hi:[1,0]
	v_pk_mul_f32 v[130:131], v[120:121], v[242:243] op_sel:[1,1] op_sel_hi:[1,0]
	v_pk_fma_f32 v[92:93], v[114:115], v[230:231], v[128:129] op_sel_hi:[0,1,1] neg_lo:[0,0,1]
	v_pk_fma_f32 v[94:95], v[122:123], v[236:237], v[132:133] op_sel_hi:[0,1,1] neg_lo:[0,0,1]
	v_pk_fma_f32 v[108:109], v[112:113], v[234:235], v[126:127] op_sel_hi:[0,1,1] neg_lo:[0,0,1]
	v_pk_fma_f32 v[110:111], v[120:121], v[242:243], v[130:131] op_sel_hi:[0,1,1] neg_lo:[0,0,1]
	v_pk_add_f32 v[74:75], v[70:71], v[84:85]
	v_pk_add_f32 v[118:119], v[88:89], v[92:93]
	v_pk_add_f32 v[114:115], v[72:73], v[86:87]
	v_pk_add_f32 v[122:123], v[90:91], v[94:95]
	v_pk_add_f32 v[112:113], v[70:71], v[84:85] neg_lo:[0,1] neg_hi:[0,1]
	v_pk_add_f32 v[120:121], v[88:89], v[92:93] neg_lo:[0,1] neg_hi:[0,1]
	v_pk_add_f32 v[116:117], v[72:73], v[86:87] neg_lo:[0,1] neg_hi:[0,1]
	v_pk_add_f32 v[124:125], v[90:91], v[94:95] neg_lo:[0,1] neg_hi:[0,1]
	v_pk_add_f32 v[70:71], v[74:75], v[114:115]
	v_pk_add_f32 v[88:89], v[118:119], v[122:123]
; DI float2 twid(float r) { return float2{__builtin_amdgcn_cosf(r), -__builtin_amdgcn_sinf(r)}; }
; DI void bfly_fwd(float2 a0, float2 a1, float2 a2, float2 a3, float r, float2& o0, float2& o1, float2& o2, float2& o3) {
;   float2 t0 = {a0.x + a2.x, a0.y + a2.y}, t1 = {a0.x - a2.x, a0.y - a2.y}, t2 = {a1.x + a3.x, a1.y + a3.y}, t3 = {a1.x - a3.x, a1.y - a3.y};
;   float2 b0 = {t0.x + t2.x, t0.y + t2.y}, b2 = {t0.x - t2.x, t0.y - t2.y}, b1 = {t1.x + t3.y, t1.y - t3.x}, b3 = {t1.x - t3.y, t1.y + t3.x};
;   float2 w1 = twid(r), w2 = cmul(w1, w1), w3 = cmul(w2, w1);
;   o0 = b0; o1 = cmul(b1, w1); o2 = cmul(b2, w2); o3 = cmul(b3, w3);
; }
;     ...
;   for (int gg = tid; gg < NBT * (N / 16); gg += NTHR) { const int g = gg & (N / 16 - 1); float2* z = z0 + (gg / (N / 16)) * N; const int jp = g & (Q2 - 1), base = ((g >> lq2) << (lq2 + 4)) + jp; float2 x[4][4];
; #pragma unroll
;     for (int q1 = 0; q1 < 4; ++q1)
; #pragma unroll
;       for (int q2 = 0; q2 < 4; ++q2) x[q1][q2] = z[base + q1 * Q1 + q2 * Q2];
; #pragma unroll
;     for (int q2 = 0; q2 < 4; ++q2) bfly_fwd(x[0][q2], x[1][q2], x[2][q2], x[3][q2], (float)(jp + q2 * Q2) * invM1, x[0][q2], x[1][q2], x[2][q2], x[3][q2]);
; #pragma unroll
;     for (int q1 = 0; q1 < 4; ++q1) bfly_fwd(x[q1][0], x[q1][1], x[q1][2], x[q1][3], (float)jp * invM2, x[q1][0], x[q1][1], x[q1][2], x[q1][3]);
; #pragma unroll
;     for (int q1 = 0; q1 < 4; ++q1)
; #pragma unroll
;       for (int q2 = 0; q2 < 4; ++q2) z[base + q1 * Q1 + q2 * Q2] = x[q1][q2]; }
	v_pk_add_f32 v[74:75], v[74:75], v[114:115] neg_lo:[0,1] neg_hi:[0,1]
	v_pk_add_f32 v[118:119], v[118:119], v[122:123] neg_lo:[0,1] neg_hi:[0,1]
	v_pk_add_f32 v[114:115], v[112:113], v[116:117] op_sel:[0,1] op_sel_hi:[1,0] neg_hi:[0,1]
	v_pk_add_f32 v[122:123], v[120:121], v[124:125] op_sel:[0,1] op_sel_hi:[1,0] neg_hi:[0,1]
	v_pk_add_f32 v[112:113], v[112:113], v[116:117] op_sel:[0,1] op_sel_hi:[1,0] neg_lo:[0,1]
	v_pk_add_f32 v[120:121], v[120:121], v[124:125] op_sel:[0,1] op_sel_hi:[1,0] neg_lo:[0,1]
	v_pk_mul_f32 v[126:127], v[74:75], v[246:247] op_sel:[1,1] op_sel_hi:[1,0]
	v_pk_mul_f32 v[130:131], v[118:119], v[246:247] op_sel:[1,1] op_sel_hi:[1,0]
	v_pk_mul_f32 v[128:129], v[114:115], v[244:245] op_sel:[1,1] op_sel_hi:[1,0]
	v_pk_mul_f32 v[132:133], v[122:123], v[244:245] op_sel:[1,1] op_sel_hi:[1,0]
	v_pk_fma_f32 v[84:85], v[74:75], v[246:247], v[126:127] op_sel_hi:[0,1,1] neg_lo:[0,0,1]
	v_pk_fma_f32 v[92:93], v[118:119], v[246:247], v[130:131] op_sel_hi:[0,1,1] neg_lo:[0,0,1]
	v_pk_mul_f32 v[126:127], v[112:113], v[248:249] op_sel:[1,1] op_sel_hi:[1,0]
	v_pk_mul_f32 v[130:131], v[120:121], v[248:249] op_sel:[1,1] op_sel_hi:[1,0]
	v_pk_fma_f32 v[72:73], v[114:115], v[244:245], v[128:129] op_sel_hi:[0,1,1] neg_lo:[0,0,1]
	v_pk_fma_f32 v[90:91], v[122:123], v[244:245], v[132:133] op_sel_hi:[0,1,1] neg_lo:[0,0,1]
	v_pk_fma_f32 v[86:87], v[112:113], v[248:249], v[126:127] op_sel_hi:[0,1,1] neg_lo:[0,0,1]
	v_pk_fma_f32 v[94:95], v[120:121], v[248:249], v[130:131] op_sel_hi:[0,1,1] neg_lo:[0,0,1]
	v_pk_add_f32 v[74:75], v[96:97], v[100:101]
	v_pk_add_f32 v[118:119], v[104:105], v[108:109]
	v_pk_add_f32 v[114:115], v[98:99], v[102:103]
	v_pk_add_f32 v[122:123], v[106:107], v[110:111]
	v_pk_add_f32 v[112:113], v[96:97], v[100:101] neg_lo:[0,1] neg_hi:[0,1]
	v_pk_add_f32 v[120:121], v[104:105], v[108:109] neg_lo:[0,1] neg_hi:[0,1]
	v_pk_add_f32 v[116:117], v[98:99], v[102:103] neg_lo:[0,1] neg_hi:[0,1]
	v_pk_add_f32 v[124:125], v[106:107], v[110:111] neg_lo:[0,1] neg_hi:[0,1]
	v_pk_add_f32 v[96:97], v[74:75], v[114:115]
	v_pk_add_f32 v[104:105], v[118:119], v[122:123]
	v_pk_add_f32 v[74:75], v[74:75], v[114:115] neg_lo:[0,1] neg_hi:[0,1]
	v_pk_add_f32 v[118:119], v[118:119], v[122:123] neg_lo:[0,1] neg_hi:[0,1]
	v_pk_add_f32 v[114:115], v[112:113], v[116:117] op_sel:[0,1] op_sel_hi:[1,0] neg_hi:[0,1]
	v_pk_add_f32 v[122:123], v[120:121], v[124:125] op_sel:[0,1] op_sel_hi:[1,0] neg_hi:[0,1]
	v_pk_add_f32 v[112:113], v[112:113], v[116:117] op_sel:[0,1] op_sel_hi:[1,0] neg_lo:[0,1]
	v_pk_add_f32 v[120:121], v[120:121], v[124:125] op_sel:[0,1] op_sel_hi:[1,0] neg_lo:[0,1]
	v_pk_mul_f32 v[126:127], v[74:75], v[246:247] op_sel:[1,1] op_sel_hi:[1,0]
	v_pk_mul_f32 v[130:131], v[118:119], v[246:247] op_sel:[1,1] op_sel_hi:[1,0]
	v_pk_mul_f32 v[128:129], v[114:115], v[244:245] op_sel:[1,1] op_sel_hi:[1,0]
	v_pk_mul_f32 v[132:133], v[122:123], v[244:245] op_sel:[1,1] op_sel_hi:[1,0]
	v_pk_fma_f32 v[100:101], v[74:75], v[246:247], v[126:127] op_sel_hi:[0,1,1] neg_lo:[0,0,1]
	v_pk_fma_f32 v[108:109], v[118:119], v[246:247], v[130:131] op_sel_hi:[0,1,1] neg_lo:[0,0,1]
	v_pk_mul_f32 v[126:127], v[112:113], v[248:249] op_sel:[1,1] op_sel_hi:[1,0]
	v_pk_mul_f32 v[130:131], v[120:121], v[248:249] op_sel:[1,1] op_sel_hi:[1,0]
	v_pk_fma_f32 v[98:99], v[114:115], v[244:245], v[128:129] op_sel_hi:[0,1,1] neg_lo:[0,0,1]
	v_pk_fma_f32 v[106:107], v[122:123], v[244:245], v[132:133] op_sel_hi:[0,1,1] neg_lo:[0,0,1]
	v_pk_fma_f32 v[102:103], v[112:113], v[248:249], v[126:127] op_sel_hi:[0,1,1] neg_lo:[0,0,1]
	v_pk_fma_f32 v[110:111], v[120:121], v[248:249], v[130:131] op_sel_hi:[0,1,1] neg_lo:[0,0,1]
	s_nop 0
	ds_write2st64_b64 v83, v[70:71], v[72:73] offset1:4
	ds_write2st64_b64 v83, v[84:85], v[86:87] offset0:8 offset1:12
	ds_write2st64_b64 v83, v[88:89], v[90:91] offset0:16 offset1:20
	ds_write2st64_b64 v83, v[92:93], v[94:95] offset0:24 offset1:28
	ds_write2st64_b64 v83, v[96:97], v[98:99] offset0:32 offset1:36
	ds_write2st64_b64 v83, v[100:101], v[102:103] offset0:40 offset1:44
	ds_write2st64_b64 v83, v[104:105], v[106:107] offset0:48 offset1:52
	ds_write2st64_b64 v83, v[108:109], v[110:111] offset0:56 offset1:60
	v_add_u32_e32 v64, 0x2000, v64
	v_add_u32_e32 v66, 0x200, v65
	v_mov_b32_e32 v65, v66
	s_andn2_b64 exec, exec, s[14:15]
	s_cbranch_execnz .LBB0_1632
; DI float2 twid(float r) { return float2{__builtin_amdgcn_cosf(r), -__builtin_amdgcn_sinf(r)}; }
; DI void bfly_fwd(float2 a0, float2 a1, float2 a2, float2 a3, float r, float2& o0, float2& o1, float2& o2, float2& o3) {
;   float2 t0 = {a0.x + a2.x, a0.y + a2.y}, t1 = {a0.x - a2.x, a0.y - a2.y}, t2 = {a1.x + a3.x, a1.y + a3.y}, t3 = {a1.x - a3.x, a1.y - a3.y};
;   float2 b0 = {t0.x + t2.x, t0.y + t2.y}, b2 = {t0.x - t2.x, t0.y - t2.y}, b1 = {t1.x + t3.y, t1.y - t3.x}, b3 = {t1.x - t3.y, t1.y + t3.x};
;   float2 w1 = twid(r), w2 = cmul(w1, w1), w3 = cmul(w2, w1);
;   const int lq2 = lq1 - 2, Q1 = 1 << lq1, Q2 = 1 << lq2; const float invM1 = 1.f / (float)(4 << lq1), invM2 = 1.f / (float)(4 << lq2);
;   for (int gg = tid; gg < NBT * (N / 16); gg += NTHR) { const int g = gg & (N / 16 - 1); float2* z = z0 + (gg / (N / 16)) * N; const int jp = g & (Q2 - 1), base = ((g >> lq2) << (lq2 + 4)) + jp; float2 x[4][4];
; #pragma unroll
;     for (int q1 = 0; q1 < 4; ++q1)
; #pragma unroll
;       for (int q2 = 0; q2 < 4; ++q2) x[q1][q2] = z[base + q1 * Q1 + q2 * Q2];
; #pragma unroll
;     for (int q2 = 0; q2 < 4; ++q2) bfly_fwd(x[0][q2], x[1][q2], x[2][q2], x[3][q2], (float)(jp + q2 * Q2) * invM1, x[0][q2], x[1][q2], x[2][q2], x[3][q2]);
; #pragma unroll
;     for (int q1 = 0; q1 < 4; ++q1) bfly_fwd(x[q1][0], x[q1][1], x[q1][2], x[q1][3], (float)jp * invM2, x[q1][0], x[q1][1], x[q1][2], x[q1][3]);
.LBB0_1633:
	s_or_b64 exec, exec, s[0:1]
	v_and_b32_e32 v83, 15, v76
	v_cvt_f32_ubyte0_e32 v67, v83
	v_or_b32_e32 v66, 16, v83
	v_or_b32_e32 v65, 32, v83
	v_or_b32_e32 v64, 48, v83
	s_waitcnt lgkmcnt(0)
	s_barrier
	s_and_saveexec_b64 s[0:1], vcc
	s_cbranch_execz .LBB0_1636
	v_mul_f32_e32 v5, 0x3b800000, v67
	v_sin_f32_e32 v4, v5
	v_cos_f32_e32 v6, v5
	v_lshlrev_b32_e32 v68, 4, v76
	s_mov_b64 s[14:15], 0
	v_mul_f32_e32 v5, v4, v4
	v_fma_f32 v8, v6, v6, -v5
	v_cvt_f32_ubyte0_e32 v5, v66
	v_mul_f32_e32 v5, 0x3b800000, v5
	v_sin_f32_e32 v14, v5
	v_cos_f32_e32 v16, v5
	v_mul_f32_e64 v7, v6, -v4
	v_add_f32_e32 v10, v7, v7
	v_mul_f32_e32 v5, v4, v8
	v_fma_f32 v18, v6, v10, -v5
	v_mul_f32_e32 v5, v14, v14
	v_fma_f32 v20, v16, v16, -v5
	v_mul_f32_e64 v5, v16, -v14
	v_add_f32_e32 v22, v5, v5
	v_cvt_f32_ubyte0_e32 v5, v65
	v_mul_f32_e32 v5, 0x3b800000, v5
	v_sin_f32_e32 v26, v5
	v_cos_f32_e32 v28, v5
	v_mul_f32_e32 v5, v14, v20
	v_fma_f32 v30, v16, v22, -v5
	v_mul_f32_e32 v5, v26, v26
	v_fma_f32 v32, v28, v28, -v5
	v_mul_f32_e64 v5, v28, -v26
	v_add_f32_e32 v34, v5, v5
	v_cvt_f32_ubyte0_e32 v5, v64
	v_mul_f32_e32 v5, 0x3b800000, v5
	v_sin_f32_e32 v38, v5
	v_cos_f32_e32 v40, v5
	v_mul_f32_e32 v5, v26, v32
	v_fma_f32 v42, v28, v34, -v5
	v_mul_f32_e32 v5, v38, v38
	v_fma_f32 v44, v40, v40, -v5
	v_mul_f32_e64 v5, v40, -v38
	v_add_f32_e32 v46, v5, v5
	v_mul_f32_e32 v5, 0x3c800000, v67
	v_sin_f32_e32 v50, v5
	v_cos_f32_e32 v52, v5
	v_mul_f32_e32 v5, v38, v44
	v_fma_f32 v54, v40, v46, -v5
	v_mul_f32_e32 v5, v50, v50
	v_fma_f32 v56, v52, v52, -v5
	v_mul_f32_e64 v5, v52, -v50
	v_add_f32_e32 v58, v5, v5
	v_mul_f32_e32 v12, v4, v10
	v_mul_f32_e32 v24, v14, v22
	v_mul_f32_e32 v36, v26, v34
	v_mul_f32_e32 v48, v38, v46
	v_mul_f32_e32 v60, v50, v58
	v_mul_f32_e32 v5, v50, v56
	v_fmac_f32_e32 v12, v6, v8
	v_fmac_f32_e32 v24, v16, v20
	v_fmac_f32_e32 v36, v28, v32
	v_fmac_f32_e32 v48, v40, v44
	v_fmac_f32_e32 v60, v52, v56
	v_fma_f32 v62, v52, v58, -v5
	v_mov_b32_e32 v53, v52
	v_mov_b32_e32 v51, v50
	v_mov_b32_e32 v57, v56
	v_mov_b32_e32 v59, v58
	v_mov_b32_e32 v61, v60
	v_mov_b32_e32 v63, v62
	v_mov_b32_e32 v7, v6
	v_mov_b32_e32 v5, v4
	v_mov_b32_e32 v29, v28
	v_mov_b32_e32 v27, v26
	v_mov_b32_e32 v17, v16
	v_mov_b32_e32 v15, v14
	v_mov_b32_e32 v41, v40
	v_mov_b32_e32 v39, v38
	v_mov_b32_e32 v9, v8
	v_mov_b32_e32 v33, v32
	v_mov_b32_e32 v21, v20
	v_mov_b32_e32 v45, v44
	v_mov_b32_e32 v13, v12
	v_mov_b32_e32 v19, v18
	v_mov_b32_e32 v37, v36
	v_mov_b32_e32 v43, v42
	v_mov_b32_e32 v25, v24
	v_mov_b32_e32 v31, v30
	v_mov_b32_e32 v49, v48
	v_mov_b32_e32 v55, v54
	v_mov_b32_e32 v11, v10
	v_mov_b32_e32 v23, v22
	v_mov_b32_e32 v35, v34
	v_mov_b32_e32 v47, v46
	v_mov_b32_e32 v69, v76
	v_and_b32_e32 v241, 0xf, v69
	v_add_u32_e32 v250, 0x0, v241
	v_cvt_f32_u32_e32 v250, v250
	v_mul_f32_e32 v250, 0x3b800000, v250
	v_cos_f32_e32 v218, v250
	v_sin_f32_e32 v219, v250
	s_nop 1
	v_xor_b32_e32 v219, 0x80000000, v219
	s_nop 0
	v_pk_mul_f32 v[130:131], v[218:219], v[218:219] op_sel:[1,1] op_sel_hi:[1,0]
	s_nop 0
	v_pk_fma_f32 v[220:221], v[218:219], v[218:219], v[130:131] op_sel_hi:[0,1,1] neg_lo:[0,0,1]
	s_nop 0
	v_pk_mul_f32 v[130:131], v[220:221], v[218:219] op_sel:[1,1] op_sel_hi:[1,0]
	s_nop 0
	v_pk_fma_f32 v[222:223], v[220:221], v[218:219], v[130:131] op_sel_hi:[0,1,1] neg_lo:[0,0,1]
	s_nop 0
	v_add_u32_e32 v250, 0x10, v241
	v_cvt_f32_u32_e32 v250, v250
	v_mul_f32_e32 v250, 0x3b800000, v250
	v_cos_f32_e32 v224, v250
	v_sin_f32_e32 v225, v250
	s_nop 1
	v_xor_b32_e32 v225, 0x80000000, v225
	s_nop 0
	v_pk_mul_f32 v[130:131], v[224:225], v[224:225] op_sel:[1,1] op_sel_hi:[1,0]
	s_nop 0
	v_pk_fma_f32 v[226:227], v[224:225], v[224:225], v[130:131] op_sel_hi:[0,1,1] neg_lo:[0,0,1]
	s_nop 0
	v_pk_mul_f32 v[130:131], v[226:227], v[224:225] op_sel:[1,1] op_sel_hi:[1,0]
	s_nop 0
	v_pk_fma_f32 v[228:229], v[226:227], v[224:225], v[130:131] op_sel_hi:[0,1,1] neg_lo:[0,0,1]
	s_nop 0
	v_add_u32_e32 v250, 0x20, v241
	v_cvt_f32_u32_e32 v250, v250
	v_mul_f32_e32 v250, 0x3b800000, v250
	v_cos_f32_e32 v230, v250
	v_sin_f32_e32 v231, v250
	s_nop 1
	v_xor_b32_e32 v231, 0x80000000, v231
	s_nop 0
	v_pk_mul_f32 v[130:131], v[230:231], v[230:231] op_sel:[1,1] op_sel_hi:[1,0]
	s_nop 0
	v_pk_fma_f32 v[232:233], v[230:231], v[230:231], v[130:131] op_sel_hi:[0,1,1] neg_lo:[0,0,1]
	s_nop 0
	v_pk_mul_f32 v[130:131], v[232:233], v[230:231] op_sel:[1,1] op_sel_hi:[1,0]
	s_nop 0
	v_pk_fma_f32 v[234:235], v[232:233], v[230:231], v[130:131] op_sel_hi:[0,1,1] neg_lo:[0,0,1]
	s_nop 0
	v_add_u32_e32 v250, 0x30, v241
	v_cvt_f32_u32_e32 v250, v250
	v_mul_f32_e32 v250, 0x3b800000, v250
	v_cos_f32_e32 v236, v250
	v_sin_f32_e32 v237, v250
	s_nop 1
	v_xor_b32_e32 v237, 0x80000000, v237
	s_nop 0
	v_pk_mul_f32 v[130:131], v[236:237], v[236:237] op_sel:[1,1] op_sel_hi:[1,0]
	s_nop 0
	v_pk_fma_f32 v[238:239], v[236:237], v[236:237], v[130:131] op_sel_hi:[0,1,1] neg_lo:[0,0,1]
	s_nop 0
	v_pk_mul_f32 v[130:131], v[238:239], v[236:237] op_sel:[1,1] op_sel_hi:[1,0]
	s_nop 0
	v_pk_fma_f32 v[242:243], v[238:239], v[236:237], v[130:131] op_sel_hi:[0,1,1] neg_lo:[0,0,1]
	s_nop 0
	v_cvt_f32_u32_e32 v250, v241
	v_mul_f32_e32 v250, 0x3c800000, v250
	v_cos_f32_e32 v244, v250
	v_sin_f32_e32 v245, v250
	s_nop 1
	v_xor_b32_e32 v245, 0x80000000, v245
	s_nop 0
	v_pk_mul_f32 v[130:131], v[244:245], v[244:245] op_sel:[1,1] op_sel_hi:[1,0]
	s_nop 0
	v_pk_fma_f32 v[246:247], v[244:245], v[244:245], v[130:131] op_sel_hi:[0,1,1] neg_lo:[0,0,1]
	s_nop 0
	v_pk_mul_f32 v[130:131], v[246:247], v[244:245] op_sel:[1,1] op_sel_hi:[1,0]
	s_nop 0
	v_pk_fma_f32 v[248:249], v[246:247], v[244:245], v[130:131] op_sel_hi:[0,1,1] neg_lo:[0,0,1]
	s_nop 0
; DI float2 twid(float r) { return float2{__builtin_amdgcn_cosf(r), -__builtin_amdgcn_sinf(r)}; }
; DI void bfly_fwd(float2 a0, float2 a1, float2 a2, float2 a3, float r, float2& o0, float2& o1, float2& o2, float2& o3) {
;   float2 t0 = {a0.x + a2.x, a0.y + a2.y}, t1 = {a0.x - a2.x, a0.y - a2.y}, t2 = {a1.x + a3.x, a1.y + a3.y}, t3 = {a1.x - a3.x, a1.y - a3.y};
;   float2 b0 = {t0.x + t2.x, t0.y + t2.y}, b2 = {t0.x - t2.x, t0.y - t2.y}, b1 = {t1.x + t3.y, t1.y - t3.x}, b3 = {t1.x - t3.y, t1.y + t3.x};
;   float2 w1 = twid(r), w2 = cmul(w1, w1), w3 = cmul(w2, w1);
;   o0 = b0; o1 = cmul(b1, w1); o2 = cmul(b2, w2); o3 = cmul(b3, w3);
; }
;     ...
;   for (int gg = tid; gg < NBT * (N / 16); gg += NTHR) { const int g = gg & (N / 16 - 1); float2* z = z0 + (gg / (N / 16)) * N; const int jp = g & (Q2 - 1), base = ((g >> lq2) << (lq2 + 4)) + jp; float2 x[4][4];
; #pragma unroll
;     for (int q1 = 0; q1 < 4; ++q1)
; #pragma unroll
;       for (int q2 = 0; q2 < 4; ++q2) x[q1][q2] = z[base + q1 * Q1 + q2 * Q2];
; #pragma unroll
;     for (int q2 = 0; q2 < 4; ++q2) bfly_fwd(x[0][q2], x[1][q2], x[2][q2], x[3][q2], (float)(jp + q2 * Q2) * invM1, x[0][q2], x[1][q2], x[2][q2], x[3][q2]);
; #pragma unroll
;     for (int q1 = 0; q1 < 4; ++q1) bfly_fwd(x[q1][0], x[q1][1], x[q1][2], x[q1][3], (float)jp * invM2, x[q1][0], x[q1][1], x[q1][2], x[q1][3]);
; #pragma unroll
;     for (int q1 = 0; q1 < 4; ++q1)
; #pragma unroll
;       for (int q2 = 0; q2 < 4; ++q2) z[base + q1 * Q1 + q2 * Q2] = x[q1][q2]; }
.LBB0_1635:
	v_ashrrev_i32_e32 v70, 31, v69
	v_lshrrev_b32_e32 v70, 22, v70
	v_add_lshl_u32 v70, v69, v70, 7
	v_and_b32_e32 v70, 0xfffe0000, v70
	v_and_b32_e32 v71, 0x3f00, v68
	v_add_u32_e32 v70, 16, v70
	v_lshlrev_b32_e32 v71, 3, v71
	v_lshlrev_b32_e32 v72, 3, v83
	v_add3_u32 v142, v70, v71, v72
	ds_read2_b64 v[84:87], v142 offset1:16
	ds_read2_b64 v[88:91], v142 offset0:32 offset1:48
	ds_read2_b64 v[92:95], v142 offset0:64 offset1:80
	ds_read2_b64 v[96:99], v142 offset0:96 offset1:112
	ds_read2_b64 v[100:103], v142 offset0:128 offset1:144
	ds_read2_b64 v[104:107], v142 offset0:160 offset1:176
	ds_read2_b64 v[108:111], v142 offset0:192 offset1:208
	ds_read2_b64 v[112:115], v142 offset0:224 offset1:240
	v_cmp_lt_i32_e64 s[12:13], s5, v69
	s_or_b64 s[14:15], s[12:13], s[14:15]
	s_waitcnt lgkmcnt(0)
	v_pk_add_f32 v[74:75], v[84:85], v[100:101]
	v_pk_add_f32 v[122:123], v[86:87], v[102:103]
	v_pk_add_f32 v[118:119], v[92:93], v[108:109]
	v_pk_add_f32 v[126:127], v[94:95], v[110:111]
	v_pk_add_f32 v[116:117], v[84:85], v[100:101] neg_lo:[0,1] neg_hi:[0,1]
	v_pk_add_f32 v[124:125], v[86:87], v[102:103] neg_lo:[0,1] neg_hi:[0,1]
	v_pk_add_f32 v[120:121], v[92:93], v[108:109] neg_lo:[0,1] neg_hi:[0,1]
	v_pk_add_f32 v[128:129], v[94:95], v[110:111] neg_lo:[0,1] neg_hi:[0,1]
	v_pk_add_f32 v[84:85], v[74:75], v[118:119]
	v_pk_add_f32 v[86:87], v[122:123], v[126:127]
	v_pk_add_f32 v[74:75], v[74:75], v[118:119] neg_lo:[0,1] neg_hi:[0,1]
	v_pk_add_f32 v[122:123], v[122:123], v[126:127] neg_lo:[0,1] neg_hi:[0,1]
	v_pk_add_f32 v[118:119], v[116:117], v[120:121] op_sel:[0,1] op_sel_hi:[1,0] neg_hi:[0,1]
	v_pk_add_f32 v[126:127], v[124:125], v[128:129] op_sel:[0,1] op_sel_hi:[1,0] neg_hi:[0,1]
	v_pk_add_f32 v[116:117], v[116:117], v[120:121] op_sel:[0,1] op_sel_hi:[1,0] neg_lo:[0,1]
	v_pk_add_f32 v[124:125], v[124:125], v[128:129] op_sel:[0,1] op_sel_hi:[1,0] neg_lo:[0,1]
	v_pk_mul_f32 v[130:131], v[74:75], v[220:221] op_sel:[1,1] op_sel_hi:[1,0]
	v_pk_mul_f32 v[134:135], v[122:123], v[226:227] op_sel:[1,1] op_sel_hi:[1,0]
	v_pk_mul_f32 v[132:133], v[118:119], v[218:219] op_sel:[1,1] op_sel_hi:[1,0]
	v_pk_mul_f32 v[136:137], v[126:127], v[224:225] op_sel:[1,1] op_sel_hi:[1,0]
	v_pk_fma_f32 v[100:101], v[74:75], v[220:221], v[130:131] op_sel_hi:[0,1,1] neg_lo:[0,0,1]
	v_pk_fma_f32 v[102:103], v[122:123], v[226:227], v[134:135] op_sel_hi:[0,1,1] neg_lo:[0,0,1]
	v_pk_mul_f32 v[130:131], v[116:117], v[222:223] op_sel:[1,1] op_sel_hi:[1,0]
	v_pk_mul_f32 v[134:135], v[124:125], v[228:229] op_sel:[1,1] op_sel_hi:[1,0]
	v_pk_fma_f32 v[92:93], v[118:119], v[218:219], v[132:133] op_sel_hi:[0,1,1] neg_lo:[0,0,1]
	v_pk_fma_f32 v[94:95], v[126:127], v[224:225], v[136:137] op_sel_hi:[0,1,1] neg_lo:[0,0,1]
	v_pk_fma_f32 v[108:109], v[116:117], v[222:223], v[130:131] op_sel_hi:[0,1,1] neg_lo:[0,0,1]
	v_pk_fma_f32 v[110:111], v[124:125], v[228:229], v[134:135] op_sel_hi:[0,1,1] neg_lo:[0,0,1]
	v_pk_add_f32 v[74:75], v[88:89], v[104:105]
	v_pk_add_f32 v[122:123], v[90:91], v[106:107]
	v_pk_add_f32 v[118:119], v[96:97], v[112:113]
	v_pk_add_f32 v[126:127], v[98:99], v[114:115]
	v_pk_add_f32 v[116:117], v[88:89], v[104:105] neg_lo:[0,1] neg_hi:[0,1]
	v_pk_add_f32 v[124:125], v[90:91], v[106:107] neg_lo:[0,1] neg_hi:[0,1]
	v_pk_add_f32 v[120:121], v[96:97], v[112:113] neg_lo:[0,1] neg_hi:[0,1]
	v_pk_add_f32 v[128:129], v[98:99], v[114:115] neg_lo:[0,1] neg_hi:[0,1]
	v_pk_add_f32 v[88:89], v[74:75], v[118:119]
	v_pk_add_f32 v[90:91], v[122:123], v[126:127]
	v_pk_add_f32 v[74:75], v[74:75], v[118:119] neg_lo:[0,1] neg_hi:[0,1]
	v_pk_add_f32 v[122:123], v[122:123], v[126:127] neg_lo:[0,1] neg_hi:[0,1]
	v_pk_add_f32 v[118:119], v[116:117], v[120:121] op_sel:[0,1] op_sel_hi:[1,0] neg_hi:[0,1]
	v_pk_add_f32 v[126:127], v[124:125], v[128:129] op_sel:[0,1] op_sel_hi:[1,0] neg_hi:[0,1]
	v_pk_add_f32 v[116:117], v[116:117], v[120:121] op_sel:[0,1] op_sel_hi:[1,0] neg_lo:[0,1]
	v_pk_add_f32 v[124:125], v[124:125], v[128:129] op_sel:[0,1] op_sel_hi:[1,0] neg_lo:[0,1]
	v_pk_mul_f32 v[130:131], v[74:75], v[232:233] op_sel:[1,1] op_sel_hi:[1,0]
	v_pk_mul_f32 v[134:135], v[122:123], v[238:239] op_sel:[1,1] op_sel_hi:[1,0]
	v_pk_mul_f32 v[132:133], v[118:119], v[230:231] op_sel:[1,1] op_sel_hi:[1,0]
	v_pk_mul_f32 v[136:137], v[126:127], v[236:237] op_sel:[1,1] op_sel_hi:[1,0]
	v_pk_fma_f32 v[104:105], v[74:75], v[232:233], v[130:131] op_sel_hi:[0,1,1] neg_lo:[0,0,1]
	v_pk_fma_f32 v[106:107], v[122:123], v[238:239], v[134:135] op_sel_hi:[0,1,1] neg_lo:[0,0,1]
	v_pk_mul_f32 v[130:131], v[116:117], v[234:235] op_sel:[1,1] op_sel_hi:[1,0]
	v_pk_mul_f32 v[134:135], v[124:125], v[242:243] op_sel:[1,1] op_sel_hi:[1,0]
	v_pk_fma_f32 v[96:97], v[118:119], v[230:231], v[132:133] op_sel_hi:[0,1,1] neg_lo:[0,0,1]
	v_pk_fma_f32 v[98:99], v[126:127], v[236:237], v[136:137] op_sel_hi:[0,1,1] neg_lo:[0,0,1]
	v_pk_fma_f32 v[112:113], v[116:117], v[234:235], v[130:131] op_sel_hi:[0,1,1] neg_lo:[0,0,1]
; DI float2 twid(float r) { return float2{__builtin_amdgcn_cosf(r), -__builtin_amdgcn_sinf(r)}; }
; DI void bfly_fwd(float2 a0, float2 a1, float2 a2, float2 a3, float r, float2& o0, float2& o1, float2& o2, float2& o3) {
;   float2 t0 = {a0.x + a2.x, a0.y + a2.y}, t1 = {a0.x - a2.x, a0.y - a2.y}, t2 = {a1.x + a3.x, a1.y + a3.y}, t3 = {a1.x - a3.x, a1.y - a3.y};
;   float2 b0 = {t0.x + t2.x, t0.y + t2.y}, b2 = {t0.x - t2.x, t0.y - t2.y}, b1 = {t1.x + t3.y, t1.y - t3.x}, b3 = {t1.x - t3.y, t1.y + t3.x};
;   float2 w1 = twid(r), w2 = cmul(w1, w1), w3 = cmul(w2, w1);
;   o0 = b0; o1 = cmul(b1, w1); o2 = cmul(b2, w2); o3 = cmul(b3, w3);
; }
;     ...
;   for (int gg = tid; gg < NBT * (N / 16); gg += NTHR) { const int g = gg & (N / 16 - 1); float2* z = z0 + (gg / (N / 16)) * N; const int jp = g & (Q2 - 1), base = ((g >> lq2) << (lq2 + 4)) + jp; float2 x[4][4];
; #pragma unroll
;     for (int q1 = 0; q1 < 4; ++q1)
; #pragma unroll
;       for (int q2 = 0; q2 < 4; ++q2) x[q1][q2] = z[base + q1 * Q1 + q2 * Q2];
; #pragma unroll
;     for (int q2 = 0; q2 < 4; ++q2) bfly_fwd(x[0][q2], x[1][q2], x[2][q2], x[3][q2], (float)(jp + q2 * Q2) * invM1, x[0][q2], x[1][q2], x[2][q2], x[3][q2]);
; #pragma unroll
;     for (int q1 = 0; q1 < 4; ++q1) bfly_fwd(x[q1][0], x[q1][1], x[q1][2], x[q1][3], (float)jp * invM2, x[q1][0], x[q1][1], x[q1][2], x[q1][3]);
; #pragma unroll
;     for (int q1 = 0; q1 < 4; ++q1)
; #pragma unroll
;       for (int q2 = 0; q2 < 4; ++q2) z[base + q1 * Q1 + q2 * Q2] = x[q1][q2]; }
	v_pk_fma_f32 v[114:115], v[124:125], v[242:243], v[134:135] op_sel_hi:[0,1,1] neg_lo:[0,0,1]
	v_pk_add_f32 v[74:75], v[84:85], v[88:89]
	v_pk_add_f32 v[122:123], v[92:93], v[96:97]
	v_pk_add_f32 v[118:119], v[86:87], v[90:91]
	v_pk_add_f32 v[126:127], v[94:95], v[98:99]
	v_pk_add_f32 v[116:117], v[84:85], v[88:89] neg_lo:[0,1] neg_hi:[0,1]
	v_pk_add_f32 v[124:125], v[92:93], v[96:97] neg_lo:[0,1] neg_hi:[0,1]
	v_pk_add_f32 v[120:121], v[86:87], v[90:91] neg_lo:[0,1] neg_hi:[0,1]
	v_pk_add_f32 v[128:129], v[94:95], v[98:99] neg_lo:[0,1] neg_hi:[0,1]
	v_pk_add_f32 v[84:85], v[74:75], v[118:119]
	v_pk_add_f32 v[92:93], v[122:123], v[126:127]
	v_pk_add_f32 v[74:75], v[74:75], v[118:119] neg_lo:[0,1] neg_hi:[0,1]
	v_pk_add_f32 v[122:123], v[122:123], v[126:127] neg_lo:[0,1] neg_hi:[0,1]
	v_pk_add_f32 v[118:119], v[116:117], v[120:121] op_sel:[0,1] op_sel_hi:[1,0] neg_hi:[0,1]
	v_pk_add_f32 v[126:127], v[124:125], v[128:129] op_sel:[0,1] op_sel_hi:[1,0] neg_hi:[0,1]
	v_pk_add_f32 v[116:117], v[116:117], v[120:121] op_sel:[0,1] op_sel_hi:[1,0] neg_lo:[0,1]
	v_pk_add_f32 v[124:125], v[124:125], v[128:129] op_sel:[0,1] op_sel_hi:[1,0] neg_lo:[0,1]
	v_pk_mul_f32 v[130:131], v[74:75], v[246:247] op_sel:[1,1] op_sel_hi:[1,0]
	v_pk_mul_f32 v[134:135], v[122:123], v[246:247] op_sel:[1,1] op_sel_hi:[1,0]
	v_pk_mul_f32 v[132:133], v[118:119], v[244:245] op_sel:[1,1] op_sel_hi:[1,0]
	v_pk_mul_f32 v[136:137], v[126:127], v[244:245] op_sel:[1,1] op_sel_hi:[1,0]
	v_pk_fma_f32 v[88:89], v[74:75], v[246:247], v[130:131] op_sel_hi:[0,1,1] neg_lo:[0,0,1]
	v_pk_fma_f32 v[96:97], v[122:123], v[246:247], v[134:135] op_sel_hi:[0,1,1] neg_lo:[0,0,1]
	v_pk_mul_f32 v[130:131], v[116:117], v[248:249] op_sel:[1,1] op_sel_hi:[1,0]
	v_pk_mul_f32 v[134:135], v[124:125], v[248:249] op_sel:[1,1] op_sel_hi:[1,0]
	v_pk_fma_f32 v[86:87], v[118:119], v[244:245], v[132:133] op_sel_hi:[0,1,1] neg_lo:[0,0,1]
	v_pk_fma_f32 v[94:95], v[126:127], v[244:245], v[136:137] op_sel_hi:[0,1,1] neg_lo:[0,0,1]
	v_pk_fma_f32 v[90:91], v[116:117], v[248:249], v[130:131] op_sel_hi:[0,1,1] neg_lo:[0,0,1]
	v_pk_fma_f32 v[98:99], v[124:125], v[248:249], v[134:135] op_sel_hi:[0,1,1] neg_lo:[0,0,1]
	v_pk_add_f32 v[74:75], v[100:101], v[104:105]
	v_pk_add_f32 v[122:123], v[108:109], v[112:113]
	v_pk_add_f32 v[118:119], v[102:103], v[106:107]
	v_pk_add_f32 v[126:127], v[110:111], v[114:115]
	v_pk_add_f32 v[116:117], v[100:101], v[104:105] neg_lo:[0,1] neg_hi:[0,1]
	v_pk_add_f32 v[124:125], v[108:109], v[112:113] neg_lo:[0,1] neg_hi:[0,1]
	v_pk_add_f32 v[120:121], v[102:103], v[106:107] neg_lo:[0,1] neg_hi:[0,1]
	v_pk_add_f32 v[128:129], v[110:111], v[114:115] neg_lo:[0,1] neg_hi:[0,1]
	v_pk_add_f32 v[100:101], v[74:75], v[118:119]
	v_pk_add_f32 v[108:109], v[122:123], v[126:127]
	v_pk_add_f32 v[74:75], v[74:75], v[118:119] neg_lo:[0,1] neg_hi:[0,1]
	v_pk_add_f32 v[122:123], v[122:123], v[126:127] neg_lo:[0,1] neg_hi:[0,1]
	v_pk_add_f32 v[118:119], v[116:117], v[120:121] op_sel:[0,1] op_sel_hi:[1,0] neg_hi:[0,1]
	v_pk_add_f32 v[126:127], v[124:125], v[128:129] op_sel:[0,1] op_sel_hi:[1,0] neg_hi:[0,1]
	v_pk_add_f32 v[116:117], v[116:117], v[120:121] op_sel:[0,1] op_sel_hi:[1,0] neg_lo:[0,1]
	v_pk_add_f32 v[124:125], v[124:125], v[128:129] op_sel:[0,1] op_sel_hi:[1,0] neg_lo:[0,1]
	v_pk_mul_f32 v[130:131], v[74:75], v[246:247] op_sel:[1,1] op_sel_hi:[1,0]
	v_pk_mul_f32 v[134:135], v[122:123], v[246:247] op_sel:[1,1] op_sel_hi:[1,0]
	v_pk_mul_f32 v[132:133], v[118:119], v[244:245] op_sel:[1,1] op_sel_hi:[1,0]
	v_pk_mul_f32 v[136:137], v[126:127], v[244:245] op_sel:[1,1] op_sel_hi:[1,0]
	v_pk_fma_f32 v[104:105], v[74:75], v[246:247], v[130:131] op_sel_hi:[0,1,1] neg_lo:[0,0,1]
	v_pk_fma_f32 v[112:113], v[122:123], v[246:247], v[134:135] op_sel_hi:[0,1,1] neg_lo:[0,0,1]
	v_pk_mul_f32 v[130:131], v[116:117], v[248:249] op_sel:[1,1] op_sel_hi:[1,0]
	v_pk_mul_f32 v[134:135], v[124:125], v[248:249] op_sel:[1,1] op_sel_hi:[1,0]
	v_pk_fma_f32 v[102:103], v[118:119], v[244:245], v[132:133] op_sel_hi:[0,1,1] neg_lo:[0,0,1]
	v_pk_fma_f32 v[110:111], v[126:127], v[244:245], v[136:137] op_sel_hi:[0,1,1] neg_lo:[0,0,1]
	v_pk_fma_f32 v[106:107], v[116:117], v[248:249], v[130:131] op_sel_hi:[0,1,1] neg_lo:[0,0,1]
	v_pk_fma_f32 v[114:115], v[124:125], v[248:249], v[134:135] op_sel_hi:[0,1,1] neg_lo:[0,0,1]
	s_nop 0
	ds_write2_b64 v142, v[84:85], v[86:87] offset1:16
	ds_write2_b64 v142, v[88:89], v[90:91] offset0:32 offset1:48
	ds_write2_b64 v142, v[92:93], v[94:95] offset0:64 offset1:80
	ds_write2_b64 v142, v[96:97], v[98:99] offset0:96 offset1:112
	ds_write2_b64 v142, v[100:101], v[102:103] offset0:128 offset1:144
	ds_write2_b64 v142, v[104:105], v[106:107] offset0:160 offset1:176
	ds_write2_b64 v142, v[108:109], v[110:111] offset0:192 offset1:208
	ds_write2_b64 v142, v[112:113], v[114:115] offset0:224 offset1:240
	v_add_u32_e32 v68, 0x2000, v68
	v_add_u32_e32 v70, 0x200, v69
	v_mov_b32_e32 v69, v70
	s_andn2_b64 exec, exec, s[14:15]
	s_cbranch_execnz .LBB0_1635

; DI float2 twid(float r) { return float2{__builtin_amdgcn_cosf(r), -__builtin_amdgcn_sinf(r)}; }
; DI void bfly_inv(float2 s0, float2 s1, float2 s2, float2 s3, float r, float2& o0, float2& o1, float2& o2, float2& o3) {
;   float2 w1 = twid(r), w2 = cmul(w1, w1), w3 = cmul(w2, w1);
;   const int lq1 = lq2 + 2, Q1 = 1 << lq1, Q2 = 1 << lq2; const float invM1 = 1.f / (float)(4 << lq1), invM2 = 1.f / (float)(4 << lq2);
;   for (int gg = tid; gg < NBT * (N / 16); gg += NTHR) { const int g = gg & (N / 16 - 1); float2* z = z0 + (gg / (N / 16)) * N; const int jp = g & (Q2 - 1), base = ((g >> lq2) << (lq2 + 4)) + jp; float2 x[4][4];
; #pragma unroll
;     for (int q1 = 0; q1 < 4; ++q1)
; #pragma unroll
;       for (int q2 = 0; q2 < 4; ++q2) x[q1][q2] = z[base + q1 * Q1 + q2 * Q2];
; #pragma unroll
;     for (int q1 = 0; q1 < 4; ++q1) bfly_inv(x[q1][0], x[q1][1], x[q1][2], x[q1][3], (float)jp * invM2, x[q1][0], x[q1][1], x[q1][2], x[q1][3]);
; #pragma unroll
;     for (int q2 = 0; q2 < 4; ++q2) bfly_inv(x[0][q2], x[1][q2], x[2][q2], x[3][q2], (float)(jp + q2 * Q2) * invM1, x[0][q2], x[1][q2], x[2][q2], x[3][q2]);
.LBB0_1648:
	s_or_b64 exec, exec, s[0:1]
	s_waitcnt lgkmcnt(0)
	s_barrier
	s_and_saveexec_b64 s[14:15], vcc
	s_cbranch_execz .LBB0_1651
	v_mul_f32_e32 v4, 0x3c800000, v67
	v_sin_f32_e32 v5, v4
	v_cos_f32_e32 v6, v4
	s_mov_b64 s[0:1], 0
	v_mov_b32_e32 v84, v76
	v_xor_b32_e32 v10, 0x80000000, v5
	v_mov_b32_e32 v4, v6
	v_mov_b32_e32 v8, v10
	v_mov_b32_e32 v9, v5
	v_mov_b32_e32 v7, v6
	v_mov_b32_e32 v11, v6
	v_pk_mul_f32 v[12:13], v[4:5], v[8:9]
	v_mov_b32_e32 v58, v6
	v_pk_fma_f32 v[8:9], v[6:7], v[10:11], v[12:13] op_sel_hi:[0,1,1] neg_lo:[0,0,1] neg_hi:[0,0,1]
	v_pk_fma_f32 v[10:11], v[6:7], v[10:11], v[12:13] op_sel_hi:[0,1,1]
	v_pk_mov_b32 v[12:13], v[8:9], v[10:11] op_sel:[1,0]
	v_mul_f32_e32 v8, 0x3b800000, v67
	v_sin_f32_e32 v14, v8
	v_cos_f32_e32 v16, v8
	v_mov_b32_e32 v18, v10
	v_mov_b32_e32 v19, v9
	v_mul_f32_e32 v8, v14, v14
	v_fma_f32 v24, v16, v16, -v8
	v_cvt_f32_ubyte0_e32 v8, v66
	v_mul_f32_e32 v8, 0x3b800000, v8
	v_sin_f32_e32 v27, v8
	v_cos_f32_e32 v29, v8
	v_pk_mul_f32 v[20:21], v[4:5], v[12:13] op_sel:[1,0]
	v_mul_f32_e64 v11, v16, -v14
	v_pk_fma_f32 v[12:13], v[6:7], v[18:19], v[20:21] op_sel_hi:[0,1,1]
	v_pk_fma_f32 v[18:19], v[6:7], v[18:19], v[20:21] op_sel_hi:[0,1,1] neg_lo:[0,0,1] neg_hi:[0,0,1]
	v_add_f32_e32 v20, v11, v11
	v_mul_f32_e32 v8, v14, v24
	v_fma_f32 v22, v16, v20, -v8
	v_mul_f32_e32 v8, v27, v27
	v_fma_f32 v30, v29, v29, -v8
	v_mul_f32_e64 v8, v29, -v27
	v_add_f32_e32 v32, v8, v8
	v_cvt_f32_ubyte0_e32 v8, v65
	v_mul_f32_e32 v8, 0x3b800000, v8
	v_sin_f32_e32 v35, v8
	v_cos_f32_e32 v37, v8
	v_mul_f32_e32 v8, v27, v30
	v_fma_f32 v28, v29, v32, -v8
	v_mul_f32_e32 v8, v35, v35
	v_fma_f32 v38, v37, v37, -v8
	v_mul_f32_e64 v8, v37, -v35
	v_add_f32_e32 v40, v8, v8
	v_cvt_f32_ubyte0_e32 v8, v64
	v_mul_f32_e32 v8, 0x3b800000, v8
	v_sin_f32_e32 v42, v8
	v_cos_f32_e32 v44, v8
	v_mul_f32_e32 v23, v14, v20
	v_mul_f32_e32 v26, v27, v32
	v_xor_b32_e32 v45, 0x80000000, v42
	v_mov_b32_e32 v43, v44
	v_mov_b32_e32 v46, v42
	v_mov_b32_e32 v47, v45
	v_pk_mul_f32 v[48:49], v[42:43], v[46:47]
	v_mul_f32_e32 v34, v35, v40
	v_pk_fma_f32 v[46:47], v[44:45], v[44:45], v[48:49] op_sel_hi:[0,1,1] neg_lo:[0,0,1] neg_hi:[0,0,1]
	v_pk_fma_f32 v[62:63], v[44:45], v[44:45], v[48:49] op_sel_hi:[0,1,1]
	v_pk_mov_b32 v[50:51], v[62:63], v[46:47] op_sel:[1,0]
	v_mul_f32_e32 v8, v35, v38
	v_mov_b32_e32 v48, v46
	v_mov_b32_e32 v49, v63
	v_pk_mul_f32 v[50:51], v[42:43], v[50:51] op_sel_hi:[0,1]
	v_fmac_f32_e32 v23, v16, v24
	v_fmac_f32_e32 v26, v29, v30
	v_fmac_f32_e32 v34, v37, v38
	v_fma_f32 v36, v37, v40, -v8
	v_pk_fma_f32 v[60:61], v[44:45], v[48:49], v[50:51] op_sel_hi:[0,1,1]
	v_pk_fma_f32 v[48:49], v[44:45], v[48:49], v[50:51] op_sel_hi:[0,1,1] neg_lo:[0,0,1] neg_hi:[0,0,1]
	v_mov_b32_e32 v21, v14
	v_mov_b32_e32 v19, v13
	v_mov_b32_e32 v48, v60
	v_mov_b32_e32 v11, v10
	v_mov_b32_e32 v31, v30
	v_mov_b32_e32 v33, v32
	v_pk_mov_b32 v[50:51], v[28:29], v[26:27] op_sel:[1,0]
	v_pk_mov_b32 v[52:53], v[26:27], v[28:29] op_sel:[1,0]
	v_mov_b32_e32 v39, v38
	v_pk_mov_b32 v[54:55], v[36:37], v[34:35] op_sel:[1,0]
	v_pk_mov_b32 v[56:57], v[34:35], v[36:37] op_sel:[1,0]
	v_mov_b32_e32 v59, v18
	v_mov_b32_e32 v12, v5
	v_pk_mov_b32 v[60:61], v[62:63], v[60:61] op_sel:[1,0]
	v_mov_b32_e32 v47, v49
	v_mov_b32_e32 v45, v46
	v_mov_b32_e32 v43, v63
	v_mov_b32_e32 v63, v18
	v_mov_b32_e32 v64, v5
	v_mov_b32_e32 v65, v5
	v_mov_b32_e32 v8, v9
	v_mov_b32_e32 v66, v6
	v_mov_b32_e32 v67, v13
	v_mov_b32_e32 v68, v5
	v_mov_b32_e32 v69, v18
	v_mov_b32_e32 v70, v13
	v_mov_b32_e32 v71, v13
	v_mov_b32_e32 v72, v18
	v_mov_b32_e32 v73, v18
	v_mov_b32_e32 v25, v16
	v_pk_mov_b32 v[74:75], v[22:23], v[20:21] op_sel:[1,0]
	v_mov_b32_e32 v41, v40
	v_lshlrev_b32_e32 v62, 4, v76
	v_and_b32_e32 v241, 0xf, v84
	v_add_u32_e32 v250, 0x0, v241
	v_cvt_f32_u32_e32 v250, v250
	v_mul_f32_e32 v250, 0x3b800000, v250
	v_cos_f32_e32 v218, v250
	v_sin_f32_e32 v219, v250
	s_nop 1
	v_xor_b32_e32 v219, 0x80000000, v219
	s_nop 0
	v_pk_mul_f32 v[134:135], v[218:219], v[218:219] op_sel:[1,1] op_sel_hi:[1,0]
	s_nop 0
	v_pk_fma_f32 v[220:221], v[218:219], v[218:219], v[134:135] op_sel_hi:[0,1,1] neg_lo:[0,0,1]
	s_nop 0
	v_pk_mul_f32 v[134:135], v[220:221], v[218:219] op_sel:[1,1] op_sel_hi:[1,0]
	s_nop 0
	v_pk_fma_f32 v[222:223], v[220:221], v[218:219], v[134:135] op_sel_hi:[0,1,1] neg_lo:[0,0,1]
	s_nop 0
	v_xor_b32_e32 v219, 0x80000000, v219
	v_xor_b32_e32 v221, 0x80000000, v221
	v_xor_b32_e32 v223, 0x80000000, v223
	v_add_u32_e32 v250, 0x10, v241
	v_cvt_f32_u32_e32 v250, v250
	v_mul_f32_e32 v250, 0x3b800000, v250
	v_cos_f32_e32 v224, v250
	v_sin_f32_e32 v225, v250
	s_nop 1
	v_xor_b32_e32 v225, 0x80000000, v225
	s_nop 0
	v_pk_mul_f32 v[134:135], v[224:225], v[224:225] op_sel:[1,1] op_sel_hi:[1,0]
	s_nop 0
	v_pk_fma_f32 v[226:227], v[224:225], v[224:225], v[134:135] op_sel_hi:[0,1,1] neg_lo:[0,0,1]
	s_nop 0
	v_pk_mul_f32 v[134:135], v[226:227], v[224:225] op_sel:[1,1] op_sel_hi:[1,0]
	s_nop 0
	v_pk_fma_f32 v[228:229], v[226:227], v[224:225], v[134:135] op_sel_hi:[0,1,1] neg_lo:[0,0,1]
	s_nop 0
	v_xor_b32_e32 v225, 0x80000000, v225
	v_xor_b32_e32 v227, 0x80000000, v227
	v_xor_b32_e32 v229, 0x80000000, v229
	v_add_u32_e32 v250, 0x20, v241
	v_cvt_f32_u32_e32 v250, v250
	v_mul_f32_e32 v250, 0x3b800000, v250
	v_cos_f32_e32 v230, v250
	v_sin_f32_e32 v231, v250
	s_nop 1
	v_xor_b32_e32 v231, 0x80000000, v231
	s_nop 0
	v_pk_mul_f32 v[134:135], v[230:231], v[230:231] op_sel:[1,1] op_sel_hi:[1,0]
	s_nop 0
	v_pk_fma_f32 v[232:233], v[230:231], v[230:231], v[134:135] op_sel_hi:[0,1,1] neg_lo:[0,0,1]
	s_nop 0
	v_pk_mul_f32 v[134:135], v[232:233], v[230:231] op_sel:[1,1] op_sel_hi:[1,0]
	s_nop 0
; DI float2 twid(float r) { return float2{__builtin_amdgcn_cosf(r), -__builtin_amdgcn_sinf(r)}; }
; DI void bfly_inv(float2 s0, float2 s1, float2 s2, float2 s3, float r, float2& o0, float2& o1, float2& o2, float2& o3) {
;   float2 w1 = twid(r), w2 = cmul(w1, w1), w3 = cmul(w2, w1);
;   float2 c0 = s0, c1 = cmulc(s1, w1), c2 = cmulc(s2, w2), c3 = cmulc(s3, w3);
;   float2 t0 = {c0.x + c2.x, c0.y + c2.y}, t1 = {c0.x - c2.x, c0.y - c2.y}, t2 = {c1.x + c3.x, c1.y + c3.y}, t3 = {c1.x - c3.x, c1.y - c3.y};
;   o0 = float2{t0.x + t2.x, t0.y + t2.y}; o2 = float2{t0.x - t2.x, t0.y - t2.y}; o1 = float2{t1.x - t3.y, t1.y + t3.x}; o3 = float2{t1.x + t3.y, t1.y - t3.x};
; }
;     ...
;   for (int gg = tid; gg < NBT * (N / 16); gg += NTHR) { const int g = gg & (N / 16 - 1); float2* z = z0 + (gg / (N / 16)) * N; const int jp = g & (Q2 - 1), base = ((g >> lq2) << (lq2 + 4)) + jp; float2 x[4][4];
; #pragma unroll
;     for (int q1 = 0; q1 < 4; ++q1)
; #pragma unroll
;       for (int q2 = 0; q2 < 4; ++q2) x[q1][q2] = z[base + q1 * Q1 + q2 * Q2];
; #pragma unroll
;     for (int q1 = 0; q1 < 4; ++q1) bfly_inv(x[q1][0], x[q1][1], x[q1][2], x[q1][3], (float)jp * invM2, x[q1][0], x[q1][1], x[q1][2], x[q1][3]);
; #pragma unroll
;     for (int q2 = 0; q2 < 4; ++q2) bfly_inv(x[0][q2], x[1][q2], x[2][q2], x[3][q2], (float)(jp + q2 * Q2) * invM1, x[0][q2], x[1][q2], x[2][q2], x[3][q2]);
; #pragma unroll
;     for (int q1 = 0; q1 < 4; ++q1)
; #pragma unroll
;       for (int q2 = 0; q2 < 4; ++q2) z[base + q1 * Q1 + q2 * Q2] = x[q1][q2]; }
	v_pk_fma_f32 v[234:235], v[232:233], v[230:231], v[134:135] op_sel_hi:[0,1,1] neg_lo:[0,0,1]
	s_nop 0
	v_xor_b32_e32 v231, 0x80000000, v231
	v_xor_b32_e32 v233, 0x80000000, v233
	v_xor_b32_e32 v235, 0x80000000, v235
	v_add_u32_e32 v250, 0x30, v241
	v_cvt_f32_u32_e32 v250, v250
	v_mul_f32_e32 v250, 0x3b800000, v250
	v_cos_f32_e32 v236, v250
	v_sin_f32_e32 v237, v250
	s_nop 1
	v_xor_b32_e32 v237, 0x80000000, v237
	s_nop 0
	v_pk_mul_f32 v[134:135], v[236:237], v[236:237] op_sel:[1,1] op_sel_hi:[1,0]
	s_nop 0
	v_pk_fma_f32 v[238:239], v[236:237], v[236:237], v[134:135] op_sel_hi:[0,1,1] neg_lo:[0,0,1]
	s_nop 0
	v_pk_mul_f32 v[134:135], v[238:239], v[236:237] op_sel:[1,1] op_sel_hi:[1,0]
	s_nop 0
	v_pk_fma_f32 v[242:243], v[238:239], v[236:237], v[134:135] op_sel_hi:[0,1,1] neg_lo:[0,0,1]
	s_nop 0
	v_xor_b32_e32 v237, 0x80000000, v237
	v_xor_b32_e32 v239, 0x80000000, v239
	v_xor_b32_e32 v243, 0x80000000, v243
	v_cvt_f32_u32_e32 v250, v241
	v_mul_f32_e32 v250, 0x3c800000, v250
	v_cos_f32_e32 v244, v250
	v_sin_f32_e32 v245, v250
	s_nop 1
	v_xor_b32_e32 v245, 0x80000000, v245
	s_nop 0
	v_pk_mul_f32 v[134:135], v[244:245], v[244:245] op_sel:[1,1] op_sel_hi:[1,0]
	s_nop 0
	v_pk_fma_f32 v[246:247], v[244:245], v[244:245], v[134:135] op_sel_hi:[0,1,1] neg_lo:[0,0,1]
	s_nop 0
	v_pk_mul_f32 v[134:135], v[246:247], v[244:245] op_sel:[1,1] op_sel_hi:[1,0]
	s_nop 0
	v_pk_fma_f32 v[248:249], v[246:247], v[244:245], v[134:135] op_sel_hi:[0,1,1] neg_lo:[0,0,1]
	s_nop 0
	v_xor_b32_e32 v245, 0x80000000, v245
	v_xor_b32_e32 v247, 0x80000000, v247
	v_xor_b32_e32 v249, 0x80000000, v249
.LBB0_1650:
	v_ashrrev_i32_e32 v15, 31, v84
	v_lshrrev_b32_e32 v15, 22, v15
	v_add_lshl_u32 v15, v84, v15, 7
	v_and_b32_e32 v15, 0xfffe0000, v15
	v_and_b32_e32 v17, 0x3f00, v62
	v_add_u32_e32 v15, 16, v15
	v_lshlrev_b32_e32 v17, 3, v17
	v_lshlrev_b32_e32 v85, 3, v83
	v_add3_u32 v85, v15, v17, v85
	ds_read2_b64 v[86:89], v85 offset0:32 offset1:48
	ds_read2_b64 v[90:93], v85 offset1:16
	ds_read2_b64 v[94:97], v85 offset0:64 offset1:80
	ds_read2_b64 v[98:101], v85 offset0:96 offset1:112
	ds_read2_b64 v[102:105], v85 offset0:128 offset1:144
	ds_read2_b64 v[106:109], v85 offset0:160 offset1:176
	ds_read2_b64 v[110:113], v85 offset0:192 offset1:208
	ds_read2_b64 v[114:117], v85 offset0:224 offset1:240
	v_cmp_lt_i32_e64 s[12:13], s5, v84
	s_or_b64 s[0:1], s[12:13], s[0:1]
	s_waitcnt lgkmcnt(0)
	v_pk_mul_f32 v[134:135], v[92:93], v[244:245] op_sel:[1,1] op_sel_hi:[1,0]
	v_pk_mul_f32 v[138:139], v[96:97], v[244:245] op_sel:[1,1] op_sel_hi:[1,0]
	v_pk_mul_f32 v[136:137], v[86:87], v[246:247] op_sel:[1,1] op_sel_hi:[1,0]
	v_pk_mul_f32 v[140:141], v[98:99], v[246:247] op_sel:[1,1] op_sel_hi:[1,0]
	v_pk_fma_f32 v[92:93], v[92:93], v[244:245], v[134:135] op_sel_hi:[0,1,1] neg_lo:[0,0,1]
	v_pk_fma_f32 v[96:97], v[96:97], v[244:245], v[138:139] op_sel_hi:[0,1,1] neg_lo:[0,0,1]
	v_pk_mul_f32 v[134:135], v[88:89], v[248:249] op_sel:[1,1] op_sel_hi:[1,0]
	v_pk_mul_f32 v[138:139], v[100:101], v[248:249] op_sel:[1,1] op_sel_hi:[1,0]
	v_pk_fma_f32 v[86:87], v[86:87], v[246:247], v[136:137] op_sel_hi:[0,1,1] neg_lo:[0,0,1]
	v_pk_fma_f32 v[98:99], v[98:99], v[246:247], v[140:141] op_sel_hi:[0,1,1] neg_lo:[0,0,1]
	v_pk_fma_f32 v[88:89], v[88:89], v[248:249], v[134:135] op_sel_hi:[0,1,1] neg_lo:[0,0,1]
	v_pk_fma_f32 v[100:101], v[100:101], v[248:249], v[138:139] op_sel_hi:[0,1,1] neg_lo:[0,0,1]
	v_pk_add_f32 v[118:119], v[90:91], v[86:87]
	v_pk_add_f32 v[126:127], v[94:95], v[98:99]
	v_pk_add_f32 v[122:123], v[92:93], v[88:89]
	v_pk_add_f32 v[130:131], v[96:97], v[100:101]
	v_pk_add_f32 v[120:121], v[90:91], v[86:87] neg_lo:[0,1] neg_hi:[0,1]
	v_pk_add_f32 v[128:129], v[94:95], v[98:99] neg_lo:[0,1] neg_hi:[0,1]
	v_pk_add_f32 v[124:125], v[92:93], v[88:89] neg_lo:[0,1] neg_hi:[0,1]
	v_pk_add_f32 v[132:133], v[96:97], v[100:101] neg_lo:[0,1] neg_hi:[0,1]
	v_pk_add_f32 v[90:91], v[118:119], v[122:123]
	v_pk_add_f32 v[94:95], v[126:127], v[130:131]
	v_pk_add_f32 v[86:87], v[118:119], v[122:123] neg_lo:[0,1] neg_hi:[0,1]
	v_pk_add_f32 v[98:99], v[126:127], v[130:131] neg_lo:[0,1] neg_hi:[0,1]
	v_pk_add_f32 v[92:93], v[120:121], v[124:125] op_sel:[0,1] op_sel_hi:[1,0] neg_lo:[0,1]
	v_pk_add_f32 v[96:97], v[128:129], v[132:133] op_sel:[0,1] op_sel_hi:[1,0] neg_lo:[0,1]
	v_pk_add_f32 v[88:89], v[120:121], v[124:125] op_sel:[0,1] op_sel_hi:[1,0] neg_hi:[0,1]
	v_pk_add_f32 v[100:101], v[128:129], v[132:133] op_sel:[0,1] op_sel_hi:[1,0] neg_hi:[0,1]
	v_pk_mul_f32 v[134:135], v[104:105], v[244:245] op_sel:[1,1] op_sel_hi:[1,0]
	v_pk_mul_f32 v[138:139], v[112:113], v[244:245] op_sel:[1,1] op_sel_hi:[1,0]
	v_pk_mul_f32 v[136:137], v[106:107], v[246:247] op_sel:[1,1] op_sel_hi:[1,0]
	v_pk_mul_f32 v[140:141], v[114:115], v[246:247] op_sel:[1,1] op_sel_hi:[1,0]
	v_pk_fma_f32 v[104:105], v[104:105], v[244:245], v[134:135] op_sel_hi:[0,1,1] neg_lo:[0,0,1]
	v_pk_fma_f32 v[112:113], v[112:113], v[244:245], v[138:139] op_sel_hi:[0,1,1] neg_lo:[0,0,1]
	v_pk_mul_f32 v[134:135], v[108:109], v[248:249] op_sel:[1,1] op_sel_hi:[1,0]
	v_pk_mul_f32 v[138:139], v[116:117], v[248:249] op_sel:[1,1] op_sel_hi:[1,0]
	v_pk_fma_f32 v[106:107], v[106:107], v[246:247], v[136:137] op_sel_hi:[0,1,1] neg_lo:[0,0,1]
	v_pk_fma_f32 v[114:115], v[114:115], v[246:247], v[140:141] op_sel_hi:[0,1,1] neg_lo:[0,0,1]
	v_pk_fma_f32 v[108:109], v[108:109], v[248:249], v[134:135] op_sel_hi:[0,1,1] neg_lo:[0,0,1]
	v_pk_fma_f32 v[116:117], v[116:117], v[248:249], v[138:139] op_sel_hi:[0,1,1] neg_lo:[0,0,1]
	v_pk_add_f32 v[118:119], v[102:103], v[106:107]
	v_pk_add_f32 v[126:127], v[110:111], v[114:115]
	v_pk_add_f32 v[122:123], v[104:105], v[108:109]
; DI float2 twid(float r) { return float2{__builtin_amdgcn_cosf(r), -__builtin_amdgcn_sinf(r)}; }
; DI void bfly_inv(float2 s0, float2 s1, float2 s2, float2 s3, float r, float2& o0, float2& o1, float2& o2, float2& o3) {
;   float2 w1 = twid(r), w2 = cmul(w1, w1), w3 = cmul(w2, w1);
;   float2 c0 = s0, c1 = cmulc(s1, w1), c2 = cmulc(s2, w2), c3 = cmulc(s3, w3);
;   float2 t0 = {c0.x + c2.x, c0.y + c2.y}, t1 = {c0.x - c2.x, c0.y - c2.y}, t2 = {c1.x + c3.x, c1.y + c3.y}, t3 = {c1.x - c3.x, c1.y - c3.y};
;   o0 = float2{t0.x + t2.x, t0.y + t2.y}; o2 = float2{t0.x - t2.x, t0.y - t2.y}; o1 = float2{t1.x - t3.y, t1.y + t3.x}; o3 = float2{t1.x + t3.y, t1.y - t3.x};
; }
;     ...
;   for (int gg = tid; gg < NBT * (N / 16); gg += NTHR) { const int g = gg & (N / 16 - 1); float2* z = z0 + (gg / (N / 16)) * N; const int jp = g & (Q2 - 1), base = ((g >> lq2) << (lq2 + 4)) + jp; float2 x[4][4];
; #pragma unroll
;     for (int q1 = 0; q1 < 4; ++q1)
; #pragma unroll
;       for (int q2 = 0; q2 < 4; ++q2) x[q1][q2] = z[base + q1 * Q1 + q2 * Q2];
; #pragma unroll
;     for (int q1 = 0; q1 < 4; ++q1) bfly_inv(x[q1][0], x[q1][1], x[q1][2], x[q1][3], (float)jp * invM2, x[q1][0], x[q1][1], x[q1][2], x[q1][3]);
; #pragma unroll
;     for (int q2 = 0; q2 < 4; ++q2) bfly_inv(x[0][q2], x[1][q2], x[2][q2], x[3][q2], (float)(jp + q2 * Q2) * invM1, x[0][q2], x[1][q2], x[2][q2], x[3][q2]);
; #pragma unroll
;     for (int q1 = 0; q1 < 4; ++q1)
; #pragma unroll
;       for (int q2 = 0; q2 < 4; ++q2) z[base + q1 * Q1 + q2 * Q2] = x[q1][q2]; }
	v_pk_add_f32 v[130:131], v[112:113], v[116:117]
	v_pk_add_f32 v[120:121], v[102:103], v[106:107] neg_lo:[0,1] neg_hi:[0,1]
	v_pk_add_f32 v[128:129], v[110:111], v[114:115] neg_lo:[0,1] neg_hi:[0,1]
	v_pk_add_f32 v[124:125], v[104:105], v[108:109] neg_lo:[0,1] neg_hi:[0,1]
	v_pk_add_f32 v[132:133], v[112:113], v[116:117] neg_lo:[0,1] neg_hi:[0,1]
	v_pk_add_f32 v[102:103], v[118:119], v[122:123]
	v_pk_add_f32 v[110:111], v[126:127], v[130:131]
	v_pk_add_f32 v[106:107], v[118:119], v[122:123] neg_lo:[0,1] neg_hi:[0,1]
	v_pk_add_f32 v[114:115], v[126:127], v[130:131] neg_lo:[0,1] neg_hi:[0,1]
	v_pk_add_f32 v[104:105], v[120:121], v[124:125] op_sel:[0,1] op_sel_hi:[1,0] neg_lo:[0,1]
	v_pk_add_f32 v[112:113], v[128:129], v[132:133] op_sel:[0,1] op_sel_hi:[1,0] neg_lo:[0,1]
	v_pk_add_f32 v[108:109], v[120:121], v[124:125] op_sel:[0,1] op_sel_hi:[1,0] neg_hi:[0,1]
	v_pk_add_f32 v[116:117], v[128:129], v[132:133] op_sel:[0,1] op_sel_hi:[1,0] neg_hi:[0,1]
	v_pk_mul_f32 v[134:135], v[94:95], v[218:219] op_sel:[1,1] op_sel_hi:[1,0]
	v_pk_mul_f32 v[138:139], v[96:97], v[224:225] op_sel:[1,1] op_sel_hi:[1,0]
	v_pk_mul_f32 v[136:137], v[102:103], v[220:221] op_sel:[1,1] op_sel_hi:[1,0]
	v_pk_mul_f32 v[140:141], v[104:105], v[226:227] op_sel:[1,1] op_sel_hi:[1,0]
	v_pk_fma_f32 v[94:95], v[94:95], v[218:219], v[134:135] op_sel_hi:[0,1,1] neg_lo:[0,0,1]
	v_pk_fma_f32 v[96:97], v[96:97], v[224:225], v[138:139] op_sel_hi:[0,1,1] neg_lo:[0,0,1]
	v_pk_mul_f32 v[134:135], v[110:111], v[222:223] op_sel:[1,1] op_sel_hi:[1,0]
	v_pk_mul_f32 v[138:139], v[112:113], v[228:229] op_sel:[1,1] op_sel_hi:[1,0]
	v_pk_fma_f32 v[102:103], v[102:103], v[220:221], v[136:137] op_sel_hi:[0,1,1] neg_lo:[0,0,1]
	v_pk_fma_f32 v[104:105], v[104:105], v[226:227], v[140:141] op_sel_hi:[0,1,1] neg_lo:[0,0,1]
	v_pk_fma_f32 v[110:111], v[110:111], v[222:223], v[134:135] op_sel_hi:[0,1,1] neg_lo:[0,0,1]
	v_pk_fma_f32 v[112:113], v[112:113], v[228:229], v[138:139] op_sel_hi:[0,1,1] neg_lo:[0,0,1]
	v_pk_add_f32 v[118:119], v[90:91], v[102:103]
	v_pk_add_f32 v[126:127], v[92:93], v[104:105]
	v_pk_add_f32 v[122:123], v[94:95], v[110:111]
	v_pk_add_f32 v[130:131], v[96:97], v[112:113]
	v_pk_add_f32 v[120:121], v[90:91], v[102:103] neg_lo:[0,1] neg_hi:[0,1]
	v_pk_add_f32 v[128:129], v[92:93], v[104:105] neg_lo:[0,1] neg_hi:[0,1]
	v_pk_add_f32 v[124:125], v[94:95], v[110:111] neg_lo:[0,1] neg_hi:[0,1]
	v_pk_add_f32 v[132:133], v[96:97], v[112:113] neg_lo:[0,1] neg_hi:[0,1]
	v_pk_add_f32 v[90:91], v[118:119], v[122:123]
	v_pk_add_f32 v[92:93], v[126:127], v[130:131]
	v_pk_add_f32 v[102:103], v[118:119], v[122:123] neg_lo:[0,1] neg_hi:[0,1]
	v_pk_add_f32 v[104:105], v[126:127], v[130:131] neg_lo:[0,1] neg_hi:[0,1]
	v_pk_add_f32 v[94:95], v[120:121], v[124:125] op_sel:[0,1] op_sel_hi:[1,0] neg_lo:[0,1]
	v_pk_add_f32 v[96:97], v[128:129], v[132:133] op_sel:[0,1] op_sel_hi:[1,0] neg_lo:[0,1]
	v_pk_add_f32 v[110:111], v[120:121], v[124:125] op_sel:[0,1] op_sel_hi:[1,0] neg_hi:[0,1]
	v_pk_add_f32 v[112:113], v[128:129], v[132:133] op_sel:[0,1] op_sel_hi:[1,0] neg_hi:[0,1]
	v_pk_mul_f32 v[134:135], v[98:99], v[230:231] op_sel:[1,1] op_sel_hi:[1,0]
	v_pk_mul_f32 v[138:139], v[100:101], v[236:237] op_sel:[1,1] op_sel_hi:[1,0]
	v_pk_mul_f32 v[136:137], v[106:107], v[232:233] op_sel:[1,1] op_sel_hi:[1,0]
	v_pk_mul_f32 v[140:141], v[108:109], v[238:239] op_sel:[1,1] op_sel_hi:[1,0]
	v_pk_fma_f32 v[98:99], v[98:99], v[230:231], v[134:135] op_sel_hi:[0,1,1] neg_lo:[0,0,1]
	v_pk_fma_f32 v[100:101], v[100:101], v[236:237], v[138:139] op_sel_hi:[0,1,1] neg_lo:[0,0,1]
	v_pk_mul_f32 v[134:135], v[114:115], v[234:235] op_sel:[1,1] op_sel_hi:[1,0]
	v_pk_mul_f32 v[138:139], v[116:117], v[242:243] op_sel:[1,1] op_sel_hi:[1,0]
	v_pk_fma_f32 v[106:107], v[106:107], v[232:233], v[136:137] op_sel_hi:[0,1,1] neg_lo:[0,0,1]
	v_pk_fma_f32 v[108:109], v[108:109], v[238:239], v[140:141] op_sel_hi:[0,1,1] neg_lo:[0,0,1]
	v_pk_fma_f32 v[114:115], v[114:115], v[234:235], v[134:135] op_sel_hi:[0,1,1] neg_lo:[0,0,1]
	v_pk_fma_f32 v[116:117], v[116:117], v[242:243], v[138:139] op_sel_hi:[0,1,1] neg_lo:[0,0,1]
	v_pk_add_f32 v[118:119], v[86:87], v[106:107]
	v_pk_add_f32 v[126:127], v[88:89], v[108:109]
	v_pk_add_f32 v[122:123], v[98:99], v[114:115]
	v_pk_add_f32 v[130:131], v[100:101], v[116:117]
	v_pk_add_f32 v[120:121], v[86:87], v[106:107] neg_lo:[0,1] neg_hi:[0,1]
	v_pk_add_f32 v[128:129], v[88:89], v[108:109] neg_lo:[0,1] neg_hi:[0,1]
	v_pk_add_f32 v[124:125], v[98:99], v[114:115] neg_lo:[0,1] neg_hi:[0,1]
	v_pk_add_f32 v[132:133], v[100:101], v[116:117] neg_lo:[0,1] neg_hi:[0,1]
	v_pk_add_f32 v[86:87], v[118:119], v[122:123]
	v_pk_add_f32 v[88:89], v[126:127], v[130:131]
	v_pk_add_f32 v[106:107], v[118:119], v[122:123] neg_lo:[0,1] neg_hi:[0,1]
	v_pk_add_f32 v[108:109], v[126:127], v[130:131] neg_lo:[0,1] neg_hi:[0,1]
	v_pk_add_f32 v[98:99], v[120:121], v[124:125] op_sel:[0,1] op_sel_hi:[1,0] neg_lo:[0,1]
	v_pk_add_f32 v[100:101], v[128:129], v[132:133] op_sel:[0,1] op_sel_hi:[1,0] neg_lo:[0,1]
	v_pk_add_f32 v[114:115], v[120:121], v[124:125] op_sel:[0,1] op_sel_hi:[1,0] neg_hi:[0,1]
	v_pk_add_f32 v[116:117], v[128:129], v[132:133] op_sel:[0,1] op_sel_hi:[1,0] neg_hi:[0,1]
	s_nop 0
	ds_write2_b64 v85, v[90:91], v[92:93] offset1:16
	ds_write2_b64 v85, v[86:87], v[88:89] offset0:32 offset1:48
	ds_write2_b64 v85, v[94:95], v[96:97] offset0:64 offset1:80
	ds_write2_b64 v85, v[98:99], v[100:101] offset0:96 offset1:112
	ds_write2_b64 v85, v[102:103], v[104:105] offset0:128 offset1:144
	ds_write2_b64 v85, v[106:107], v[108:109] offset0:160 offset1:176
	ds_write2_b64 v85, v[110:111], v[112:113] offset0:192 offset1:208
	ds_write2_b64 v85, v[114:115], v[116:117] offset0:224 offset1:240
	v_add_u32_e32 v15, 0x200, v84
	v_add_u32_e32 v62, 0x2000, v62
	v_mov_b32_e32 v84, v15
	s_andn2_b64 exec, exec, s[0:1]
	s_cbranch_execnz .LBB0_1650
; DI float2 twid(float r) { return float2{__builtin_amdgcn_cosf(r), -__builtin_amdgcn_sinf(r)}; }
; DI void bfly_inv(float2 s0, float2 s1, float2 s2, float2 s3, float r, float2& o0, float2& o1, float2& o2, float2& o3) {
;   float2 w1 = twid(r), w2 = cmul(w1, w1), w3 = cmul(w2, w1);
;   const int lq1 = lq2 + 2, Q1 = 1 << lq1, Q2 = 1 << lq2; const float invM1 = 1.f / (float)(4 << lq1), invM2 = 1.f / (float)(4 << lq2);
;   for (int gg = tid; gg < NBT * (N / 16); gg += NTHR) { const int g = gg & (N / 16 - 1); float2* z = z0 + (gg / (N / 16)) * N; const int jp = g & (Q2 - 1), base = ((g >> lq2) << (lq2 + 4)) + jp; float2 x[4][4];
; #pragma unroll
;     for (int q1 = 0; q1 < 4; ++q1)
; #pragma unroll
;       for (int q2 = 0; q2 < 4; ++q2) x[q1][q2] = z[base + q1 * Q1 + q2 * Q2];
; #pragma unroll
;     for (int q1 = 0; q1 < 4; ++q1) bfly_inv(x[q1][0], x[q1][1], x[q1][2], x[q1][3], (float)jp * invM2, x[q1][0], x[q1][1], x[q1][2], x[q1][3]);
; #pragma unroll
;     for (int q2 = 0; q2 < 4; ++q2) bfly_inv(x[0][q2], x[1][q2], x[2][q2], x[3][q2], (float)(jp + q2 * Q2) * invM1, x[0][q2], x[1][q2], x[2][q2], x[3][q2]);
.LBB0_1651:
	s_or_b64 exec, exec, s[14:15]
	s_waitcnt lgkmcnt(0)
	s_barrier
	s_and_saveexec_b64 s[12:13], vcc
	s_cbranch_execz .LBB0_1654
	v_sin_f32_e32 v5, v82
	v_cos_f32_e32 v6, v82
	v_sin_f32_e32 v14, v81
	v_cos_f32_e32 v16, v81
	v_xor_b32_e32 v10, 0x80000000, v5
	v_mov_b32_e32 v4, v6
	v_mov_b32_e32 v8, v10
	v_mov_b32_e32 v9, v5
	v_mov_b32_e32 v7, v6
	v_mov_b32_e32 v11, v6
	v_pk_mul_f32 v[12:13], v[4:5], v[8:9]
	v_mov_b32_e32 v58, v6
	v_pk_fma_f32 v[8:9], v[6:7], v[10:11], v[12:13] op_sel_hi:[0,1,1] neg_lo:[0,0,1] neg_hi:[0,0,1]
	v_pk_fma_f32 v[10:11], v[6:7], v[10:11], v[12:13] op_sel_hi:[0,1,1]
	v_pk_mov_b32 v[12:13], v[8:9], v[10:11] op_sel:[1,0]
	v_mov_b32_e32 v18, v10
	v_mov_b32_e32 v19, v9
	v_pk_mul_f32 v[20:21], v[4:5], v[12:13] op_sel:[1,0]
	v_mul_f32_e64 v11, v16, -v14
	v_pk_fma_f32 v[12:13], v[6:7], v[18:19], v[20:21] op_sel_hi:[0,1,1]
	v_pk_fma_f32 v[18:19], v[6:7], v[18:19], v[20:21] op_sel_hi:[0,1,1] neg_lo:[0,0,1] neg_hi:[0,0,1]
	v_add_f32_e32 v20, v11, v11
	v_cvt_f32_u32_e32 v11, v80
	v_mul_f32_e32 v8, v14, v14
	v_fma_f32 v24, v16, v16, -v8
	v_mul_f32_e32 v23, v14, v20
	v_mul_f32_e32 v8, 0x39800000, v11
	v_sin_f32_e32 v27, v8
	v_cos_f32_e32 v29, v8
	v_cvt_f32_u32_e32 v11, v79
	v_mul_f32_e32 v8, v14, v24
	v_fma_f32 v22, v16, v20, -v8
	v_mul_f32_e32 v8, v27, v27
	v_fma_f32 v30, v29, v29, -v8
	v_mul_f32_e64 v8, v29, -v27
	v_add_f32_e32 v32, v8, v8
	v_mul_f32_e32 v8, 0x39800000, v11
	v_sin_f32_e32 v35, v8
	v_cos_f32_e32 v37, v8
	v_cvt_f32_u32_e32 v11, v78
	v_mul_f32_e32 v8, v27, v30
	v_fma_f32 v28, v29, v32, -v8
	v_mul_f32_e32 v8, v35, v35
	v_fma_f32 v38, v37, v37, -v8
	v_mul_f32_e64 v8, v37, -v35
	v_add_f32_e32 v40, v8, v8
	v_mul_f32_e32 v8, 0x39800000, v11
	v_sin_f32_e32 v42, v8
	v_cos_f32_e32 v44, v8
	v_mul_f32_e32 v26, v27, v32
	v_mul_f32_e32 v34, v35, v40
	v_xor_b32_e32 v45, 0x80000000, v42
	v_mov_b32_e32 v43, v44
	v_mov_b32_e32 v46, v42
	v_mov_b32_e32 v47, v45
	v_pk_mul_f32 v[48:49], v[42:43], v[46:47]
	v_mul_f32_e32 v8, v35, v38
	v_pk_fma_f32 v[46:47], v[44:45], v[44:45], v[48:49] op_sel_hi:[0,1,1] neg_lo:[0,0,1] neg_hi:[0,0,1]
	v_pk_fma_f32 v[62:63], v[44:45], v[44:45], v[48:49] op_sel_hi:[0,1,1]
	v_pk_mov_b32 v[50:51], v[62:63], v[46:47] op_sel:[1,0]
	v_mov_b32_e32 v48, v46
	v_mov_b32_e32 v49, v63
	v_pk_mul_f32 v[50:51], v[42:43], v[50:51] op_sel_hi:[0,1]
	v_fmac_f32_e32 v23, v16, v24
	v_fmac_f32_e32 v26, v29, v30
	v_fmac_f32_e32 v34, v37, v38
	v_fma_f32 v36, v37, v40, -v8
	v_pk_fma_f32 v[60:61], v[44:45], v[48:49], v[50:51] op_sel_hi:[0,1,1]
	v_pk_fma_f32 v[48:49], v[44:45], v[48:49], v[50:51] op_sel_hi:[0,1,1] neg_lo:[0,0,1] neg_hi:[0,0,1]
	v_mov_b32_e32 v21, v14
	v_mov_b32_e32 v19, v13
	v_mov_b32_e32 v48, v60
	v_mov_b32_e32 v11, v10
	v_mov_b32_e32 v31, v30
	v_mov_b32_e32 v33, v32
	v_pk_mov_b32 v[50:51], v[28:29], v[26:27] op_sel:[1,0]
	v_pk_mov_b32 v[52:53], v[26:27], v[28:29] op_sel:[1,0]
	v_mov_b32_e32 v39, v38
	v_pk_mov_b32 v[54:55], v[36:37], v[34:35] op_sel:[1,0]
	v_pk_mov_b32 v[56:57], v[34:35], v[36:37] op_sel:[1,0]
	v_mov_b32_e32 v59, v18
	v_mov_b32_e32 v12, v5
	v_pk_mov_b32 v[60:61], v[62:63], v[60:61] op_sel:[1,0]
	v_mov_b32_e32 v47, v49
	v_mov_b32_e32 v45, v46
	v_mov_b32_e32 v43, v63
	v_mov_b32_e32 v63, v18
	v_mov_b32_e32 v64, v5
	v_mov_b32_e32 v65, v5
	v_mov_b32_e32 v8, v9
	v_mov_b32_e32 v66, v6
	v_mov_b32_e32 v67, v13
	v_mov_b32_e32 v68, v5
	v_mov_b32_e32 v69, v18
	v_mov_b32_e32 v70, v13
	v_mov_b32_e32 v71, v13
	v_mov_b32_e32 v72, v18
	v_mov_b32_e32 v73, v18
	v_mov_b32_e32 v25, v16
	v_pk_mov_b32 v[74:75], v[22:23], v[20:21] op_sel:[1,0]
	v_mov_b32_e32 v41, v40
	s_mov_b64 s[0:1], 0
	v_mov_b32_e32 v62, v76
	v_and_b32_e32 v241, 0xff, v62
	v_add_u32_e32 v250, 0x0, v241
	v_cvt_f32_u32_e32 v250, v250
	v_mul_f32_e32 v250, 0x39800000, v250
	v_cos_f32_e32 v218, v250
	v_sin_f32_e32 v219, v250
	s_nop 1
	v_xor_b32_e32 v219, 0x80000000, v219
	s_nop 0
	v_pk_mul_f32 v[128:129], v[218:219], v[218:219] op_sel:[1,1] op_sel_hi:[1,0]
	s_nop 0
	v_pk_fma_f32 v[220:221], v[218:219], v[218:219], v[128:129] op_sel_hi:[0,1,1] neg_lo:[0,0,1]
	s_nop 0
	v_pk_mul_f32 v[128:129], v[220:221], v[218:219] op_sel:[1,1] op_sel_hi:[1,0]
	s_nop 0
	v_pk_fma_f32 v[222:223], v[220:221], v[218:219], v[128:129] op_sel_hi:[0,1,1] neg_lo:[0,0,1]
	s_nop 0
	v_xor_b32_e32 v219, 0x80000000, v219
	v_xor_b32_e32 v221, 0x80000000, v221
	v_xor_b32_e32 v223, 0x80000000, v223
	v_add_u32_e32 v250, 0x100, v241
	v_cvt_f32_u32_e32 v250, v250
	v_mul_f32_e32 v250, 0x39800000, v250
	v_cos_f32_e32 v224, v250
	v_sin_f32_e32 v225, v250
	s_nop 1
	v_xor_b32_e32 v225, 0x80000000, v225
	s_nop 0
	v_pk_mul_f32 v[128:129], v[224:225], v[224:225] op_sel:[1,1] op_sel_hi:[1,0]
	s_nop 0
	v_pk_fma_f32 v[226:227], v[224:225], v[224:225], v[128:129] op_sel_hi:[0,1,1] neg_lo:[0,0,1]
	s_nop 0
	v_pk_mul_f32 v[128:129], v[226:227], v[224:225] op_sel:[1,1] op_sel_hi:[1,0]
	s_nop 0
	v_pk_fma_f32 v[228:229], v[226:227], v[224:225], v[128:129] op_sel_hi:[0,1,1] neg_lo:[0,0,1]
	s_nop 0
	v_xor_b32_e32 v225, 0x80000000, v225
	v_xor_b32_e32 v227, 0x80000000, v227
	v_xor_b32_e32 v229, 0x80000000, v229
	v_add_u32_e32 v250, 0x200, v241
	v_cvt_f32_u32_e32 v250, v250
	v_mul_f32_e32 v250, 0x39800000, v250
	v_cos_f32_e32 v230, v250
	v_sin_f32_e32 v231, v250
	s_nop 1
	v_xor_b32_e32 v231, 0x80000000, v231
	s_nop 0
	v_pk_mul_f32 v[128:129], v[230:231], v[230:231] op_sel:[1,1] op_sel_hi:[1,0]
	s_nop 0
	v_pk_fma_f32 v[232:233], v[230:231], v[230:231], v[128:129] op_sel_hi:[0,1,1] neg_lo:[0,0,1]
	s_nop 0
	v_pk_mul_f32 v[128:129], v[232:233], v[230:231] op_sel:[1,1] op_sel_hi:[1,0]
	s_nop 0
	v_pk_fma_f32 v[234:235], v[232:233], v[230:231], v[128:129] op_sel_hi:[0,1,1] neg_lo:[0,0,1]
	s_nop 0
; DI float2 twid(float r) { return float2{__builtin_amdgcn_cosf(r), -__builtin_amdgcn_sinf(r)}; }
; DI void bfly_inv(float2 s0, float2 s1, float2 s2, float2 s3, float r, float2& o0, float2& o1, float2& o2, float2& o3) {
;   float2 w1 = twid(r), w2 = cmul(w1, w1), w3 = cmul(w2, w1);
;   float2 c0 = s0, c1 = cmulc(s1, w1), c2 = cmulc(s2, w2), c3 = cmulc(s3, w3);
;   float2 t0 = {c0.x + c2.x, c0.y + c2.y}, t1 = {c0.x - c2.x, c0.y - c2.y}, t2 = {c1.x + c3.x, c1.y + c3.y}, t3 = {c1.x - c3.x, c1.y - c3.y};
;   o0 = float2{t0.x + t2.x, t0.y + t2.y}; o2 = float2{t0.x - t2.x, t0.y - t2.y}; o1 = float2{t1.x - t3.y, t1.y + t3.x}; o3 = float2{t1.x + t3.y, t1.y - t3.x};
; }
;     ...
;   for (int gg = tid; gg < NBT * (N / 16); gg += NTHR) { const int g = gg & (N / 16 - 1); float2* z = z0 + (gg / (N / 16)) * N; const int jp = g & (Q2 - 1), base = ((g >> lq2) << (lq2 + 4)) + jp; float2 x[4][4];
; #pragma unroll
;     for (int q1 = 0; q1 < 4; ++q1)
; #pragma unroll
;       for (int q2 = 0; q2 < 4; ++q2) x[q1][q2] = z[base + q1 * Q1 + q2 * Q2];
; #pragma unroll
;     for (int q1 = 0; q1 < 4; ++q1) bfly_inv(x[q1][0], x[q1][1], x[q1][2], x[q1][3], (float)jp * invM2, x[q1][0], x[q1][1], x[q1][2], x[q1][3]);
; #pragma unroll
;     for (int q2 = 0; q2 < 4; ++q2) bfly_inv(x[0][q2], x[1][q2], x[2][q2], x[3][q2], (float)(jp + q2 * Q2) * invM1, x[0][q2], x[1][q2], x[2][q2], x[3][q2]);
; #pragma unroll
;     for (int q1 = 0; q1 < 4; ++q1)
; #pragma unroll
;       for (int q2 = 0; q2 < 4; ++q2) z[base + q1 * Q1 + q2 * Q2] = x[q1][q2]; }
	v_xor_b32_e32 v231, 0x80000000, v231
	v_xor_b32_e32 v233, 0x80000000, v233
	v_xor_b32_e32 v235, 0x80000000, v235
	v_add_u32_e32 v250, 0x300, v241
	v_cvt_f32_u32_e32 v250, v250
	v_mul_f32_e32 v250, 0x39800000, v250
	v_cos_f32_e32 v236, v250
	v_sin_f32_e32 v237, v250
	s_nop 1
	v_xor_b32_e32 v237, 0x80000000, v237
	s_nop 0
	v_pk_mul_f32 v[128:129], v[236:237], v[236:237] op_sel:[1,1] op_sel_hi:[1,0]
	s_nop 0
	v_pk_fma_f32 v[238:239], v[236:237], v[236:237], v[128:129] op_sel_hi:[0,1,1] neg_lo:[0,0,1]
	s_nop 0
	v_pk_mul_f32 v[128:129], v[238:239], v[236:237] op_sel:[1,1] op_sel_hi:[1,0]
	s_nop 0
	v_pk_fma_f32 v[242:243], v[238:239], v[236:237], v[128:129] op_sel_hi:[0,1,1] neg_lo:[0,0,1]
	s_nop 0
	v_xor_b32_e32 v237, 0x80000000, v237
	v_xor_b32_e32 v239, 0x80000000, v239
	v_xor_b32_e32 v243, 0x80000000, v243
	v_cvt_f32_u32_e32 v250, v241
	v_mul_f32_e32 v250, 0x3a800000, v250
	v_cos_f32_e32 v244, v250
	v_sin_f32_e32 v245, v250
	s_nop 1
	v_xor_b32_e32 v245, 0x80000000, v245
	s_nop 0
	v_pk_mul_f32 v[128:129], v[244:245], v[244:245] op_sel:[1,1] op_sel_hi:[1,0]
	s_nop 0
	v_pk_fma_f32 v[246:247], v[244:245], v[244:245], v[128:129] op_sel_hi:[0,1,1] neg_lo:[0,0,1]
	s_nop 0
	v_pk_mul_f32 v[128:129], v[246:247], v[244:245] op_sel:[1,1] op_sel_hi:[1,0]
	s_nop 0
	v_pk_fma_f32 v[248:249], v[246:247], v[244:245], v[128:129] op_sel_hi:[0,1,1] neg_lo:[0,0,1]
	s_nop 0
	v_xor_b32_e32 v245, 0x80000000, v245
	v_xor_b32_e32 v247, 0x80000000, v247
	v_xor_b32_e32 v249, 0x80000000, v249
.LBB0_1653:
	v_ashrrev_i32_e32 v15, 31, v62
	v_lshrrev_b32_e32 v15, 22, v15
	v_add_lshl_u32 v15, v62, v15, 7
	v_and_b32_e32 v15, 0xfffe0000, v15
	v_and_b32_e32 v17, 0x3000, v77
	v_add_u32_e32 v15, 16, v15
	v_lshlrev_b32_e32 v17, 3, v17
	v_lshlrev_b32_sdwa v78, v151, v76 dst_sel:DWORD dst_unused:UNUSED_PAD src0_sel:DWORD src1_sel:BYTE_0
	v_add3_u32 v178, v15, v17, v78
	ds_read2st64_b64 v[80:83], v178 offset0:8 offset1:12
	ds_read2st64_b64 v[84:87], v178 offset1:4
	ds_read2st64_b64 v[88:91], v178 offset0:16 offset1:20
	ds_read2st64_b64 v[92:95], v178 offset0:24 offset1:28
	ds_read2st64_b64 v[96:99], v178 offset0:32 offset1:36
	ds_read2st64_b64 v[100:103], v178 offset0:40 offset1:44
	ds_read2st64_b64 v[104:107], v178 offset0:48 offset1:52
	ds_read2st64_b64 v[108:111], v178 offset0:56 offset1:60
	v_cmp_lt_i32_e32 vcc, s5, v62
	s_or_b64 s[0:1], vcc, s[0:1]
	s_waitcnt lgkmcnt(0)
	v_pk_mul_f32 v[128:129], v[86:87], v[244:245] op_sel:[1,1] op_sel_hi:[1,0]
	v_pk_mul_f32 v[132:133], v[90:91], v[244:245] op_sel:[1,1] op_sel_hi:[1,0]
	v_pk_mul_f32 v[130:131], v[80:81], v[246:247] op_sel:[1,1] op_sel_hi:[1,0]
	v_pk_mul_f32 v[134:135], v[92:93], v[246:247] op_sel:[1,1] op_sel_hi:[1,0]
	v_pk_fma_f32 v[86:87], v[86:87], v[244:245], v[128:129] op_sel_hi:[0,1,1] neg_lo:[0,0,1]
	v_pk_fma_f32 v[90:91], v[90:91], v[244:245], v[132:133] op_sel_hi:[0,1,1] neg_lo:[0,0,1]
	v_pk_mul_f32 v[128:129], v[82:83], v[248:249] op_sel:[1,1] op_sel_hi:[1,0]
	v_pk_mul_f32 v[132:133], v[94:95], v[248:249] op_sel:[1,1] op_sel_hi:[1,0]
	v_pk_fma_f32 v[80:81], v[80:81], v[246:247], v[130:131] op_sel_hi:[0,1,1] neg_lo:[0,0,1]
	v_pk_fma_f32 v[92:93], v[92:93], v[246:247], v[134:135] op_sel_hi:[0,1,1] neg_lo:[0,0,1]
	v_pk_fma_f32 v[82:83], v[82:83], v[248:249], v[128:129] op_sel_hi:[0,1,1] neg_lo:[0,0,1]
	v_pk_fma_f32 v[94:95], v[94:95], v[248:249], v[132:133] op_sel_hi:[0,1,1] neg_lo:[0,0,1]
	v_pk_add_f32 v[112:113], v[84:85], v[80:81]
	v_pk_add_f32 v[120:121], v[88:89], v[92:93]
	v_pk_add_f32 v[116:117], v[86:87], v[82:83]
	v_pk_add_f32 v[124:125], v[90:91], v[94:95]
	v_pk_add_f32 v[114:115], v[84:85], v[80:81] neg_lo:[0,1] neg_hi:[0,1]
	v_pk_add_f32 v[122:123], v[88:89], v[92:93] neg_lo:[0,1] neg_hi:[0,1]
	v_pk_add_f32 v[118:119], v[86:87], v[82:83] neg_lo:[0,1] neg_hi:[0,1]
	v_pk_add_f32 v[126:127], v[90:91], v[94:95] neg_lo:[0,1] neg_hi:[0,1]
	v_pk_add_f32 v[84:85], v[112:113], v[116:117]
	v_pk_add_f32 v[88:89], v[120:121], v[124:125]
	v_pk_add_f32 v[80:81], v[112:113], v[116:117] neg_lo:[0,1] neg_hi:[0,1]
	v_pk_add_f32 v[92:93], v[120:121], v[124:125] neg_lo:[0,1] neg_hi:[0,1]
	v_pk_add_f32 v[86:87], v[114:115], v[118:119] op_sel:[0,1] op_sel_hi:[1,0] neg_lo:[0,1]
	v_pk_add_f32 v[90:91], v[122:123], v[126:127] op_sel:[0,1] op_sel_hi:[1,0] neg_lo:[0,1]
	v_pk_add_f32 v[82:83], v[114:115], v[118:119] op_sel:[0,1] op_sel_hi:[1,0] neg_hi:[0,1]
	v_pk_add_f32 v[94:95], v[122:123], v[126:127] op_sel:[0,1] op_sel_hi:[1,0] neg_hi:[0,1]
	v_pk_mul_f32 v[128:129], v[98:99], v[244:245] op_sel:[1,1] op_sel_hi:[1,0]
	v_pk_mul_f32 v[132:133], v[106:107], v[244:245] op_sel:[1,1] op_sel_hi:[1,0]
	v_pk_mul_f32 v[130:131], v[100:101], v[246:247] op_sel:[1,1] op_sel_hi:[1,0]
	v_pk_mul_f32 v[134:135], v[108:109], v[246:247] op_sel:[1,1] op_sel_hi:[1,0]
	v_pk_fma_f32 v[98:99], v[98:99], v[244:245], v[128:129] op_sel_hi:[0,1,1] neg_lo:[0,0,1]
	v_pk_fma_f32 v[106:107], v[106:107], v[244:245], v[132:133] op_sel_hi:[0,1,1] neg_lo:[0,0,1]
	v_pk_mul_f32 v[128:129], v[102:103], v[248:249] op_sel:[1,1] op_sel_hi:[1,0]
	v_pk_mul_f32 v[132:133], v[110:111], v[248:249] op_sel:[1,1] op_sel_hi:[1,0]
	v_pk_fma_f32 v[100:101], v[100:101], v[246:247], v[130:131] op_sel_hi:[0,1,1] neg_lo:[0,0,1]
	v_pk_fma_f32 v[108:109], v[108:109], v[246:247], v[134:135] op_sel_hi:[0,1,1] neg_lo:[0,0,1]
	v_pk_fma_f32 v[102:103], v[102:103], v[248:249], v[128:129] op_sel_hi:[0,1,1] neg_lo:[0,0,1]
	v_pk_fma_f32 v[110:111], v[110:111], v[248:249], v[132:133] op_sel_hi:[0,1,1] neg_lo:[0,0,1]
	v_pk_add_f32 v[112:113], v[96:97], v[100:101]
	v_pk_add_f32 v[120:121], v[104:105], v[108:109]
	v_pk_add_f32 v[116:117], v[98:99], v[102:103]
	v_pk_add_f32 v[124:125], v[106:107], v[110:111]
; DI float2 twid(float r) { return float2{__builtin_amdgcn_cosf(r), -__builtin_amdgcn_sinf(r)}; }
; DI void bfly_inv(float2 s0, float2 s1, float2 s2, float2 s3, float r, float2& o0, float2& o1, float2& o2, float2& o3) {
;   float2 w1 = twid(r), w2 = cmul(w1, w1), w3 = cmul(w2, w1);
;   float2 c0 = s0, c1 = cmulc(s1, w1), c2 = cmulc(s2, w2), c3 = cmulc(s3, w3);
;   float2 t0 = {c0.x + c2.x, c0.y + c2.y}, t1 = {c0.x - c2.x, c0.y - c2.y}, t2 = {c1.x + c3.x, c1.y + c3.y}, t3 = {c1.x - c3.x, c1.y - c3.y};
;   o0 = float2{t0.x + t2.x, t0.y + t2.y}; o2 = float2{t0.x - t2.x, t0.y - t2.y}; o1 = float2{t1.x - t3.y, t1.y + t3.x}; o3 = float2{t1.x + t3.y, t1.y - t3.x};
; }
;     ...
;   for (int gg = tid; gg < NBT * (N / 16); gg += NTHR) { const int g = gg & (N / 16 - 1); float2* z = z0 + (gg / (N / 16)) * N; const int jp = g & (Q2 - 1), base = ((g >> lq2) << (lq2 + 4)) + jp; float2 x[4][4];
; #pragma unroll
;     for (int q1 = 0; q1 < 4; ++q1)
; #pragma unroll
;       for (int q2 = 0; q2 < 4; ++q2) x[q1][q2] = z[base + q1 * Q1 + q2 * Q2];
; #pragma unroll
;     for (int q1 = 0; q1 < 4; ++q1) bfly_inv(x[q1][0], x[q1][1], x[q1][2], x[q1][3], (float)jp * invM2, x[q1][0], x[q1][1], x[q1][2], x[q1][3]);
; #pragma unroll
;     for (int q2 = 0; q2 < 4; ++q2) bfly_inv(x[0][q2], x[1][q2], x[2][q2], x[3][q2], (float)(jp + q2 * Q2) * invM1, x[0][q2], x[1][q2], x[2][q2], x[3][q2]);
; #pragma unroll
;     for (int q1 = 0; q1 < 4; ++q1)
; #pragma unroll
;       for (int q2 = 0; q2 < 4; ++q2) z[base + q1 * Q1 + q2 * Q2] = x[q1][q2]; }
	v_pk_add_f32 v[114:115], v[96:97], v[100:101] neg_lo:[0,1] neg_hi:[0,1]
	v_pk_add_f32 v[122:123], v[104:105], v[108:109] neg_lo:[0,1] neg_hi:[0,1]
	v_pk_add_f32 v[118:119], v[98:99], v[102:103] neg_lo:[0,1] neg_hi:[0,1]
	v_pk_add_f32 v[126:127], v[106:107], v[110:111] neg_lo:[0,1] neg_hi:[0,1]
	v_pk_add_f32 v[96:97], v[112:113], v[116:117]
	v_pk_add_f32 v[104:105], v[120:121], v[124:125]
	v_pk_add_f32 v[100:101], v[112:113], v[116:117] neg_lo:[0,1] neg_hi:[0,1]
	v_pk_add_f32 v[108:109], v[120:121], v[124:125] neg_lo:[0,1] neg_hi:[0,1]
	v_pk_add_f32 v[98:99], v[114:115], v[118:119] op_sel:[0,1] op_sel_hi:[1,0] neg_lo:[0,1]
	v_pk_add_f32 v[106:107], v[122:123], v[126:127] op_sel:[0,1] op_sel_hi:[1,0] neg_lo:[0,1]
	v_pk_add_f32 v[102:103], v[114:115], v[118:119] op_sel:[0,1] op_sel_hi:[1,0] neg_hi:[0,1]
	v_pk_add_f32 v[110:111], v[122:123], v[126:127] op_sel:[0,1] op_sel_hi:[1,0] neg_hi:[0,1]
	v_pk_mul_f32 v[128:129], v[88:89], v[218:219] op_sel:[1,1] op_sel_hi:[1,0]
	v_pk_mul_f32 v[132:133], v[90:91], v[224:225] op_sel:[1,1] op_sel_hi:[1,0]
	v_pk_mul_f32 v[130:131], v[96:97], v[220:221] op_sel:[1,1] op_sel_hi:[1,0]
	v_pk_mul_f32 v[134:135], v[98:99], v[226:227] op_sel:[1,1] op_sel_hi:[1,0]
	v_pk_fma_f32 v[88:89], v[88:89], v[218:219], v[128:129] op_sel_hi:[0,1,1] neg_lo:[0,0,1]
	v_pk_fma_f32 v[90:91], v[90:91], v[224:225], v[132:133] op_sel_hi:[0,1,1] neg_lo:[0,0,1]
	v_pk_mul_f32 v[128:129], v[104:105], v[222:223] op_sel:[1,1] op_sel_hi:[1,0]
	v_pk_mul_f32 v[132:133], v[106:107], v[228:229] op_sel:[1,1] op_sel_hi:[1,0]
	v_pk_fma_f32 v[96:97], v[96:97], v[220:221], v[130:131] op_sel_hi:[0,1,1] neg_lo:[0,0,1]
	v_pk_fma_f32 v[98:99], v[98:99], v[226:227], v[134:135] op_sel_hi:[0,1,1] neg_lo:[0,0,1]
	v_pk_fma_f32 v[104:105], v[104:105], v[222:223], v[128:129] op_sel_hi:[0,1,1] neg_lo:[0,0,1]
	v_pk_fma_f32 v[106:107], v[106:107], v[228:229], v[132:133] op_sel_hi:[0,1,1] neg_lo:[0,0,1]
	v_pk_add_f32 v[112:113], v[84:85], v[96:97]
	v_pk_add_f32 v[120:121], v[86:87], v[98:99]
	v_pk_add_f32 v[116:117], v[88:89], v[104:105]
	v_pk_add_f32 v[124:125], v[90:91], v[106:107]
	v_pk_add_f32 v[114:115], v[84:85], v[96:97] neg_lo:[0,1] neg_hi:[0,1]
	v_pk_add_f32 v[122:123], v[86:87], v[98:99] neg_lo:[0,1] neg_hi:[0,1]
	v_pk_add_f32 v[118:119], v[88:89], v[104:105] neg_lo:[0,1] neg_hi:[0,1]
	v_pk_add_f32 v[126:127], v[90:91], v[106:107] neg_lo:[0,1] neg_hi:[0,1]
	v_pk_add_f32 v[84:85], v[112:113], v[116:117]
	v_pk_add_f32 v[86:87], v[120:121], v[124:125]
	v_pk_add_f32 v[96:97], v[112:113], v[116:117] neg_lo:[0,1] neg_hi:[0,1]
	v_pk_add_f32 v[98:99], v[120:121], v[124:125] neg_lo:[0,1] neg_hi:[0,1]
	v_pk_add_f32 v[88:89], v[114:115], v[118:119] op_sel:[0,1] op_sel_hi:[1,0] neg_lo:[0,1]
	v_pk_add_f32 v[90:91], v[122:123], v[126:127] op_sel:[0,1] op_sel_hi:[1,0] neg_lo:[0,1]
	v_pk_add_f32 v[104:105], v[114:115], v[118:119] op_sel:[0,1] op_sel_hi:[1,0] neg_hi:[0,1]
	v_pk_add_f32 v[106:107], v[122:123], v[126:127] op_sel:[0,1] op_sel_hi:[1,0] neg_hi:[0,1]
	v_pk_mul_f32 v[128:129], v[92:93], v[230:231] op_sel:[1,1] op_sel_hi:[1,0]
	v_pk_mul_f32 v[132:133], v[94:95], v[236:237] op_sel:[1,1] op_sel_hi:[1,0]
	v_pk_mul_f32 v[130:131], v[100:101], v[232:233] op_sel:[1,1] op_sel_hi:[1,0]
	v_pk_mul_f32 v[134:135], v[102:103], v[238:239] op_sel:[1,1] op_sel_hi:[1,0]
	v_pk_fma_f32 v[92:93], v[92:93], v[230:231], v[128:129] op_sel_hi:[0,1,1] neg_lo:[0,0,1]
	v_pk_fma_f32 v[94:95], v[94:95], v[236:237], v[132:133] op_sel_hi:[0,1,1] neg_lo:[0,0,1]
	v_pk_mul_f32 v[128:129], v[108:109], v[234:235] op_sel:[1,1] op_sel_hi:[1,0]
	v_pk_mul_f32 v[132:133], v[110:111], v[242:243] op_sel:[1,1] op_sel_hi:[1,0]
	v_pk_fma_f32 v[100:101], v[100:101], v[232:233], v[130:131] op_sel_hi:[0,1,1] neg_lo:[0,0,1]
	v_pk_fma_f32 v[102:103], v[102:103], v[238:239], v[134:135] op_sel_hi:[0,1,1] neg_lo:[0,0,1]
	v_pk_fma_f32 v[108:109], v[108:109], v[234:235], v[128:129] op_sel_hi:[0,1,1] neg_lo:[0,0,1]
	v_pk_fma_f32 v[110:111], v[110:111], v[242:243], v[132:133] op_sel_hi:[0,1,1] neg_lo:[0,0,1]
	v_pk_add_f32 v[112:113], v[80:81], v[100:101]
	v_pk_add_f32 v[120:121], v[82:83], v[102:103]
	v_pk_add_f32 v[116:117], v[92:93], v[108:109]
	v_pk_add_f32 v[124:125], v[94:95], v[110:111]
	v_pk_add_f32 v[114:115], v[80:81], v[100:101] neg_lo:[0,1] neg_hi:[0,1]
	v_pk_add_f32 v[122:123], v[82:83], v[102:103] neg_lo:[0,1] neg_hi:[0,1]
	v_pk_add_f32 v[118:119], v[92:93], v[108:109] neg_lo:[0,1] neg_hi:[0,1]
	v_pk_add_f32 v[126:127], v[94:95], v[110:111] neg_lo:[0,1] neg_hi:[0,1]
	v_pk_add_f32 v[80:81], v[112:113], v[116:117]
	v_pk_add_f32 v[82:83], v[120:121], v[124:125]
	v_pk_add_f32 v[100:101], v[112:113], v[116:117] neg_lo:[0,1] neg_hi:[0,1]
	v_pk_add_f32 v[102:103], v[120:121], v[124:125] neg_lo:[0,1] neg_hi:[0,1]
	v_pk_add_f32 v[92:93], v[114:115], v[118:119] op_sel:[0,1] op_sel_hi:[1,0] neg_lo:[0,1]
	v_pk_add_f32 v[94:95], v[122:123], v[126:127] op_sel:[0,1] op_sel_hi:[1,0] neg_lo:[0,1]
	v_pk_add_f32 v[108:109], v[114:115], v[118:119] op_sel:[0,1] op_sel_hi:[1,0] neg_hi:[0,1]
	v_pk_add_f32 v[110:111], v[122:123], v[126:127] op_sel:[0,1] op_sel_hi:[1,0] neg_hi:[0,1]
	s_nop 0
	ds_write2st64_b64 v178, v[84:85], v[86:87] offset1:4
	ds_write2st64_b64 v178, v[80:81], v[82:83] offset0:8 offset1:12
	ds_write2st64_b64 v178, v[88:89], v[90:91] offset0:16 offset1:20
	ds_write2st64_b64 v178, v[92:93], v[94:95] offset0:24 offset1:28
	ds_write2st64_b64 v178, v[96:97], v[98:99] offset0:32 offset1:36
	ds_write2st64_b64 v178, v[100:101], v[102:103] offset0:40 offset1:44
	ds_write2st64_b64 v178, v[104:105], v[106:107] offset0:48 offset1:52
	ds_write2st64_b64 v178, v[108:109], v[110:111] offset0:56 offset1:60
	v_add_u32_e32 v77, 0x2000, v77
	v_add_u32_e32 v15, 0x200, v62
	v_mov_b32_e32 v62, v15
	s_andn2_b64 exec, exec, s[0:1]
	s_cbranch_execnz .LBB0_1653
